# A/B: every s_setprio flip of the GEMM K loops deleted
# speedup vs baseline: 1.0075x; 1.0075x over previous
.LBB0_179:
	s_add_u32 s29, s56, 0xfffc0080
	s_addc_u32 s30, s57, -1
	s_add_i32 s31, 0, 0x10000
	s_cmp_eq_u32 s28, 12
	s_cselect_b32 s61, s6, s30
	s_cselect_b32 s60, s7, s29
	s_cselect_b32 s59, s24, s27
	s_cselect_b32 s58, s25, s26
	s_add_i32 s29, 0, 0x14000
	v_add_u32_e32 v156, s31, v145
	v_add_u32_e32 v162, s29, v145
	ds_read_b128 v[140:143], v156
	ds_read_b128 v[148:151], v156 offset:1024
	ds_read_b128 v[152:155], v156 offset:2048
	ds_read_b128 v[156:159], v156 offset:3072
	ds_read_b128 v[178:181], v162
	ds_read_b128 v[182:185], v162 offset:1024
	ds_read_b128 v[186:189], v162 offset:2048
	ds_read_b128 v[190:193], v162 offset:3072
	v_lshl_add_u64 v[174:175], s[56:57], 0, v[136:137]
	s_add_i32 m0, s65, 0xc000
	ds_read_b128 v[194:197], v147
	ds_read_b128 v[198:201], v147 offset:1024
	ds_read_b128 v[202:205], v147 offset:2048
	ds_read_b128 v[220:223], v147 offset:3072
	ds_read_b128 v[228:231], v147 offset:4096
	ds_read_b128 v[232:235], v147 offset:5120
	ds_read_b128 v[236:239], v147 offset:6144
	ds_read_b128 v[240:243], v147 offset:7168
	global_load_lds_dwordx4 v[174:175], off
	v_lshl_add_u64 v[174:175], s[56:57], 0, v[138:139]
	s_add_i32 m0, s65, 0xe000
	s_nop 0
	global_load_lds_dwordx4 v[174:175], off
	s_waitcnt vmcnt(8)
	s_waitcnt lgkmcnt(0)
	s_barrier
	s_waitcnt lgkmcnt(0)
	v_mfma_f32_16x16x32_bf16 v[124:127], v[140:143], v[194:197], v[124:127]
	v_mfma_f32_16x16x32_bf16 v[120:123], v[152:155], v[194:197], v[120:123]
	v_mfma_f32_16x16x32_bf16 v[108:111], v[140:143], v[202:205], v[108:111]
	v_mfma_f32_16x16x32_bf16 v[104:107], v[152:155], v[202:205], v[104:107]
	v_mfma_f32_16x16x32_bf16 v[92:95], v[140:143], v[228:231], v[92:95]
	v_mfma_f32_16x16x32_bf16 v[88:91], v[152:155], v[228:231], v[88:91]
	v_mfma_f32_16x16x32_bf16 v[76:79], v[140:143], v[236:239], v[76:79]
	v_mfma_f32_16x16x32_bf16 v[72:75], v[152:155], v[236:239], v[72:75]
	v_mfma_f32_16x16x32_bf16 v[124:127], v[148:151], v[198:201], v[124:127]
	v_mfma_f32_16x16x32_bf16 v[120:123], v[156:159], v[198:201], v[120:123]
	v_mfma_f32_16x16x32_bf16 v[108:111], v[148:151], v[220:223], v[108:111]
	v_mfma_f32_16x16x32_bf16 v[104:107], v[156:159], v[220:223], v[104:107]
	v_mfma_f32_16x16x32_bf16 v[92:95], v[148:151], v[232:235], v[92:95]
	v_mfma_f32_16x16x32_bf16 v[88:91], v[156:159], v[232:235], v[88:91]
	v_mfma_f32_16x16x32_bf16 v[76:79], v[148:151], v[240:243], v[76:79]
	v_mfma_f32_16x16x32_bf16 v[72:75], v[156:159], v[240:243], v[72:75]
	v_mfma_f32_16x16x32_bf16 v[116:119], v[178:181], v[194:197], v[116:119]
	v_mfma_f32_16x16x32_bf16 v[112:115], v[186:189], v[194:197], v[112:115]
	v_mfma_f32_16x16x32_bf16 v[100:103], v[178:181], v[202:205], v[100:103]
	v_mfma_f32_16x16x32_bf16 v[96:99], v[186:189], v[202:205], v[96:99]
	v_mfma_f32_16x16x32_bf16 v[84:87], v[178:181], v[228:231], v[84:87]
	v_mfma_f32_16x16x32_bf16 v[80:83], v[186:189], v[228:231], v[80:83]
	v_mfma_f32_16x16x32_bf16 v[68:71], v[178:181], v[236:239], v[68:71]
	v_mfma_f32_16x16x32_bf16 v[64:67], v[186:189], v[236:239], v[64:67]
	v_mfma_f32_16x16x32_bf16 v[116:119], v[182:185], v[198:201], v[116:119]
	v_mfma_f32_16x16x32_bf16 v[112:115], v[190:193], v[198:201], v[112:115]
	v_mfma_f32_16x16x32_bf16 v[100:103], v[182:185], v[220:223], v[100:103]
	v_mfma_f32_16x16x32_bf16 v[96:99], v[190:193], v[220:223], v[96:99]
	v_mfma_f32_16x16x32_bf16 v[84:87], v[182:185], v[232:235], v[84:87]
	v_mfma_f32_16x16x32_bf16 v[80:83], v[190:193], v[232:235], v[80:83]
	v_mfma_f32_16x16x32_bf16 v[68:71], v[182:185], v[240:243], v[68:71]
	v_mfma_f32_16x16x32_bf16 v[64:67], v[190:193], v[240:243], v[64:67]
	s_barrier
	s_add_i32 s30, s31, s64
	v_lshl_add_u64 v[174:175], s[58:59], 0, v[132:133]
	s_mov_b32 m0, s30
	ds_read_b128 v[194:197], v147 offset:16384
	ds_read_b128 v[198:201], v147 offset:17408
	ds_read_b128 v[202:205], v147 offset:18432
	ds_read_b128 v[220:223], v147 offset:19456
	ds_read_b128 v[228:231], v147 offset:20480
	ds_read_b128 v[232:235], v147 offset:21504
	ds_read_b128 v[236:239], v147 offset:22528
	ds_read_b128 v[240:243], v147 offset:23552
	global_load_lds_dwordx4 v[174:175], off
	s_add_i32 m0, s30, 0x2000
	s_add_u32 s30, s58, 0x40000
	v_lshl_add_u64 v[176:177], s[58:59], 0, v[128:129]
	s_addc_u32 s31, s59, 0
	s_add_i32 s29, s29, s64
	global_load_lds_dwordx4 v[176:177], off
	v_lshl_add_u64 v[244:245], s[30:31], 0, v[132:133]
	s_mov_b32 m0, s29
	v_lshl_add_u64 v[246:247], s[60:61], 0, v[130:131]
	global_load_lds_dwordx4 v[244:245], off
	v_lshl_add_u64 v[244:245], s[30:31], 0, v[128:129]
	s_add_i32 m0, s29, 0x2000
	s_nop 0
	global_load_lds_dwordx4 v[244:245], off
	v_lshl_add_u64 v[244:245], s[60:61], 0, v[134:135]
	s_mov_b32 m0, s65
	s_nop 0
	global_load_lds_dwordx4 v[244:245], off
	s_mov_b32 m0, s66
	s_nop 0
	global_load_lds_dwordx4 v[246:247], off
	s_waitcnt vmcnt(8)
	s_waitcnt lgkmcnt(0)
	s_barrier
	s_waitcnt lgkmcnt(0)
	v_mfma_f32_16x16x32_bf16 v[60:63], v[140:143], v[194:197], v[60:63]
	v_mfma_f32_16x16x32_bf16 v[56:59], v[152:155], v[194:197], v[56:59]
	v_mfma_f32_16x16x32_bf16 v[44:47], v[140:143], v[202:205], v[44:47]
	v_mfma_f32_16x16x32_bf16 v[40:43], v[152:155], v[202:205], v[40:43]
	v_mfma_f32_16x16x32_bf16 v[28:31], v[140:143], v[228:231], v[28:31]
	v_mfma_f32_16x16x32_bf16 v[24:27], v[152:155], v[228:231], v[24:27]
	v_mfma_f32_16x16x32_bf16 v[12:15], v[140:143], v[236:239], v[12:15]
	v_mfma_f32_16x16x32_bf16 v[8:11], v[152:155], v[236:239], v[8:11]
	v_mfma_f32_16x16x32_bf16 v[60:63], v[148:151], v[198:201], v[60:63]
	v_mfma_f32_16x16x32_bf16 v[56:59], v[156:159], v[198:201], v[56:59]
	v_mfma_f32_16x16x32_bf16 v[44:47], v[148:151], v[220:223], v[44:47]
	v_mfma_f32_16x16x32_bf16 v[40:43], v[156:159], v[220:223], v[40:43]
	v_mfma_f32_16x16x32_bf16 v[28:31], v[148:151], v[232:235], v[28:31]
	v_mfma_f32_16x16x32_bf16 v[24:27], v[156:159], v[232:235], v[24:27]
	v_mfma_f32_16x16x32_bf16 v[12:15], v[148:151], v[240:243], v[12:15]
	v_mfma_f32_16x16x32_bf16 v[8:11], v[156:159], v[240:243], v[8:11]
	v_mfma_f32_16x16x32_bf16 v[52:55], v[178:181], v[194:197], v[52:55]
	v_mfma_f32_16x16x32_bf16 v[48:51], v[186:189], v[194:197], v[48:51]
	v_mfma_f32_16x16x32_bf16 v[36:39], v[178:181], v[202:205], v[36:39]
	v_mfma_f32_16x16x32_bf16 v[32:35], v[186:189], v[202:205], v[32:35]
	v_mfma_f32_16x16x32_bf16 v[20:23], v[178:181], v[228:231], v[20:23]
	v_mfma_f32_16x16x32_bf16 v[16:19], v[186:189], v[228:231], v[16:19]
	v_mfma_f32_16x16x32_bf16 v[4:7], v[178:181], v[236:239], v[4:7]
	v_mfma_f32_16x16x32_bf16 v[0:3], v[186:189], v[236:239], v[0:3]
	v_mfma_f32_16x16x32_bf16 v[52:55], v[182:185], v[198:201], v[52:55]
	v_mfma_f32_16x16x32_bf16 v[48:51], v[190:193], v[198:201], v[48:51]
	v_mfma_f32_16x16x32_bf16 v[36:39], v[182:185], v[220:223], v[36:39]
	v_mfma_f32_16x16x32_bf16 v[32:35], v[190:193], v[220:223], v[32:35]
	v_mfma_f32_16x16x32_bf16 v[20:23], v[182:185], v[232:235], v[20:23]
	v_mfma_f32_16x16x32_bf16 v[16:19], v[190:193], v[232:235], v[16:19]
	v_mfma_f32_16x16x32_bf16 v[4:7], v[182:185], v[240:243], v[4:7]
	v_mfma_f32_16x16x32_bf16 v[0:3], v[190:193], v[240:243], v[0:3]
	s_barrier
	s_add_i32 s29, 0, 0x18000
	s_add_i32 s49, 0, 0x1c000
	v_add_u32_e32 v156, s29, v145
	v_add_u32_e32 v162, s49, v145
	ds_read_b128 v[140:143], v156
	ds_read_b128 v[148:151], v156 offset:1024
	ds_read_b128 v[152:155], v156 offset:2048
	ds_read_b128 v[156:159], v156 offset:3072
	ds_read_b128 v[178:181], v162
	ds_read_b128 v[182:185], v162 offset:1024
	ds_read_b128 v[186:189], v162 offset:2048
	ds_read_b128 v[190:193], v162 offset:3072
	s_add_u32 s30, s60, 0x40000
	s_addc_u32 s31, s61, 0
	s_mov_b32 m0, s67
	v_lshl_add_u64 v[248:249], s[30:31], 0, v[134:135]
	ds_read_b128 v[194:197], v147 offset:32768
	ds_read_b128 v[198:201], v147 offset:33792
	ds_read_b128 v[202:205], v147 offset:34816
	ds_read_b128 v[220:223], v147 offset:35840
	ds_read_b128 v[228:231], v147 offset:36864
	ds_read_b128 v[232:235], v147 offset:37888
	ds_read_b128 v[236:239], v147 offset:38912
	ds_read_b128 v[240:243], v147 offset:39936
	global_load_lds_dwordx4 v[248:249], off
	v_lshl_add_u64 v[248:249], s[30:31], 0, v[130:131]
	s_mov_b32 m0, s68
	s_nop 0
	global_load_lds_dwordx4 v[248:249], off
	s_waitcnt vmcnt(8)
	s_waitcnt lgkmcnt(0)
	s_barrier
	s_waitcnt lgkmcnt(0)
	v_mfma_f32_16x16x32_bf16 v[124:127], v[140:143], v[194:197], v[124:127]
	v_mfma_f32_16x16x32_bf16 v[120:123], v[152:155], v[194:197], v[120:123]
	v_mfma_f32_16x16x32_bf16 v[108:111], v[140:143], v[202:205], v[108:111]
	v_mfma_f32_16x16x32_bf16 v[104:107], v[152:155], v[202:205], v[104:107]
	v_mfma_f32_16x16x32_bf16 v[92:95], v[140:143], v[228:231], v[92:95]
	v_mfma_f32_16x16x32_bf16 v[88:91], v[152:155], v[228:231], v[88:91]
	v_mfma_f32_16x16x32_bf16 v[76:79], v[140:143], v[236:239], v[76:79]
	v_mfma_f32_16x16x32_bf16 v[72:75], v[152:155], v[236:239], v[72:75]
	v_mfma_f32_16x16x32_bf16 v[124:127], v[148:151], v[198:201], v[124:127]
	v_mfma_f32_16x16x32_bf16 v[120:123], v[156:159], v[198:201], v[120:123]
	v_mfma_f32_16x16x32_bf16 v[108:111], v[148:151], v[220:223], v[108:111]
	v_mfma_f32_16x16x32_bf16 v[104:107], v[156:159], v[220:223], v[104:107]
	v_mfma_f32_16x16x32_bf16 v[92:95], v[148:151], v[232:235], v[92:95]
	v_mfma_f32_16x16x32_bf16 v[88:91], v[156:159], v[232:235], v[88:91]
	v_mfma_f32_16x16x32_bf16 v[76:79], v[148:151], v[240:243], v[76:79]
	v_mfma_f32_16x16x32_bf16 v[72:75], v[156:159], v[240:243], v[72:75]
	v_mfma_f32_16x16x32_bf16 v[116:119], v[178:181], v[194:197], v[116:119]
	v_mfma_f32_16x16x32_bf16 v[112:115], v[186:189], v[194:197], v[112:115]
	v_mfma_f32_16x16x32_bf16 v[100:103], v[178:181], v[202:205], v[100:103]
	v_mfma_f32_16x16x32_bf16 v[96:99], v[186:189], v[202:205], v[96:99]
	v_mfma_f32_16x16x32_bf16 v[84:87], v[178:181], v[228:231], v[84:87]
	v_mfma_f32_16x16x32_bf16 v[80:83], v[186:189], v[228:231], v[80:83]
	v_mfma_f32_16x16x32_bf16 v[68:71], v[178:181], v[236:239], v[68:71]
	v_mfma_f32_16x16x32_bf16 v[64:67], v[186:189], v[236:239], v[64:67]
	v_mfma_f32_16x16x32_bf16 v[116:119], v[182:185], v[198:201], v[116:119]
	v_mfma_f32_16x16x32_bf16 v[112:115], v[190:193], v[198:201], v[112:115]
	v_mfma_f32_16x16x32_bf16 v[100:103], v[182:185], v[220:223], v[100:103]
	v_mfma_f32_16x16x32_bf16 v[96:99], v[190:193], v[220:223], v[96:99]
	v_mfma_f32_16x16x32_bf16 v[84:87], v[182:185], v[232:235], v[84:87]
	v_mfma_f32_16x16x32_bf16 v[80:83], v[190:193], v[232:235], v[80:83]
	v_mfma_f32_16x16x32_bf16 v[68:71], v[182:185], v[240:243], v[68:71]
	v_mfma_f32_16x16x32_bf16 v[64:67], v[190:193], v[240:243], v[64:67]
	s_barrier
	s_add_i32 s29, s29, s64
	v_lshl_add_u64 v[174:175], v[174:175], 0, s[4:5]
	s_mov_b32 m0, s29
	ds_read_b128 v[194:197], v147 offset:49152
	ds_read_b128 v[198:201], v147 offset:50176
	ds_read_b128 v[202:205], v147 offset:51200
	ds_read_b128 v[220:223], v147 offset:52224
	ds_read_b128 v[228:231], v147 offset:53248
	ds_read_b128 v[232:235], v147 offset:54272
	ds_read_b128 v[236:239], v147 offset:55296
	ds_read_b128 v[240:243], v147 offset:56320
	global_load_lds_dwordx4 v[174:175], off
	s_add_i32 m0, s29, 0x2000
	s_add_u32 s30, s58, 0x40080
	v_lshl_add_u64 v[174:175], v[176:177], 0, s[4:5]
	s_addc_u32 s31, s59, 0
	s_add_i32 s29, s49, s64
	global_load_lds_dwordx4 v[174:175], off
	v_lshl_add_u64 v[174:175], s[30:31], 0, v[132:133]
	s_mov_b32 m0, s29
	s_nop 0
	global_load_lds_dwordx4 v[174:175], off
	v_lshl_add_u64 v[174:175], s[30:31], 0, v[128:129]
	s_add_i32 m0, s29, 0x2000
	s_nop 0
	global_load_lds_dwordx4 v[174:175], off
	v_lshl_add_u64 v[174:175], v[244:245], 0, s[4:5]
	s_mov_b32 m0, s73
	s_nop 0
	global_load_lds_dwordx4 v[174:175], off
	v_lshl_add_u64 v[174:175], v[246:247], 0, s[4:5]
	s_mov_b32 m0, s74
	s_nop 0
	global_load_lds_dwordx4 v[174:175], off
	s_waitcnt vmcnt(8)
	s_waitcnt lgkmcnt(0)
	s_barrier
	s_waitcnt lgkmcnt(0)
	v_mfma_f32_16x16x32_bf16 v[60:63], v[140:143], v[194:197], v[60:63]
	v_mfma_f32_16x16x32_bf16 v[56:59], v[152:155], v[194:197], v[56:59]
	v_mfma_f32_16x16x32_bf16 v[44:47], v[140:143], v[202:205], v[44:47]
	v_mfma_f32_16x16x32_bf16 v[40:43], v[152:155], v[202:205], v[40:43]
	v_mfma_f32_16x16x32_bf16 v[28:31], v[140:143], v[228:231], v[28:31]
	v_mfma_f32_16x16x32_bf16 v[24:27], v[152:155], v[228:231], v[24:27]
	v_mfma_f32_16x16x32_bf16 v[12:15], v[140:143], v[236:239], v[12:15]
	v_mfma_f32_16x16x32_bf16 v[8:11], v[152:155], v[236:239], v[8:11]
	v_mfma_f32_16x16x32_bf16 v[60:63], v[148:151], v[198:201], v[60:63]
	v_mfma_f32_16x16x32_bf16 v[56:59], v[156:159], v[198:201], v[56:59]
	v_mfma_f32_16x16x32_bf16 v[44:47], v[148:151], v[220:223], v[44:47]
	v_mfma_f32_16x16x32_bf16 v[40:43], v[156:159], v[220:223], v[40:43]
	v_mfma_f32_16x16x32_bf16 v[28:31], v[148:151], v[232:235], v[28:31]
	v_mfma_f32_16x16x32_bf16 v[24:27], v[156:159], v[232:235], v[24:27]
	v_mfma_f32_16x16x32_bf16 v[12:15], v[148:151], v[240:243], v[12:15]
	v_mfma_f32_16x16x32_bf16 v[8:11], v[156:159], v[240:243], v[8:11]
	v_mfma_f32_16x16x32_bf16 v[52:55], v[178:181], v[194:197], v[52:55]
	v_mfma_f32_16x16x32_bf16 v[48:51], v[186:189], v[194:197], v[48:51]
	v_mfma_f32_16x16x32_bf16 v[36:39], v[178:181], v[202:205], v[36:39]
	v_mfma_f32_16x16x32_bf16 v[32:35], v[186:189], v[202:205], v[32:35]
	v_mfma_f32_16x16x32_bf16 v[20:23], v[178:181], v[228:231], v[20:23]
	v_mfma_f32_16x16x32_bf16 v[16:19], v[186:189], v[228:231], v[16:19]
	v_mfma_f32_16x16x32_bf16 v[4:7], v[178:181], v[236:239], v[4:7]
	v_mfma_f32_16x16x32_bf16 v[0:3], v[186:189], v[236:239], v[0:3]
	v_mfma_f32_16x16x32_bf16 v[52:55], v[182:185], v[198:201], v[52:55]
	v_mfma_f32_16x16x32_bf16 v[48:51], v[190:193], v[198:201], v[48:51]
	v_mfma_f32_16x16x32_bf16 v[36:39], v[182:185], v[220:223], v[36:39]
	v_mfma_f32_16x16x32_bf16 v[32:35], v[190:193], v[220:223], v[32:35]
	v_mfma_f32_16x16x32_bf16 v[20:23], v[182:185], v[232:235], v[20:23]
	v_mfma_f32_16x16x32_bf16 v[16:19], v[190:193], v[232:235], v[16:19]
	v_mfma_f32_16x16x32_bf16 v[4:7], v[182:185], v[240:243], v[4:7]
	v_mfma_f32_16x16x32_bf16 v[0:3], v[190:193], v[240:243], v[0:3]
	s_barrier
	s_add_i32 s28, s28, 2
	s_add_u32 s56, s56, 0x100
	s_addc_u32 s57, s57, 0
	s_add_u32 s26, s26, 0x100
	s_addc_u32 s27, s27, 0
	s_cmp_gt_u32 s28, 13
	s_cbranch_scc0 .LBB0_179
	s_and_b64 vcc, exec, s[46:47]
	s_cbranch_vccz .LBB0_182
	s_barrier

.LBB0_204:
	s_add_u32 s28, s42, 0xfffc0080
	s_addc_u32 s29, s43, -1
	s_add_i32 s30, 0, 0x10000
	s_cmp_eq_u32 s27, 12
	s_cselect_b32 s63, s6, s29
	s_cselect_b32 s62, s7, s28
	s_cselect_b32 s61, s23, s26
	s_cselect_b32 s60, s24, s25
	s_add_i32 s31, 0, 0x14000
	v_add_u32_e32 v140, s30, v221
	v_add_u32_e32 v156, s31, v221
	ds_read_b128 v[128:131], v140
	ds_read_b128 v[132:135], v140 offset:1024
	ds_read_b128 v[136:139], v140 offset:2048
	ds_read_b128 v[140:143], v140 offset:3072
	ds_read_b128 v[144:147], v156
	ds_read_b128 v[148:151], v156 offset:1024
	ds_read_b128 v[152:155], v156 offset:2048
	ds_read_b128 v[156:159], v156 offset:3072
	v_lshl_add_u64 v[174:175], s[42:43], 0, v[184:185]
	s_add_i32 m0, s67, 0xc000
	ds_read_b128 v[188:191], v223
	ds_read_b128 v[192:195], v223 offset:1024
	ds_read_b128 v[196:199], v223 offset:2048
	ds_read_b128 v[200:203], v223 offset:3072
	ds_read_b128 v[228:231], v223 offset:4096
	ds_read_b128 v[232:235], v223 offset:5120
	ds_read_b128 v[236:239], v223 offset:6144
	ds_read_b128 v[240:243], v223 offset:7168
	global_load_lds_dwordx4 v[174:175], off
	v_lshl_add_u64 v[174:175], s[42:43], 0, v[186:187]
	s_add_i32 m0, s67, 0xe000
	s_nop 0
	global_load_lds_dwordx4 v[174:175], off
	s_waitcnt vmcnt(8)
	s_waitcnt lgkmcnt(0)
	s_barrier
	s_waitcnt lgkmcnt(0)
	v_mfma_f32_16x16x32_bf16 v[124:127], v[128:131], v[188:191], v[124:127]
	v_mfma_f32_16x16x32_bf16 v[120:123], v[136:139], v[188:191], v[120:123]
	v_mfma_f32_16x16x32_bf16 v[116:119], v[128:131], v[196:199], v[116:119]
	v_mfma_f32_16x16x32_bf16 v[108:111], v[136:139], v[196:199], v[108:111]
	v_mfma_f32_16x16x32_bf16 v[100:103], v[128:131], v[228:231], v[100:103]
	v_mfma_f32_16x16x32_bf16 v[92:95], v[136:139], v[228:231], v[92:95]
	v_mfma_f32_16x16x32_bf16 v[84:87], v[128:131], v[236:239], v[84:87]
	v_mfma_f32_16x16x32_bf16 v[76:79], v[136:139], v[236:239], v[76:79]
	v_mfma_f32_16x16x32_bf16 v[124:127], v[132:135], v[192:195], v[124:127]
	v_mfma_f32_16x16x32_bf16 v[120:123], v[140:143], v[192:195], v[120:123]
	v_mfma_f32_16x16x32_bf16 v[116:119], v[132:135], v[200:203], v[116:119]
	v_mfma_f32_16x16x32_bf16 v[108:111], v[140:143], v[200:203], v[108:111]
	v_mfma_f32_16x16x32_bf16 v[100:103], v[132:135], v[232:235], v[100:103]
	v_mfma_f32_16x16x32_bf16 v[92:95], v[140:143], v[232:235], v[92:95]
	v_mfma_f32_16x16x32_bf16 v[84:87], v[132:135], v[240:243], v[84:87]
	v_mfma_f32_16x16x32_bf16 v[76:79], v[140:143], v[240:243], v[76:79]
	v_mfma_f32_16x16x32_bf16 v[112:115], v[144:147], v[188:191], v[112:115]
	v_mfma_f32_16x16x32_bf16 v[104:107], v[152:155], v[188:191], v[104:107]
	v_mfma_f32_16x16x32_bf16 v[96:99], v[144:147], v[196:199], v[96:99]
	v_mfma_f32_16x16x32_bf16 v[88:91], v[152:155], v[196:199], v[88:91]
	v_mfma_f32_16x16x32_bf16 v[80:83], v[144:147], v[228:231], v[80:83]
	v_mfma_f32_16x16x32_bf16 v[72:75], v[152:155], v[228:231], v[72:75]
	v_mfma_f32_16x16x32_bf16 v[68:71], v[144:147], v[236:239], v[68:71]
	v_mfma_f32_16x16x32_bf16 v[64:67], v[152:155], v[236:239], v[64:67]
	v_mfma_f32_16x16x32_bf16 v[112:115], v[148:151], v[192:195], v[112:115]
	v_mfma_f32_16x16x32_bf16 v[104:107], v[156:159], v[192:195], v[104:107]
	v_mfma_f32_16x16x32_bf16 v[96:99], v[148:151], v[200:203], v[96:99]
	v_mfma_f32_16x16x32_bf16 v[88:91], v[156:159], v[200:203], v[88:91]
	v_mfma_f32_16x16x32_bf16 v[80:83], v[148:151], v[232:235], v[80:83]
	v_mfma_f32_16x16x32_bf16 v[72:75], v[156:159], v[232:235], v[72:75]
	v_mfma_f32_16x16x32_bf16 v[68:71], v[148:151], v[240:243], v[68:71]
	v_mfma_f32_16x16x32_bf16 v[64:67], v[156:159], v[240:243], v[64:67]
	s_barrier
	s_add_i32 s28, s30, s66
	v_lshl_add_u64 v[174:175], s[60:61], 0, v[162:163]
	s_mov_b32 m0, s28
	ds_read_b128 v[188:191], v223 offset:16384
	ds_read_b128 v[192:195], v223 offset:17408
	ds_read_b128 v[196:199], v223 offset:18432
	ds_read_b128 v[200:203], v223 offset:19456
	ds_read_b128 v[228:231], v223 offset:20480
	ds_read_b128 v[232:235], v223 offset:21504
	ds_read_b128 v[236:239], v223 offset:22528
	ds_read_b128 v[240:243], v223 offset:23552
	global_load_lds_dwordx4 v[174:175], off
	s_add_i32 m0, s28, 0x2000
	s_add_u32 s28, s60, 0x40000
	v_lshl_add_u64 v[176:177], s[60:61], 0, v[178:179]
	s_addc_u32 s29, s61, 0
	s_add_i32 s30, s31, s66
	global_load_lds_dwordx4 v[176:177], off
	v_lshl_add_u64 v[204:205], s[28:29], 0, v[162:163]
	s_mov_b32 m0, s30
	v_lshl_add_u64 v[244:245], s[62:63], 0, v[180:181]
	global_load_lds_dwordx4 v[204:205], off
	v_lshl_add_u64 v[204:205], s[28:29], 0, v[178:179]
	s_add_i32 m0, s30, 0x2000
	s_nop 0
	global_load_lds_dwordx4 v[204:205], off
	v_lshl_add_u64 v[204:205], s[62:63], 0, v[182:183]
	s_mov_b32 m0, s67
	s_nop 0
	global_load_lds_dwordx4 v[204:205], off
	s_mov_b32 m0, s68
	s_nop 0
	global_load_lds_dwordx4 v[244:245], off
	s_waitcnt vmcnt(8)
	s_waitcnt lgkmcnt(0)
	s_barrier
	s_waitcnt lgkmcnt(0)
	v_mfma_f32_16x16x32_bf16 v[60:63], v[128:131], v[188:191], v[60:63]
	v_mfma_f32_16x16x32_bf16 v[56:59], v[136:139], v[188:191], v[56:59]
	v_mfma_f32_16x16x32_bf16 v[52:55], v[128:131], v[196:199], v[52:55]
	v_mfma_f32_16x16x32_bf16 v[44:47], v[136:139], v[196:199], v[44:47]
	v_mfma_f32_16x16x32_bf16 v[36:39], v[128:131], v[228:231], v[36:39]
	v_mfma_f32_16x16x32_bf16 v[28:31], v[136:139], v[228:231], v[28:31]
	v_mfma_f32_16x16x32_bf16 v[20:23], v[128:131], v[236:239], v[20:23]
	v_mfma_f32_16x16x32_bf16 v[12:15], v[136:139], v[236:239], v[12:15]
	v_mfma_f32_16x16x32_bf16 v[60:63], v[132:135], v[192:195], v[60:63]
	v_mfma_f32_16x16x32_bf16 v[56:59], v[140:143], v[192:195], v[56:59]
	v_mfma_f32_16x16x32_bf16 v[52:55], v[132:135], v[200:203], v[52:55]
	v_mfma_f32_16x16x32_bf16 v[44:47], v[140:143], v[200:203], v[44:47]
	v_mfma_f32_16x16x32_bf16 v[36:39], v[132:135], v[232:235], v[36:39]
	v_mfma_f32_16x16x32_bf16 v[28:31], v[140:143], v[232:235], v[28:31]
	v_mfma_f32_16x16x32_bf16 v[20:23], v[132:135], v[240:243], v[20:23]
	v_mfma_f32_16x16x32_bf16 v[12:15], v[140:143], v[240:243], v[12:15]
	v_mfma_f32_16x16x32_bf16 v[48:51], v[144:147], v[188:191], v[48:51]
	v_mfma_f32_16x16x32_bf16 v[40:43], v[152:155], v[188:191], v[40:43]
	v_mfma_f32_16x16x32_bf16 v[32:35], v[144:147], v[196:199], v[32:35]
	v_mfma_f32_16x16x32_bf16 v[24:27], v[152:155], v[196:199], v[24:27]
	v_mfma_f32_16x16x32_bf16 v[16:19], v[144:147], v[228:231], v[16:19]
	v_mfma_f32_16x16x32_bf16 v[8:11], v[152:155], v[228:231], v[8:11]
	v_mfma_f32_16x16x32_bf16 v[4:7], v[144:147], v[236:239], v[4:7]
	v_mfma_f32_16x16x32_bf16 v[0:3], v[152:155], v[236:239], v[0:3]
	v_mfma_f32_16x16x32_bf16 v[48:51], v[148:151], v[192:195], v[48:51]
	v_mfma_f32_16x16x32_bf16 v[40:43], v[156:159], v[192:195], v[40:43]
	v_mfma_f32_16x16x32_bf16 v[32:35], v[148:151], v[200:203], v[32:35]
	v_mfma_f32_16x16x32_bf16 v[24:27], v[156:159], v[200:203], v[24:27]
	v_mfma_f32_16x16x32_bf16 v[16:19], v[148:151], v[232:235], v[16:19]
	v_mfma_f32_16x16x32_bf16 v[8:11], v[156:159], v[232:235], v[8:11]
	v_mfma_f32_16x16x32_bf16 v[4:7], v[148:151], v[240:243], v[4:7]
	v_mfma_f32_16x16x32_bf16 v[0:3], v[156:159], v[240:243], v[0:3]
	s_barrier
	s_add_i32 s30, 0, 0x18000
	s_add_i32 s31, 0, 0x1c000
	v_add_u32_e32 v140, s30, v221
	v_add_u32_e32 v156, s31, v221
	ds_read_b128 v[128:131], v140
	ds_read_b128 v[132:135], v140 offset:1024
	ds_read_b128 v[136:139], v140 offset:2048
	ds_read_b128 v[140:143], v140 offset:3072
	ds_read_b128 v[144:147], v156
	ds_read_b128 v[148:151], v156 offset:1024
	ds_read_b128 v[152:155], v156 offset:2048
	ds_read_b128 v[156:159], v156 offset:3072
	s_add_u32 s28, s62, 0x40000
	s_addc_u32 s29, s63, 0
	s_mov_b32 m0, s69
	v_lshl_add_u64 v[246:247], s[28:29], 0, v[182:183]
	ds_read_b128 v[188:191], v223 offset:32768
	ds_read_b128 v[192:195], v223 offset:33792
	ds_read_b128 v[196:199], v223 offset:34816
	ds_read_b128 v[200:203], v223 offset:35840
	ds_read_b128 v[228:231], v223 offset:36864
	ds_read_b128 v[232:235], v223 offset:37888
	ds_read_b128 v[236:239], v223 offset:38912
	ds_read_b128 v[240:243], v223 offset:39936
	global_load_lds_dwordx4 v[246:247], off
	v_lshl_add_u64 v[246:247], s[28:29], 0, v[180:181]
	s_mov_b32 m0, s70
	s_nop 0
	global_load_lds_dwordx4 v[246:247], off
	s_waitcnt vmcnt(8)
	s_waitcnt lgkmcnt(0)
	s_barrier
	s_waitcnt lgkmcnt(0)
	v_mfma_f32_16x16x32_bf16 v[124:127], v[128:131], v[188:191], v[124:127]
	v_mfma_f32_16x16x32_bf16 v[120:123], v[136:139], v[188:191], v[120:123]
	v_mfma_f32_16x16x32_bf16 v[116:119], v[128:131], v[196:199], v[116:119]
	v_mfma_f32_16x16x32_bf16 v[108:111], v[136:139], v[196:199], v[108:111]
	v_mfma_f32_16x16x32_bf16 v[100:103], v[128:131], v[228:231], v[100:103]
	v_mfma_f32_16x16x32_bf16 v[92:95], v[136:139], v[228:231], v[92:95]
	v_mfma_f32_16x16x32_bf16 v[84:87], v[128:131], v[236:239], v[84:87]
	v_mfma_f32_16x16x32_bf16 v[76:79], v[136:139], v[236:239], v[76:79]
	v_mfma_f32_16x16x32_bf16 v[124:127], v[132:135], v[192:195], v[124:127]
	v_mfma_f32_16x16x32_bf16 v[120:123], v[140:143], v[192:195], v[120:123]
	v_mfma_f32_16x16x32_bf16 v[116:119], v[132:135], v[200:203], v[116:119]
	v_mfma_f32_16x16x32_bf16 v[108:111], v[140:143], v[200:203], v[108:111]
	v_mfma_f32_16x16x32_bf16 v[100:103], v[132:135], v[232:235], v[100:103]
	v_mfma_f32_16x16x32_bf16 v[92:95], v[140:143], v[232:235], v[92:95]
	v_mfma_f32_16x16x32_bf16 v[84:87], v[132:135], v[240:243], v[84:87]
	v_mfma_f32_16x16x32_bf16 v[76:79], v[140:143], v[240:243], v[76:79]
	v_mfma_f32_16x16x32_bf16 v[112:115], v[144:147], v[188:191], v[112:115]
	v_mfma_f32_16x16x32_bf16 v[104:107], v[152:155], v[188:191], v[104:107]
	v_mfma_f32_16x16x32_bf16 v[96:99], v[144:147], v[196:199], v[96:99]
	v_mfma_f32_16x16x32_bf16 v[88:91], v[152:155], v[196:199], v[88:91]
	v_mfma_f32_16x16x32_bf16 v[80:83], v[144:147], v[228:231], v[80:83]
	v_mfma_f32_16x16x32_bf16 v[72:75], v[152:155], v[228:231], v[72:75]
	v_mfma_f32_16x16x32_bf16 v[68:71], v[144:147], v[236:239], v[68:71]
	v_mfma_f32_16x16x32_bf16 v[64:67], v[152:155], v[236:239], v[64:67]
	v_mfma_f32_16x16x32_bf16 v[112:115], v[148:151], v[192:195], v[112:115]
	v_mfma_f32_16x16x32_bf16 v[104:107], v[156:159], v[192:195], v[104:107]
	v_mfma_f32_16x16x32_bf16 v[96:99], v[148:151], v[200:203], v[96:99]
	v_mfma_f32_16x16x32_bf16 v[88:91], v[156:159], v[200:203], v[88:91]
	v_mfma_f32_16x16x32_bf16 v[80:83], v[148:151], v[232:235], v[80:83]
	v_mfma_f32_16x16x32_bf16 v[72:75], v[156:159], v[232:235], v[72:75]
	v_mfma_f32_16x16x32_bf16 v[68:71], v[148:151], v[240:243], v[68:71]
	v_mfma_f32_16x16x32_bf16 v[64:67], v[156:159], v[240:243], v[64:67]
	s_barrier
	s_add_i32 s28, s30, s66
	v_lshl_add_u64 v[174:175], v[174:175], 0, s[4:5]
	s_mov_b32 m0, s28
	ds_read_b128 v[188:191], v223 offset:49152
	ds_read_b128 v[192:195], v223 offset:50176
	ds_read_b128 v[196:199], v223 offset:51200
	ds_read_b128 v[200:203], v223 offset:52224
	ds_read_b128 v[228:231], v223 offset:53248
	ds_read_b128 v[232:235], v223 offset:54272
	ds_read_b128 v[236:239], v223 offset:55296
	ds_read_b128 v[240:243], v223 offset:56320
	global_load_lds_dwordx4 v[174:175], off
	s_add_i32 m0, s28, 0x2000
	s_add_u32 s28, s60, 0x40080
	v_lshl_add_u64 v[174:175], v[176:177], 0, s[4:5]
	s_addc_u32 s29, s61, 0
	s_add_i32 s30, s31, s66
	global_load_lds_dwordx4 v[174:175], off
	v_lshl_add_u64 v[174:175], s[28:29], 0, v[162:163]
	s_mov_b32 m0, s30
	s_nop 0
	global_load_lds_dwordx4 v[174:175], off
	v_lshl_add_u64 v[174:175], s[28:29], 0, v[178:179]
	s_add_i32 m0, s30, 0x2000
	s_nop 0
	global_load_lds_dwordx4 v[174:175], off
	v_lshl_add_u64 v[174:175], v[204:205], 0, s[4:5]
	s_mov_b32 m0, s71
	s_nop 0
	global_load_lds_dwordx4 v[174:175], off
	v_lshl_add_u64 v[174:175], v[244:245], 0, s[4:5]
	s_mov_b32 m0, s72
	s_nop 0
	global_load_lds_dwordx4 v[174:175], off
	s_waitcnt vmcnt(8)
	s_waitcnt lgkmcnt(0)
	s_barrier
	s_waitcnt lgkmcnt(0)
	v_mfma_f32_16x16x32_bf16 v[60:63], v[128:131], v[188:191], v[60:63]
	v_mfma_f32_16x16x32_bf16 v[56:59], v[136:139], v[188:191], v[56:59]
	v_mfma_f32_16x16x32_bf16 v[52:55], v[128:131], v[196:199], v[52:55]
	v_mfma_f32_16x16x32_bf16 v[44:47], v[136:139], v[196:199], v[44:47]
	v_mfma_f32_16x16x32_bf16 v[36:39], v[128:131], v[228:231], v[36:39]
	v_mfma_f32_16x16x32_bf16 v[28:31], v[136:139], v[228:231], v[28:31]
	v_mfma_f32_16x16x32_bf16 v[20:23], v[128:131], v[236:239], v[20:23]
	v_mfma_f32_16x16x32_bf16 v[12:15], v[136:139], v[236:239], v[12:15]
	v_mfma_f32_16x16x32_bf16 v[60:63], v[132:135], v[192:195], v[60:63]
	v_mfma_f32_16x16x32_bf16 v[56:59], v[140:143], v[192:195], v[56:59]
	v_mfma_f32_16x16x32_bf16 v[52:55], v[132:135], v[200:203], v[52:55]
	v_mfma_f32_16x16x32_bf16 v[44:47], v[140:143], v[200:203], v[44:47]
	v_mfma_f32_16x16x32_bf16 v[36:39], v[132:135], v[232:235], v[36:39]
	v_mfma_f32_16x16x32_bf16 v[28:31], v[140:143], v[232:235], v[28:31]
	v_mfma_f32_16x16x32_bf16 v[20:23], v[132:135], v[240:243], v[20:23]
	v_mfma_f32_16x16x32_bf16 v[12:15], v[140:143], v[240:243], v[12:15]
	v_mfma_f32_16x16x32_bf16 v[48:51], v[144:147], v[188:191], v[48:51]
	v_mfma_f32_16x16x32_bf16 v[40:43], v[152:155], v[188:191], v[40:43]
	v_mfma_f32_16x16x32_bf16 v[32:35], v[144:147], v[196:199], v[32:35]
	v_mfma_f32_16x16x32_bf16 v[24:27], v[152:155], v[196:199], v[24:27]
	v_mfma_f32_16x16x32_bf16 v[16:19], v[144:147], v[228:231], v[16:19]
	v_mfma_f32_16x16x32_bf16 v[8:11], v[152:155], v[228:231], v[8:11]
	v_mfma_f32_16x16x32_bf16 v[4:7], v[144:147], v[236:239], v[4:7]
	v_mfma_f32_16x16x32_bf16 v[0:3], v[152:155], v[236:239], v[0:3]
	v_mfma_f32_16x16x32_bf16 v[48:51], v[148:151], v[192:195], v[48:51]
	v_mfma_f32_16x16x32_bf16 v[40:43], v[156:159], v[192:195], v[40:43]
	v_mfma_f32_16x16x32_bf16 v[32:35], v[148:151], v[200:203], v[32:35]
	v_mfma_f32_16x16x32_bf16 v[24:27], v[156:159], v[200:203], v[24:27]
	v_mfma_f32_16x16x32_bf16 v[16:19], v[148:151], v[232:235], v[16:19]
	v_mfma_f32_16x16x32_bf16 v[8:11], v[156:159], v[232:235], v[8:11]
	v_mfma_f32_16x16x32_bf16 v[4:7], v[148:151], v[240:243], v[4:7]
	v_mfma_f32_16x16x32_bf16 v[0:3], v[156:159], v[240:243], v[0:3]
	s_barrier
	s_add_i32 s27, s27, 2
	s_add_u32 s42, s42, 0x100
	s_addc_u32 s43, s43, 0
	s_add_u32 s25, s25, 0x100
	s_addc_u32 s26, s26, 0
	s_cmp_gt_u32 s27, 13
	s_cbranch_scc0 .LBB0_204
	s_and_b64 vcc, exec, s[50:51]
	s_cbranch_vccz .LBB0_207
	s_barrier

.LBB0_502:
	s_add_i32 s62, 0, 0x10000
	s_add_i32 s61, 0, 0x14000
	v_add_u32_e32 v19, s62, v16
	v_add_u32_e32 v20, s61, v16
	ds_read_b128 v[22:25], v19
	ds_read_b128 v[26:29], v19 offset:1024
	ds_read_b128 v[30:33], v19 offset:2048
	ds_read_b128 v[34:37], v19 offset:3072
	ds_read_b128 v[38:41], v20
	ds_read_b128 v[42:45], v20 offset:1024
	ds_read_b128 v[46:49], v20 offset:2048
	ds_read_b128 v[50:53], v20 offset:3072
	s_add_u32 s58, s50, 0x18080
	s_addc_u32 s59, s51, 0
	s_add_i32 s65, s26, 0xc000
	v_lshl_add_u64 v[78:79], s[58:59], 0, v[6:7]
	s_mov_b32 m0, s65
	s_add_i32 s57, s26, 0xe000
	ds_read_b128 v[8:11], v17
	ds_read_b128 v[12:15], v17 offset:1024
	ds_read_b128 v[54:57], v17 offset:2048
	ds_read_b128 v[58:61], v17 offset:3072
	ds_read_b128 v[62:65], v17 offset:4096
	ds_read_b128 v[66:69], v17 offset:5120
	ds_read_b128 v[70:73], v17 offset:6144
	ds_read_b128 v[74:77], v17 offset:7168
	global_load_lds_dwordx4 v[78:79], off
	v_lshl_add_u64 v[78:79], s[58:59], 0, v[2:3]
	s_mov_b32 m0, s57
	s_nop 0
	global_load_lds_dwordx4 v[78:79], off
	s_waitcnt vmcnt(8)
	s_waitcnt lgkmcnt(0)
	s_barrier
	s_waitcnt lgkmcnt(0)
	v_mfma_f32_16x16x32_bf16 v[78:81], v[22:25], v[8:11], 0
	v_mfma_f32_16x16x32_bf16 v[82:85], v[30:33], v[8:11], 0
	v_mfma_f32_16x16x32_bf16 v[86:89], v[22:25], v[54:57], 0
	v_mfma_f32_16x16x32_bf16 v[90:93], v[30:33], v[54:57], 0
	v_mfma_f32_16x16x32_bf16 v[94:97], v[22:25], v[62:65], 0
	v_mfma_f32_16x16x32_bf16 v[98:101], v[30:33], v[62:65], 0
	v_mfma_f32_16x16x32_bf16 v[102:105], v[22:25], v[70:73], 0
	v_mfma_f32_16x16x32_bf16 v[106:109], v[30:33], v[70:73], 0
	v_mfma_f32_16x16x32_bf16 v[78:81], v[26:29], v[12:15], v[78:81]
	v_mfma_f32_16x16x32_bf16 v[82:85], v[34:37], v[12:15], v[82:85]
	v_mfma_f32_16x16x32_bf16 v[86:89], v[26:29], v[58:61], v[86:89]
	v_mfma_f32_16x16x32_bf16 v[90:93], v[34:37], v[58:61], v[90:93]
	v_mfma_f32_16x16x32_bf16 v[94:97], v[26:29], v[66:69], v[94:97]
	v_mfma_f32_16x16x32_bf16 v[98:101], v[34:37], v[66:69], v[98:101]
	v_mfma_f32_16x16x32_bf16 v[102:105], v[26:29], v[74:77], v[102:105]
	v_mfma_f32_16x16x32_bf16 v[106:109], v[34:37], v[74:77], v[106:109]
	v_mfma_f32_16x16x32_bf16 v[110:113], v[38:41], v[8:11], 0
	v_mfma_f32_16x16x32_bf16 v[8:11], v[46:49], v[8:11], 0
	v_mfma_f32_16x16x32_bf16 v[114:117], v[50:53], v[12:15], v[8:11]
	v_mfma_f32_16x16x32_bf16 v[8:11], v[38:41], v[54:57], 0
	v_mfma_f32_16x16x32_bf16 v[118:121], v[42:45], v[58:61], v[8:11]
	v_mfma_f32_16x16x32_bf16 v[8:11], v[46:49], v[54:57], 0
	v_mfma_f32_16x16x32_bf16 v[54:57], v[50:53], v[58:61], v[8:11]
	v_mfma_f32_16x16x32_bf16 v[8:11], v[38:41], v[62:65], 0
	v_mfma_f32_16x16x32_bf16 v[58:61], v[42:45], v[66:69], v[8:11]
	v_mfma_f32_16x16x32_bf16 v[8:11], v[46:49], v[62:65], 0
	v_mfma_f32_16x16x32_bf16 v[62:65], v[50:53], v[66:69], v[8:11]
	v_mfma_f32_16x16x32_bf16 v[8:11], v[38:41], v[70:73], 0
	v_mfma_f32_16x16x32_bf16 v[66:69], v[42:45], v[74:77], v[8:11]
	v_mfma_f32_16x16x32_bf16 v[8:11], v[46:49], v[70:73], 0
	v_mfma_f32_16x16x32_bf16 v[110:113], v[42:45], v[12:15], v[110:113]
	v_mfma_f32_16x16x32_bf16 v[70:73], v[50:53], v[74:77], v[8:11]
	s_barrier
	s_nop 3
	v_lshl_add_u64 v[8:9], s[52:53], 0, v[4:5]
	s_mov_b64 s[68:69], 0x100
	s_add_i32 s62, s62, s25
	v_lshl_add_u64 v[10:11], v[8:9], 0, s[68:69]
	s_mov_b32 m0, s62
	s_add_i32 s58, s62, 0x2000
	ds_read_b128 v[74:77], v17 offset:16384
	ds_read_b128 v[122:125], v17 offset:17408
	ds_read_b128 v[126:129], v17 offset:18432
	ds_read_b128 v[130:133], v17 offset:19456
	ds_read_b128 v[134:137], v17 offset:20480
	ds_read_b128 v[138:141], v17 offset:21504
	ds_read_b128 v[142:145], v17 offset:22528
	ds_read_b128 v[146:149], v17 offset:23552
	global_load_lds_dwordx4 v[10:11], off
	v_lshl_add_u64 v[10:11], s[52:53], 0, v[0:1]
	s_add_u32 s66, s52, 0x18100
	v_lshl_add_u64 v[12:13], v[10:11], 0, s[68:69]
	s_mov_b32 m0, s58
	s_addc_u32 s67, s53, 0
	s_add_i32 s59, s61, s25
	global_load_lds_dwordx4 v[12:13], off
	v_lshl_add_u64 v[12:13], s[66:67], 0, v[4:5]
	s_mov_b32 m0, s59
	s_add_i32 s61, s59, 0x2000
	global_load_lds_dwordx4 v[12:13], off
	v_lshl_add_u64 v[12:13], s[66:67], 0, v[0:1]
	s_mov_b32 m0, s61
	s_nop 0
	global_load_lds_dwordx4 v[12:13], off
	v_lshl_add_u64 v[12:13], s[50:51], 0, v[6:7]
	v_lshl_add_u64 v[14:15], v[12:13], 0, s[68:69]
	s_mov_b32 m0, s26
	s_nop 0
	global_load_lds_dwordx4 v[14:15], off
	v_lshl_add_u64 v[14:15], s[50:51], 0, v[2:3]
	v_lshl_add_u64 v[150:151], v[14:15], 0, s[68:69]
	s_mov_b32 m0, s27
	s_nop 0
	global_load_lds_dwordx4 v[150:151], off
	s_waitcnt vmcnt(8)
	s_waitcnt lgkmcnt(0)
	s_barrier
	s_waitcnt lgkmcnt(0)
	v_mfma_f32_16x16x32_bf16 v[150:153], v[22:25], v[74:77], 0
	v_mfma_f32_16x16x32_bf16 v[178:181], v[22:25], v[126:129], 0
	v_mfma_f32_16x16x32_bf16 v[186:189], v[22:25], v[134:137], 0
	v_mfma_f32_16x16x32_bf16 v[22:25], v[22:25], v[142:145], 0
	v_mfma_f32_16x16x32_bf16 v[150:153], v[26:29], v[122:125], v[150:153]
	v_mfma_f32_16x16x32_bf16 v[154:157], v[30:33], v[74:77], 0
	v_mfma_f32_16x16x32_bf16 v[178:181], v[26:29], v[130:133], v[178:181]
	v_mfma_f32_16x16x32_bf16 v[182:185], v[30:33], v[126:129], 0
	v_mfma_f32_16x16x32_bf16 v[186:189], v[26:29], v[138:141], v[186:189]
	v_mfma_f32_16x16x32_bf16 v[190:193], v[30:33], v[134:137], 0
	v_mfma_f32_16x16x32_bf16 v[24:27], v[26:29], v[146:149], v[22:25]
	v_mfma_f32_16x16x32_bf16 v[28:31], v[30:33], v[142:145], 0
	v_mfma_f32_16x16x32_bf16 v[154:157], v[34:37], v[122:125], v[154:157]
	v_mfma_f32_16x16x32_bf16 v[182:185], v[34:37], v[130:133], v[182:185]
	v_mfma_f32_16x16x32_bf16 v[190:193], v[34:37], v[138:141], v[190:193]
	v_mfma_f32_16x16x32_bf16 v[28:31], v[34:37], v[146:149], v[28:31]
	v_mfma_f32_16x16x32_bf16 v[32:35], v[38:41], v[74:77], 0
	v_mfma_f32_16x16x32_bf16 v[74:77], v[46:49], v[74:77], 0
	v_mfma_f32_16x16x32_bf16 v[32:35], v[42:45], v[122:125], v[32:35]
	v_mfma_f32_16x16x32_bf16 v[74:77], v[50:53], v[122:125], v[74:77]
	v_mfma_f32_16x16x32_bf16 v[122:125], v[38:41], v[126:129], 0
	v_mfma_f32_16x16x32_bf16 v[126:129], v[46:49], v[126:129], 0
	v_mfma_f32_16x16x32_bf16 v[122:125], v[42:45], v[130:133], v[122:125]
	v_mfma_f32_16x16x32_bf16 v[126:129], v[50:53], v[130:133], v[126:129]
	v_mfma_f32_16x16x32_bf16 v[130:133], v[38:41], v[134:137], 0
	v_mfma_f32_16x16x32_bf16 v[36:39], v[38:41], v[142:145], 0
	v_mfma_f32_16x16x32_bf16 v[130:133], v[42:45], v[138:141], v[130:133]
	v_mfma_f32_16x16x32_bf16 v[134:137], v[46:49], v[134:137], 0
	v_mfma_f32_16x16x32_bf16 v[36:39], v[42:45], v[146:149], v[36:39]
	v_mfma_f32_16x16x32_bf16 v[40:43], v[46:49], v[142:145], 0
	v_mfma_f32_16x16x32_bf16 v[134:137], v[50:53], v[138:141], v[134:137]
	v_mfma_f32_16x16x32_bf16 v[40:43], v[50:53], v[146:149], v[40:43]
	s_barrier
	s_add_i32 s63, 0, 0x18000
	s_add_i32 s64, 0, 0x1c000
	v_add_u32_e32 v21, s63, v16
	v_add_u32_e32 v22, s64, v16
	ds_read_b128 v[44:47], v21
	ds_read_b128 v[48:51], v21 offset:1024
	ds_read_b128 v[138:141], v21 offset:2048
	ds_read_b128 v[142:145], v21 offset:3072
	ds_read_b128 v[146:149], v22
	ds_read_b128 v[194:197], v22 offset:1024
	ds_read_b128 v[198:201], v22 offset:2048
	ds_read_b128 v[202:205], v22 offset:3072
	s_add_u32 s66, s50, 0x18100
	s_addc_u32 s67, s51, 0
	s_mov_b32 m0, s28
	v_lshl_add_u64 v[52:53], s[66:67], 0, v[6:7]
	ds_read_b128 v[220:223], v17 offset:32768
	ds_read_b128 v[228:231], v17 offset:33792
	ds_read_b128 v[232:235], v17 offset:34816
	ds_read_b128 v[236:239], v17 offset:35840
	ds_read_b128 v[240:243], v17 offset:36864
	ds_read_b128 v[244:247], v17 offset:37888
	ds_read_b128 v[248:251], v17 offset:38912
	ds_read_b128 v[174:177], v17 offset:39936
	global_load_lds_dwordx4 v[52:53], off
	v_lshl_add_u64 v[52:53], s[66:67], 0, v[2:3]
	s_mov_b32 m0, s29
	s_nop 0
	global_load_lds_dwordx4 v[52:53], off
	s_waitcnt vmcnt(8)
	s_waitcnt lgkmcnt(0)
	s_barrier
	s_waitcnt lgkmcnt(0)
	v_mfma_f32_16x16x32_bf16 v[78:81], v[44:47], v[220:223], v[78:81]
	v_mfma_f32_16x16x32_bf16 v[82:85], v[138:141], v[220:223], v[82:85]
	v_mfma_f32_16x16x32_bf16 v[86:89], v[44:47], v[232:235], v[86:89]
	v_mfma_f32_16x16x32_bf16 v[90:93], v[138:141], v[232:235], v[90:93]
	v_mfma_f32_16x16x32_bf16 v[94:97], v[44:47], v[240:243], v[94:97]
	v_mfma_f32_16x16x32_bf16 v[98:101], v[138:141], v[240:243], v[98:101]
	v_mfma_f32_16x16x32_bf16 v[102:105], v[44:47], v[248:251], v[102:105]
	v_mfma_f32_16x16x32_bf16 v[106:109], v[138:141], v[248:251], v[106:109]
	v_mfma_f32_16x16x32_bf16 v[78:81], v[48:51], v[228:231], v[78:81]
	v_mfma_f32_16x16x32_bf16 v[82:85], v[142:145], v[228:231], v[82:85]
	v_mfma_f32_16x16x32_bf16 v[86:89], v[48:51], v[236:239], v[86:89]
	v_mfma_f32_16x16x32_bf16 v[90:93], v[142:145], v[236:239], v[90:93]
	v_mfma_f32_16x16x32_bf16 v[94:97], v[48:51], v[244:247], v[94:97]
	v_mfma_f32_16x16x32_bf16 v[98:101], v[142:145], v[244:247], v[98:101]
	v_mfma_f32_16x16x32_bf16 v[102:105], v[48:51], v[174:177], v[102:105]
	v_mfma_f32_16x16x32_bf16 v[106:109], v[142:145], v[174:177], v[106:109]
	v_mfma_f32_16x16x32_bf16 v[110:113], v[146:149], v[220:223], v[110:113]
	v_mfma_f32_16x16x32_bf16 v[114:117], v[198:201], v[220:223], v[114:117]
	v_mfma_f32_16x16x32_bf16 v[118:121], v[146:149], v[232:235], v[118:121]
	v_mfma_f32_16x16x32_bf16 v[52:55], v[198:201], v[232:235], v[54:57]
	v_mfma_f32_16x16x32_bf16 v[56:59], v[146:149], v[240:243], v[58:61]
	v_mfma_f32_16x16x32_bf16 v[60:63], v[198:201], v[240:243], v[62:65]
	v_mfma_f32_16x16x32_bf16 v[64:67], v[146:149], v[248:251], v[66:69]
	v_mfma_f32_16x16x32_bf16 v[68:71], v[198:201], v[248:251], v[70:73]
	v_mfma_f32_16x16x32_bf16 v[110:113], v[194:197], v[228:231], v[110:113]
	v_mfma_f32_16x16x32_bf16 v[114:117], v[202:205], v[228:231], v[114:117]
	v_mfma_f32_16x16x32_bf16 v[118:121], v[194:197], v[236:239], v[118:121]
	v_mfma_f32_16x16x32_bf16 v[52:55], v[202:205], v[236:239], v[52:55]
	v_mfma_f32_16x16x32_bf16 v[56:59], v[194:197], v[244:247], v[56:59]
	v_mfma_f32_16x16x32_bf16 v[60:63], v[202:205], v[244:247], v[60:63]
	v_mfma_f32_16x16x32_bf16 v[64:67], v[194:197], v[174:177], v[64:67]
	v_mfma_f32_16x16x32_bf16 v[68:71], v[202:205], v[174:177], v[68:71]
	s_barrier
	s_add_i32 s67, s63, s25
	s_mov_b64 s[70:71], 0x180
	s_add_i32 s63, s67, 0x2000
	v_lshl_add_u64 v[72:73], v[8:9], 0, s[70:71]
	s_mov_b32 m0, s67
	s_add_u32 s68, s52, 0x18180
	ds_read_b128 v[174:177], v17 offset:49152
	ds_read_b128 v[220:223], v17 offset:50176
	ds_read_b128 v[228:231], v17 offset:51200
	ds_read_b128 v[232:235], v17 offset:52224
	ds_read_b128 v[236:239], v17 offset:53248
	ds_read_b128 v[240:243], v17 offset:54272
	ds_read_b128 v[244:247], v17 offset:55296
	ds_read_b128 v[248:251], v17 offset:56320
	global_load_lds_dwordx4 v[72:73], off
	v_lshl_add_u64 v[72:73], v[10:11], 0, s[70:71]
	s_mov_b32 m0, s63
	s_addc_u32 s69, s53, 0
	s_add_i32 s64, s64, s25
	global_load_lds_dwordx4 v[72:73], off
	v_lshl_add_u64 v[72:73], s[68:69], 0, v[4:5]
	s_mov_b32 m0, s64
	s_add_i32 s66, s64, 0x2000
	global_load_lds_dwordx4 v[72:73], off
	v_lshl_add_u64 v[72:73], s[68:69], 0, v[0:1]
	s_mov_b32 m0, s66
	s_nop 0
	global_load_lds_dwordx4 v[72:73], off
	v_lshl_add_u64 v[72:73], v[12:13], 0, s[70:71]
	s_mov_b32 m0, s30
	s_nop 0
	global_load_lds_dwordx4 v[72:73], off
	v_lshl_add_u64 v[72:73], v[14:15], 0, s[70:71]
	s_mov_b32 m0, s31
	s_nop 0
	global_load_lds_dwordx4 v[72:73], off
	s_waitcnt vmcnt(8)
	s_waitcnt lgkmcnt(0)
	s_barrier
	s_waitcnt lgkmcnt(0)
	v_mfma_f32_16x16x32_bf16 v[150:153], v[44:47], v[174:177], v[150:153]
	v_mfma_f32_16x16x32_bf16 v[154:157], v[138:141], v[174:177], v[154:157]
	v_mfma_f32_16x16x32_bf16 v[178:181], v[44:47], v[228:231], v[178:181]
	v_mfma_f32_16x16x32_bf16 v[182:185], v[138:141], v[228:231], v[182:185]
	v_mfma_f32_16x16x32_bf16 v[186:189], v[44:47], v[236:239], v[186:189]
	v_mfma_f32_16x16x32_bf16 v[190:193], v[138:141], v[236:239], v[190:193]
	v_mfma_f32_16x16x32_bf16 v[24:27], v[44:47], v[244:247], v[24:27]
	v_mfma_f32_16x16x32_bf16 v[28:31], v[138:141], v[244:247], v[28:31]
	v_mfma_f32_16x16x32_bf16 v[150:153], v[48:51], v[220:223], v[150:153]
	v_mfma_f32_16x16x32_bf16 v[154:157], v[142:145], v[220:223], v[154:157]
	v_mfma_f32_16x16x32_bf16 v[178:181], v[48:51], v[232:235], v[178:181]
	v_mfma_f32_16x16x32_bf16 v[182:185], v[142:145], v[232:235], v[182:185]
	v_mfma_f32_16x16x32_bf16 v[186:189], v[48:51], v[240:243], v[186:189]
	v_mfma_f32_16x16x32_bf16 v[190:193], v[142:145], v[240:243], v[190:193]
	v_mfma_f32_16x16x32_bf16 v[24:27], v[48:51], v[248:251], v[24:27]
	v_mfma_f32_16x16x32_bf16 v[28:31], v[142:145], v[248:251], v[28:31]
	v_mfma_f32_16x16x32_bf16 v[32:35], v[146:149], v[174:177], v[32:35]
	v_mfma_f32_16x16x32_bf16 v[44:47], v[198:201], v[174:177], v[74:77]
	v_mfma_f32_16x16x32_bf16 v[48:51], v[146:149], v[228:231], v[122:125]
	v_mfma_f32_16x16x32_bf16 v[72:75], v[198:201], v[228:231], v[126:129]
	v_mfma_f32_16x16x32_bf16 v[122:125], v[146:149], v[236:239], v[130:133]
	v_mfma_f32_16x16x32_bf16 v[126:129], v[198:201], v[236:239], v[134:137]
	v_mfma_f32_16x16x32_bf16 v[36:39], v[146:149], v[244:247], v[36:39]
	v_mfma_f32_16x16x32_bf16 v[40:43], v[198:201], v[244:247], v[40:43]
	v_mfma_f32_16x16x32_bf16 v[32:35], v[194:197], v[220:223], v[32:35]
	v_mfma_f32_16x16x32_bf16 v[44:47], v[202:205], v[220:223], v[44:47]
	v_mfma_f32_16x16x32_bf16 v[48:51], v[194:197], v[232:235], v[48:51]
	v_mfma_f32_16x16x32_bf16 v[72:75], v[202:205], v[232:235], v[72:75]
	v_mfma_f32_16x16x32_bf16 v[122:125], v[194:197], v[240:243], v[122:125]
	v_mfma_f32_16x16x32_bf16 v[126:129], v[202:205], v[240:243], v[126:129]
	v_mfma_f32_16x16x32_bf16 v[36:39], v[194:197], v[248:251], v[36:39]
	v_mfma_f32_16x16x32_bf16 v[40:43], v[202:205], v[248:251], v[40:43]
	s_barrier
	ds_read_b128 v[130:133], v19
	ds_read_b128 v[134:137], v19 offset:1024
	ds_read_b128 v[138:141], v19 offset:2048
	ds_read_b128 v[142:145], v19 offset:3072
	ds_read_b128 v[146:149], v20
	ds_read_b128 v[174:177], v20 offset:1024
	ds_read_b128 v[194:197], v20 offset:2048
	ds_read_b128 v[198:201], v20 offset:3072
	s_add_u32 s68, s50, 0x18180
	s_addc_u32 s69, s51, 0
	s_mov_b32 m0, s65
	v_lshl_add_u64 v[76:77], s[68:69], 0, v[6:7]
	ds_read_b128 v[202:205], v17
	ds_read_b128 v[220:223], v17 offset:1024
	ds_read_b128 v[228:231], v17 offset:2048
	ds_read_b128 v[232:235], v17 offset:3072
	ds_read_b128 v[236:239], v17 offset:4096
	ds_read_b128 v[240:243], v17 offset:5120
	ds_read_b128 v[244:247], v17 offset:6144
	ds_read_b128 v[248:251], v17 offset:7168
	global_load_lds_dwordx4 v[76:77], off
	v_lshl_add_u64 v[76:77], s[68:69], 0, v[2:3]
	s_mov_b32 m0, s57
	s_nop 0
	global_load_lds_dwordx4 v[76:77], off
	s_waitcnt vmcnt(8)
	s_waitcnt lgkmcnt(0)
	s_barrier
	s_waitcnt lgkmcnt(0)
	v_mfma_f32_16x16x32_bf16 v[76:79], v[130:133], v[202:205], v[78:81]
	v_mfma_f32_16x16x32_bf16 v[80:83], v[138:141], v[202:205], v[82:85]
	v_mfma_f32_16x16x32_bf16 v[84:87], v[130:133], v[228:231], v[86:89]
	v_mfma_f32_16x16x32_bf16 v[88:91], v[138:141], v[228:231], v[90:93]
	v_mfma_f32_16x16x32_bf16 v[92:95], v[130:133], v[236:239], v[94:97]
	v_mfma_f32_16x16x32_bf16 v[96:99], v[138:141], v[236:239], v[98:101]
	v_mfma_f32_16x16x32_bf16 v[100:103], v[130:133], v[244:247], v[102:105]
	v_mfma_f32_16x16x32_bf16 v[104:107], v[138:141], v[244:247], v[106:109]
	v_mfma_f32_16x16x32_bf16 v[76:79], v[134:137], v[220:223], v[76:79]
	v_mfma_f32_16x16x32_bf16 v[80:83], v[142:145], v[220:223], v[80:83]
	v_mfma_f32_16x16x32_bf16 v[84:87], v[134:137], v[232:235], v[84:87]
	v_mfma_f32_16x16x32_bf16 v[88:91], v[142:145], v[232:235], v[88:91]
	v_mfma_f32_16x16x32_bf16 v[92:95], v[134:137], v[240:243], v[92:95]
	v_mfma_f32_16x16x32_bf16 v[96:99], v[142:145], v[240:243], v[96:99]
	v_mfma_f32_16x16x32_bf16 v[100:103], v[134:137], v[248:251], v[100:103]
	v_mfma_f32_16x16x32_bf16 v[104:107], v[142:145], v[248:251], v[104:107]
	v_mfma_f32_16x16x32_bf16 v[108:111], v[146:149], v[202:205], v[110:113]
	v_mfma_f32_16x16x32_bf16 v[112:115], v[194:197], v[202:205], v[114:117]
	v_mfma_f32_16x16x32_bf16 v[116:119], v[146:149], v[228:231], v[118:121]
	v_mfma_f32_16x16x32_bf16 v[52:55], v[194:197], v[228:231], v[52:55]
	v_mfma_f32_16x16x32_bf16 v[56:59], v[146:149], v[236:239], v[56:59]
	v_mfma_f32_16x16x32_bf16 v[60:63], v[194:197], v[236:239], v[60:63]
	v_mfma_f32_16x16x32_bf16 v[64:67], v[146:149], v[244:247], v[64:67]
	v_mfma_f32_16x16x32_bf16 v[68:71], v[194:197], v[244:247], v[68:71]
	v_mfma_f32_16x16x32_bf16 v[108:111], v[174:177], v[220:223], v[108:111]
	v_mfma_f32_16x16x32_bf16 v[112:115], v[198:201], v[220:223], v[112:115]
	v_mfma_f32_16x16x32_bf16 v[116:119], v[174:177], v[232:235], v[116:119]
	v_mfma_f32_16x16x32_bf16 v[52:55], v[198:201], v[232:235], v[52:55]
	v_mfma_f32_16x16x32_bf16 v[56:59], v[174:177], v[240:243], v[56:59]
	v_mfma_f32_16x16x32_bf16 v[60:63], v[198:201], v[240:243], v[60:63]
	v_mfma_f32_16x16x32_bf16 v[64:67], v[174:177], v[248:251], v[64:67]
	v_mfma_f32_16x16x32_bf16 v[68:71], v[198:201], v[248:251], v[68:71]
	s_barrier
	s_mov_b64 s[70:71], 0x200
	s_mov_b32 m0, s62
	v_lshl_add_u64 v[120:121], v[8:9], 0, s[70:71]
	s_add_u32 s68, s52, 0x18200
	ds_read_b128 v[202:205], v17 offset:16384
	ds_read_b128 v[220:223], v17 offset:17408
	ds_read_b128 v[228:231], v17 offset:18432
	ds_read_b128 v[232:235], v17 offset:19456
	ds_read_b128 v[236:239], v17 offset:20480
	ds_read_b128 v[240:243], v17 offset:21504
	ds_read_b128 v[244:247], v17 offset:22528
	ds_read_b128 v[248:251], v17 offset:23552
	global_load_lds_dwordx4 v[120:121], off
	v_lshl_add_u64 v[120:121], v[10:11], 0, s[70:71]
	s_mov_b32 m0, s58
	s_addc_u32 s69, s53, 0
	global_load_lds_dwordx4 v[120:121], off
	v_lshl_add_u64 v[120:121], s[68:69], 0, v[4:5]
	s_mov_b32 m0, s59
	s_nop 0
	global_load_lds_dwordx4 v[120:121], off
	v_lshl_add_u64 v[120:121], s[68:69], 0, v[0:1]
	s_mov_b32 m0, s61
	s_nop 0
	global_load_lds_dwordx4 v[120:121], off
	v_lshl_add_u64 v[120:121], v[12:13], 0, s[70:71]
	s_mov_b32 m0, s26
	s_nop 0
	global_load_lds_dwordx4 v[120:121], off
	v_lshl_add_u64 v[120:121], v[14:15], 0, s[70:71]
	s_mov_b32 m0, s27
	s_nop 0
	global_load_lds_dwordx4 v[120:121], off
	s_waitcnt vmcnt(8)
	s_waitcnt lgkmcnt(0)
	s_barrier
	s_waitcnt lgkmcnt(0)
	v_mfma_f32_16x16x32_bf16 v[150:153], v[130:133], v[202:205], v[150:153]
	v_mfma_f32_16x16x32_bf16 v[154:157], v[138:141], v[202:205], v[154:157]
	v_mfma_f32_16x16x32_bf16 v[178:181], v[130:133], v[228:231], v[178:181]
	v_mfma_f32_16x16x32_bf16 v[182:185], v[138:141], v[228:231], v[182:185]
	v_mfma_f32_16x16x32_bf16 v[186:189], v[130:133], v[236:239], v[186:189]
	v_mfma_f32_16x16x32_bf16 v[190:193], v[138:141], v[236:239], v[190:193]
	v_mfma_f32_16x16x32_bf16 v[24:27], v[130:133], v[244:247], v[24:27]
	v_mfma_f32_16x16x32_bf16 v[28:31], v[138:141], v[244:247], v[28:31]
	v_mfma_f32_16x16x32_bf16 v[150:153], v[134:137], v[220:223], v[150:153]
	v_mfma_f32_16x16x32_bf16 v[154:157], v[142:145], v[220:223], v[154:157]
	v_mfma_f32_16x16x32_bf16 v[178:181], v[134:137], v[232:235], v[178:181]
	v_mfma_f32_16x16x32_bf16 v[182:185], v[142:145], v[232:235], v[182:185]
	v_mfma_f32_16x16x32_bf16 v[186:189], v[134:137], v[240:243], v[186:189]
	v_mfma_f32_16x16x32_bf16 v[190:193], v[142:145], v[240:243], v[190:193]
	v_mfma_f32_16x16x32_bf16 v[24:27], v[134:137], v[248:251], v[24:27]
	v_mfma_f32_16x16x32_bf16 v[28:31], v[142:145], v[248:251], v[28:31]
	v_mfma_f32_16x16x32_bf16 v[32:35], v[146:149], v[202:205], v[32:35]
	v_mfma_f32_16x16x32_bf16 v[44:47], v[194:197], v[202:205], v[44:47]
	v_mfma_f32_16x16x32_bf16 v[48:51], v[146:149], v[228:231], v[48:51]
	v_mfma_f32_16x16x32_bf16 v[72:75], v[194:197], v[228:231], v[72:75]
	v_mfma_f32_16x16x32_bf16 v[120:123], v[146:149], v[236:239], v[122:125]
	v_mfma_f32_16x16x32_bf16 v[124:127], v[194:197], v[236:239], v[126:129]
	v_mfma_f32_16x16x32_bf16 v[36:39], v[146:149], v[244:247], v[36:39]
	v_mfma_f32_16x16x32_bf16 v[40:43], v[194:197], v[244:247], v[40:43]
	v_mfma_f32_16x16x32_bf16 v[32:35], v[174:177], v[220:223], v[32:35]
	v_mfma_f32_16x16x32_bf16 v[44:47], v[198:201], v[220:223], v[44:47]
	v_mfma_f32_16x16x32_bf16 v[48:51], v[174:177], v[232:235], v[48:51]
	v_mfma_f32_16x16x32_bf16 v[72:75], v[198:201], v[232:235], v[72:75]
	v_mfma_f32_16x16x32_bf16 v[120:123], v[174:177], v[240:243], v[120:123]
	v_mfma_f32_16x16x32_bf16 v[124:127], v[198:201], v[240:243], v[124:127]
	v_mfma_f32_16x16x32_bf16 v[36:39], v[174:177], v[248:251], v[36:39]
	v_mfma_f32_16x16x32_bf16 v[40:43], v[198:201], v[248:251], v[40:43]
	s_barrier
	ds_read_b128 v[128:131], v21
	ds_read_b128 v[132:135], v21 offset:1024
	ds_read_b128 v[136:139], v21 offset:2048
	ds_read_b128 v[140:143], v21 offset:3072
	ds_read_b128 v[144:147], v22
	ds_read_b128 v[174:177], v22 offset:1024
	ds_read_b128 v[194:197], v22 offset:2048
	ds_read_b128 v[198:201], v22 offset:3072
	s_add_u32 s68, s50, 0x18200
	s_addc_u32 s69, s51, 0
	s_mov_b32 m0, s28
	v_lshl_add_u64 v[148:149], s[68:69], 0, v[6:7]
	ds_read_b128 v[202:205], v17 offset:32768
	ds_read_b128 v[220:223], v17 offset:33792
	ds_read_b128 v[228:231], v17 offset:34816
	ds_read_b128 v[232:235], v17 offset:35840
	ds_read_b128 v[236:239], v17 offset:36864
	ds_read_b128 v[240:243], v17 offset:37888
	ds_read_b128 v[244:247], v17 offset:38912
	ds_read_b128 v[248:251], v17 offset:39936
	global_load_lds_dwordx4 v[148:149], off
	v_lshl_add_u64 v[148:149], s[68:69], 0, v[2:3]
	s_mov_b32 m0, s29
	s_nop 0
	global_load_lds_dwordx4 v[148:149], off
	s_waitcnt vmcnt(8)
	s_waitcnt lgkmcnt(0)
	s_barrier
	s_waitcnt lgkmcnt(0)
	v_mfma_f32_16x16x32_bf16 v[76:79], v[128:131], v[202:205], v[76:79]
	v_mfma_f32_16x16x32_bf16 v[80:83], v[136:139], v[202:205], v[80:83]
	v_mfma_f32_16x16x32_bf16 v[84:87], v[128:131], v[228:231], v[84:87]
	v_mfma_f32_16x16x32_bf16 v[88:91], v[136:139], v[228:231], v[88:91]
	v_mfma_f32_16x16x32_bf16 v[92:95], v[128:131], v[236:239], v[92:95]
	v_mfma_f32_16x16x32_bf16 v[96:99], v[136:139], v[236:239], v[96:99]
	v_mfma_f32_16x16x32_bf16 v[100:103], v[128:131], v[244:247], v[100:103]
	v_mfma_f32_16x16x32_bf16 v[104:107], v[136:139], v[244:247], v[104:107]
	v_mfma_f32_16x16x32_bf16 v[76:79], v[132:135], v[220:223], v[76:79]
	v_mfma_f32_16x16x32_bf16 v[80:83], v[140:143], v[220:223], v[80:83]
	v_mfma_f32_16x16x32_bf16 v[84:87], v[132:135], v[232:235], v[84:87]
	v_mfma_f32_16x16x32_bf16 v[88:91], v[140:143], v[232:235], v[88:91]
	v_mfma_f32_16x16x32_bf16 v[92:95], v[132:135], v[240:243], v[92:95]
	v_mfma_f32_16x16x32_bf16 v[96:99], v[140:143], v[240:243], v[96:99]
	v_mfma_f32_16x16x32_bf16 v[100:103], v[132:135], v[248:251], v[100:103]
	v_mfma_f32_16x16x32_bf16 v[104:107], v[140:143], v[248:251], v[104:107]
	v_mfma_f32_16x16x32_bf16 v[108:111], v[144:147], v[202:205], v[108:111]
	v_mfma_f32_16x16x32_bf16 v[112:115], v[194:197], v[202:205], v[112:115]
	v_mfma_f32_16x16x32_bf16 v[116:119], v[144:147], v[228:231], v[116:119]
	v_mfma_f32_16x16x32_bf16 v[52:55], v[194:197], v[228:231], v[52:55]
	v_mfma_f32_16x16x32_bf16 v[56:59], v[144:147], v[236:239], v[56:59]
	v_mfma_f32_16x16x32_bf16 v[60:63], v[194:197], v[236:239], v[60:63]
	v_mfma_f32_16x16x32_bf16 v[64:67], v[144:147], v[244:247], v[64:67]
	v_mfma_f32_16x16x32_bf16 v[68:71], v[194:197], v[244:247], v[68:71]
	v_mfma_f32_16x16x32_bf16 v[108:111], v[174:177], v[220:223], v[108:111]
	v_mfma_f32_16x16x32_bf16 v[112:115], v[198:201], v[220:223], v[112:115]
	v_mfma_f32_16x16x32_bf16 v[116:119], v[174:177], v[232:235], v[116:119]
	v_mfma_f32_16x16x32_bf16 v[52:55], v[198:201], v[232:235], v[52:55]
	v_mfma_f32_16x16x32_bf16 v[56:59], v[174:177], v[240:243], v[56:59]
	v_mfma_f32_16x16x32_bf16 v[60:63], v[198:201], v[240:243], v[60:63]
	v_mfma_f32_16x16x32_bf16 v[64:67], v[174:177], v[248:251], v[64:67]
	v_mfma_f32_16x16x32_bf16 v[68:71], v[198:201], v[248:251], v[68:71]
	s_barrier
	s_mov_b64 s[68:69], 0x280
	s_mov_b32 m0, s67
	v_lshl_add_u64 v[8:9], v[8:9], 0, s[68:69]
	s_add_u32 s52, s52, 0x18280
	ds_read_b128 v[202:205], v17 offset:49152
	ds_read_b128 v[220:223], v17 offset:50176
	ds_read_b128 v[228:231], v17 offset:51200
	ds_read_b128 v[232:235], v17 offset:52224
	ds_read_b128 v[236:239], v17 offset:53248
	ds_read_b128 v[240:243], v17 offset:54272
	ds_read_b128 v[244:247], v17 offset:55296
	ds_read_b128 v[248:251], v17 offset:56320
	global_load_lds_dwordx4 v[8:9], off
	v_lshl_add_u64 v[8:9], v[10:11], 0, s[68:69]
	s_mov_b32 m0, s63
	s_addc_u32 s53, s53, 0
	global_load_lds_dwordx4 v[8:9], off
	v_lshl_add_u64 v[8:9], s[52:53], 0, v[4:5]
	s_mov_b32 m0, s64
	s_nop 0
	global_load_lds_dwordx4 v[8:9], off
	v_lshl_add_u64 v[8:9], s[52:53], 0, v[0:1]
	s_mov_b32 m0, s66
	s_nop 0
	global_load_lds_dwordx4 v[8:9], off
	v_lshl_add_u64 v[8:9], v[12:13], 0, s[68:69]
	s_mov_b32 m0, s30
	s_nop 0
	global_load_lds_dwordx4 v[8:9], off
	v_lshl_add_u64 v[8:9], v[14:15], 0, s[68:69]
	s_mov_b32 m0, s31
	s_nop 0
	global_load_lds_dwordx4 v[8:9], off
	s_waitcnt vmcnt(8)
	s_waitcnt lgkmcnt(0)
	s_barrier
	s_waitcnt lgkmcnt(0)
	v_mfma_f32_16x16x32_bf16 v[8:11], v[128:131], v[202:205], v[150:153]
	v_mfma_f32_16x16x32_bf16 v[12:15], v[136:139], v[202:205], v[154:157]
	v_mfma_f32_16x16x32_bf16 v[148:151], v[128:131], v[228:231], v[178:181]
	v_mfma_f32_16x16x32_bf16 v[152:155], v[136:139], v[228:231], v[182:185]
	v_mfma_f32_16x16x32_bf16 v[156:159], v[128:131], v[236:239], v[186:189]
	v_mfma_f32_16x16x32_bf16 v[178:181], v[136:139], v[236:239], v[190:193]
	v_mfma_f32_16x16x32_bf16 v[24:27], v[128:131], v[244:247], v[24:27]
	v_mfma_f32_16x16x32_bf16 v[28:31], v[136:139], v[244:247], v[28:31]
	v_mfma_f32_16x16x32_bf16 v[8:11], v[132:135], v[220:223], v[8:11]
	v_mfma_f32_16x16x32_bf16 v[12:15], v[140:143], v[220:223], v[12:15]
	v_mfma_f32_16x16x32_bf16 v[148:151], v[132:135], v[232:235], v[148:151]
	v_mfma_f32_16x16x32_bf16 v[152:155], v[140:143], v[232:235], v[152:155]
	v_mfma_f32_16x16x32_bf16 v[156:159], v[132:135], v[240:243], v[156:159]
	v_mfma_f32_16x16x32_bf16 v[178:181], v[140:143], v[240:243], v[178:181]
	v_mfma_f32_16x16x32_bf16 v[24:27], v[132:135], v[248:251], v[24:27]
	v_mfma_f32_16x16x32_bf16 v[28:31], v[140:143], v[248:251], v[28:31]
	v_mfma_f32_16x16x32_bf16 v[32:35], v[144:147], v[202:205], v[32:35]
	v_mfma_f32_16x16x32_bf16 v[44:47], v[194:197], v[202:205], v[44:47]
	v_mfma_f32_16x16x32_bf16 v[48:51], v[144:147], v[228:231], v[48:51]
	v_mfma_f32_16x16x32_bf16 v[72:75], v[194:197], v[228:231], v[72:75]
	v_mfma_f32_16x16x32_bf16 v[120:123], v[144:147], v[236:239], v[120:123]
	v_mfma_f32_16x16x32_bf16 v[124:127], v[194:197], v[236:239], v[124:127]
	v_mfma_f32_16x16x32_bf16 v[36:39], v[144:147], v[244:247], v[36:39]
	v_mfma_f32_16x16x32_bf16 v[40:43], v[194:197], v[244:247], v[40:43]
	v_mfma_f32_16x16x32_bf16 v[32:35], v[174:177], v[220:223], v[32:35]
	v_mfma_f32_16x16x32_bf16 v[44:47], v[198:201], v[220:223], v[44:47]
	v_mfma_f32_16x16x32_bf16 v[48:51], v[174:177], v[232:235], v[48:51]
	v_mfma_f32_16x16x32_bf16 v[72:75], v[198:201], v[232:235], v[72:75]
	v_mfma_f32_16x16x32_bf16 v[120:123], v[174:177], v[240:243], v[120:123]
	v_mfma_f32_16x16x32_bf16 v[124:127], v[198:201], v[240:243], v[124:127]
	v_mfma_f32_16x16x32_bf16 v[36:39], v[174:177], v[248:251], v[36:39]
	v_mfma_f32_16x16x32_bf16 v[40:43], v[198:201], v[248:251], v[40:43]
	s_barrier
	ds_read_b128 v[128:131], v19
	ds_read_b128 v[132:135], v19 offset:1024
	ds_read_b128 v[136:139], v19 offset:2048
	ds_read_b128 v[140:143], v19 offset:3072
	ds_read_b128 v[144:147], v20
	ds_read_b128 v[174:177], v20 offset:1024
	ds_read_b128 v[182:185], v20 offset:2048
	ds_read_b128 v[186:189], v20 offset:3072
	s_add_u32 s50, s50, 0x18280
	s_addc_u32 s51, s51, 0
	s_mov_b32 m0, s65
	v_lshl_add_u64 v[240:241], s[50:51], 0, v[6:7]
	ds_read_b128 v[190:193], v17
	ds_read_b128 v[194:197], v17 offset:1024
	ds_read_b128 v[198:201], v17 offset:2048
	ds_read_b128 v[202:205], v17 offset:3072
	ds_read_b128 v[220:223], v17 offset:4096
	ds_read_b128 v[228:231], v17 offset:5120
	ds_read_b128 v[232:235], v17 offset:6144
	ds_read_b128 v[236:239], v17 offset:7168
	global_load_lds_dwordx4 v[240:241], off
	v_lshl_add_u64 v[240:241], s[50:51], 0, v[2:3]
	s_mov_b32 m0, s57
	s_nop 0
	global_load_lds_dwordx4 v[240:241], off
	s_waitcnt vmcnt(8)
	s_waitcnt lgkmcnt(0)
	s_barrier
	s_waitcnt lgkmcnt(0)
	v_mfma_f32_16x16x32_bf16 v[76:79], v[128:131], v[190:193], v[76:79]
	v_mfma_f32_16x16x32_bf16 v[80:83], v[136:139], v[190:193], v[80:83]
	v_mfma_f32_16x16x32_bf16 v[84:87], v[128:131], v[198:201], v[84:87]
	v_mfma_f32_16x16x32_bf16 v[88:91], v[136:139], v[198:201], v[88:91]
	v_mfma_f32_16x16x32_bf16 v[92:95], v[128:131], v[220:223], v[92:95]
	v_mfma_f32_16x16x32_bf16 v[96:99], v[136:139], v[220:223], v[96:99]
	v_mfma_f32_16x16x32_bf16 v[100:103], v[128:131], v[232:235], v[100:103]
	v_mfma_f32_16x16x32_bf16 v[104:107], v[136:139], v[232:235], v[104:107]
	v_mfma_f32_16x16x32_bf16 v[76:79], v[132:135], v[194:197], v[76:79]
	v_mfma_f32_16x16x32_bf16 v[80:83], v[140:143], v[194:197], v[80:83]
	v_mfma_f32_16x16x32_bf16 v[84:87], v[132:135], v[202:205], v[84:87]
	v_mfma_f32_16x16x32_bf16 v[88:91], v[140:143], v[202:205], v[88:91]
	v_mfma_f32_16x16x32_bf16 v[92:95], v[132:135], v[228:231], v[92:95]
	v_mfma_f32_16x16x32_bf16 v[96:99], v[140:143], v[228:231], v[96:99]
	v_mfma_f32_16x16x32_bf16 v[100:103], v[132:135], v[236:239], v[100:103]
	v_mfma_f32_16x16x32_bf16 v[104:107], v[140:143], v[236:239], v[104:107]
	v_mfma_f32_16x16x32_bf16 v[108:111], v[144:147], v[190:193], v[108:111]
	v_mfma_f32_16x16x32_bf16 v[112:115], v[182:185], v[190:193], v[112:115]
	v_mfma_f32_16x16x32_bf16 v[116:119], v[144:147], v[198:201], v[116:119]
	v_mfma_f32_16x16x32_bf16 v[52:55], v[182:185], v[198:201], v[52:55]
	v_mfma_f32_16x16x32_bf16 v[56:59], v[144:147], v[220:223], v[56:59]
	v_mfma_f32_16x16x32_bf16 v[60:63], v[182:185], v[220:223], v[60:63]
	v_mfma_f32_16x16x32_bf16 v[64:67], v[144:147], v[232:235], v[64:67]
	v_mfma_f32_16x16x32_bf16 v[68:71], v[182:185], v[232:235], v[68:71]
	v_mfma_f32_16x16x32_bf16 v[108:111], v[174:177], v[194:197], v[108:111]
	v_mfma_f32_16x16x32_bf16 v[112:115], v[186:189], v[194:197], v[112:115]
	v_mfma_f32_16x16x32_bf16 v[116:119], v[174:177], v[202:205], v[116:119]
	v_mfma_f32_16x16x32_bf16 v[52:55], v[186:189], v[202:205], v[52:55]
	v_mfma_f32_16x16x32_bf16 v[56:59], v[174:177], v[228:231], v[56:59]
	v_mfma_f32_16x16x32_bf16 v[60:63], v[186:189], v[228:231], v[60:63]
	v_mfma_f32_16x16x32_bf16 v[64:67], v[174:177], v[236:239], v[64:67]
	v_mfma_f32_16x16x32_bf16 v[68:71], v[186:189], v[236:239], v[68:71]
	s_barrier
	s_mov_b32 m0, s62
	v_lshl_add_u64 v[240:241], s[44:45], 0, v[4:5]
	s_add_u32 s50, s44, 0x18000
	ds_read_b128 v[190:193], v17 offset:16384
	ds_read_b128 v[194:197], v17 offset:17408
	ds_read_b128 v[198:201], v17 offset:18432
	ds_read_b128 v[202:205], v17 offset:19456
	ds_read_b128 v[220:223], v17 offset:20480
	ds_read_b128 v[228:231], v17 offset:21504
	ds_read_b128 v[232:235], v17 offset:22528
	ds_read_b128 v[236:239], v17 offset:23552
	global_load_lds_dwordx4 v[240:241], off
	v_lshl_add_u64 v[242:243], s[44:45], 0, v[0:1]
	s_mov_b32 m0, s58
	s_addc_u32 s51, s45, 0
	global_load_lds_dwordx4 v[242:243], off
	v_lshl_add_u64 v[244:245], s[50:51], 0, v[4:5]
	s_mov_b32 m0, s59
	v_lshl_add_u64 v[246:247], s[42:43], 0, v[2:3]
	global_load_lds_dwordx4 v[244:245], off
	v_lshl_add_u64 v[244:245], s[50:51], 0, v[0:1]
	s_mov_b32 m0, s61
	s_nop 0
	global_load_lds_dwordx4 v[244:245], off
	v_lshl_add_u64 v[244:245], s[42:43], 0, v[6:7]
	s_mov_b32 m0, s26
	s_nop 0
	global_load_lds_dwordx4 v[244:245], off
	s_mov_b32 m0, s27
	s_nop 0
	global_load_lds_dwordx4 v[246:247], off
	s_waitcnt vmcnt(8)
	s_waitcnt lgkmcnt(0)
	s_barrier
	s_waitcnt lgkmcnt(0)
	v_mfma_f32_16x16x32_bf16 v[8:11], v[128:131], v[190:193], v[8:11]
	v_mfma_f32_16x16x32_bf16 v[12:15], v[136:139], v[190:193], v[12:15]
	v_mfma_f32_16x16x32_bf16 v[148:151], v[128:131], v[198:201], v[148:151]
	v_mfma_f32_16x16x32_bf16 v[152:155], v[136:139], v[198:201], v[152:155]
	v_mfma_f32_16x16x32_bf16 v[156:159], v[128:131], v[220:223], v[156:159]
	v_mfma_f32_16x16x32_bf16 v[178:181], v[136:139], v[220:223], v[178:181]
	v_mfma_f32_16x16x32_bf16 v[24:27], v[128:131], v[232:235], v[24:27]
	v_mfma_f32_16x16x32_bf16 v[28:31], v[136:139], v[232:235], v[28:31]
	v_mfma_f32_16x16x32_bf16 v[8:11], v[132:135], v[194:197], v[8:11]
	v_mfma_f32_16x16x32_bf16 v[12:15], v[140:143], v[194:197], v[12:15]
	v_mfma_f32_16x16x32_bf16 v[148:151], v[132:135], v[202:205], v[148:151]
	v_mfma_f32_16x16x32_bf16 v[152:155], v[140:143], v[202:205], v[152:155]
	v_mfma_f32_16x16x32_bf16 v[156:159], v[132:135], v[228:231], v[156:159]
	v_mfma_f32_16x16x32_bf16 v[178:181], v[140:143], v[228:231], v[178:181]
	v_mfma_f32_16x16x32_bf16 v[24:27], v[132:135], v[236:239], v[24:27]
	v_mfma_f32_16x16x32_bf16 v[28:31], v[140:143], v[236:239], v[28:31]
	v_mfma_f32_16x16x32_bf16 v[32:35], v[144:147], v[190:193], v[32:35]
	v_mfma_f32_16x16x32_bf16 v[44:47], v[182:185], v[190:193], v[44:47]
	v_mfma_f32_16x16x32_bf16 v[48:51], v[144:147], v[198:201], v[48:51]
	v_mfma_f32_16x16x32_bf16 v[72:75], v[182:185], v[198:201], v[72:75]
	v_mfma_f32_16x16x32_bf16 v[120:123], v[144:147], v[220:223], v[120:123]
	v_mfma_f32_16x16x32_bf16 v[124:127], v[182:185], v[220:223], v[124:127]
	v_mfma_f32_16x16x32_bf16 v[36:39], v[144:147], v[232:235], v[36:39]
	v_mfma_f32_16x16x32_bf16 v[40:43], v[182:185], v[232:235], v[40:43]
	v_mfma_f32_16x16x32_bf16 v[32:35], v[174:177], v[194:197], v[32:35]
	v_mfma_f32_16x16x32_bf16 v[44:47], v[186:189], v[194:197], v[44:47]
	v_mfma_f32_16x16x32_bf16 v[48:51], v[174:177], v[202:205], v[48:51]
	v_mfma_f32_16x16x32_bf16 v[72:75], v[186:189], v[202:205], v[72:75]
	v_mfma_f32_16x16x32_bf16 v[120:123], v[174:177], v[228:231], v[120:123]
	v_mfma_f32_16x16x32_bf16 v[124:127], v[186:189], v[228:231], v[124:127]
	v_mfma_f32_16x16x32_bf16 v[36:39], v[174:177], v[236:239], v[36:39]
	v_mfma_f32_16x16x32_bf16 v[40:43], v[186:189], v[236:239], v[40:43]
	s_barrier
	ds_read_b128 v[128:131], v21
	ds_read_b128 v[132:135], v21 offset:1024
	ds_read_b128 v[136:139], v21 offset:2048
	ds_read_b128 v[140:143], v21 offset:3072
	ds_read_b128 v[144:147], v22
	ds_read_b128 v[174:177], v22 offset:1024
	ds_read_b128 v[182:185], v22 offset:2048
	ds_read_b128 v[20:23], v22 offset:3072
	s_add_u32 s50, s42, 0x18000
	s_addc_u32 s51, s43, 0
	s_mov_b32 m0, s28
	v_lshl_add_u64 v[236:237], s[50:51], 0, v[6:7]
	ds_read_b128 v[186:189], v17 offset:32768
	ds_read_b128 v[190:193], v17 offset:33792
	ds_read_b128 v[194:197], v17 offset:34816
	ds_read_b128 v[198:201], v17 offset:35840
	ds_read_b128 v[202:205], v17 offset:36864
	ds_read_b128 v[220:223], v17 offset:37888
	ds_read_b128 v[228:231], v17 offset:38912
	ds_read_b128 v[232:235], v17 offset:39936
	global_load_lds_dwordx4 v[236:237], off
	v_lshl_add_u64 v[236:237], s[50:51], 0, v[2:3]
	s_mov_b32 m0, s29
	s_nop 0
	global_load_lds_dwordx4 v[236:237], off
	s_waitcnt vmcnt(8)
	s_waitcnt lgkmcnt(0)
	s_barrier
	s_waitcnt lgkmcnt(0)
	v_mfma_f32_16x16x32_bf16 v[76:79], v[128:131], v[186:189], v[76:79]
	v_mfma_f32_16x16x32_bf16 v[80:83], v[136:139], v[186:189], v[80:83]
	v_mfma_f32_16x16x32_bf16 v[84:87], v[128:131], v[194:197], v[84:87]
	v_mfma_f32_16x16x32_bf16 v[88:91], v[136:139], v[194:197], v[88:91]
	v_mfma_f32_16x16x32_bf16 v[92:95], v[128:131], v[202:205], v[92:95]
	v_mfma_f32_16x16x32_bf16 v[96:99], v[136:139], v[202:205], v[96:99]
	v_mfma_f32_16x16x32_bf16 v[100:103], v[128:131], v[228:231], v[100:103]
	v_mfma_f32_16x16x32_bf16 v[104:107], v[136:139], v[228:231], v[104:107]
	v_mfma_f32_16x16x32_bf16 v[76:79], v[132:135], v[190:193], v[76:79]
	v_mfma_f32_16x16x32_bf16 v[80:83], v[140:143], v[190:193], v[80:83]
	v_mfma_f32_16x16x32_bf16 v[84:87], v[132:135], v[198:201], v[84:87]
	v_mfma_f32_16x16x32_bf16 v[88:91], v[140:143], v[198:201], v[88:91]
	v_mfma_f32_16x16x32_bf16 v[92:95], v[132:135], v[220:223], v[92:95]
	v_mfma_f32_16x16x32_bf16 v[96:99], v[140:143], v[220:223], v[96:99]
	v_mfma_f32_16x16x32_bf16 v[100:103], v[132:135], v[232:235], v[100:103]
	v_mfma_f32_16x16x32_bf16 v[104:107], v[140:143], v[232:235], v[104:107]
	v_mfma_f32_16x16x32_bf16 v[108:111], v[144:147], v[186:189], v[108:111]
	v_mfma_f32_16x16x32_bf16 v[112:115], v[182:185], v[186:189], v[112:115]
	v_mfma_f32_16x16x32_bf16 v[116:119], v[144:147], v[194:197], v[116:119]
	v_mfma_f32_16x16x32_bf16 v[52:55], v[182:185], v[194:197], v[52:55]
	v_mfma_f32_16x16x32_bf16 v[56:59], v[144:147], v[202:205], v[56:59]
	v_mfma_f32_16x16x32_bf16 v[60:63], v[182:185], v[202:205], v[60:63]
	v_mfma_f32_16x16x32_bf16 v[64:67], v[144:147], v[228:231], v[64:67]
	v_mfma_f32_16x16x32_bf16 v[68:71], v[182:185], v[228:231], v[68:71]
	v_mfma_f32_16x16x32_bf16 v[108:111], v[174:177], v[190:193], v[108:111]
	v_mfma_f32_16x16x32_bf16 v[112:115], v[20:23], v[190:193], v[112:115]
	v_mfma_f32_16x16x32_bf16 v[116:119], v[174:177], v[198:201], v[116:119]
	v_mfma_f32_16x16x32_bf16 v[52:55], v[20:23], v[198:201], v[52:55]
	v_mfma_f32_16x16x32_bf16 v[56:59], v[174:177], v[220:223], v[56:59]
	v_mfma_f32_16x16x32_bf16 v[60:63], v[20:23], v[220:223], v[60:63]
	v_mfma_f32_16x16x32_bf16 v[64:67], v[174:177], v[232:235], v[64:67]
	v_mfma_f32_16x16x32_bf16 v[68:71], v[20:23], v[232:235], v[68:71]
	s_barrier
	s_mov_b32 m0, s67
	v_lshl_add_u64 v[236:237], v[240:241], 0, s[4:5]
	s_add_u32 s50, s44, 0x18080
	ds_read_b128 v[186:189], v17 offset:49152
	ds_read_b128 v[190:193], v17 offset:50176
	ds_read_b128 v[194:197], v17 offset:51200
	ds_read_b128 v[198:201], v17 offset:52224
	ds_read_b128 v[202:205], v17 offset:53248
	ds_read_b128 v[220:223], v17 offset:54272
	ds_read_b128 v[228:231], v17 offset:55296
	ds_read_b128 v[232:235], v17 offset:56320
	global_load_lds_dwordx4 v[236:237], off
	v_lshl_add_u64 v[236:237], v[242:243], 0, s[4:5]
	s_mov_b32 m0, s63
	s_addc_u32 s51, s45, 0
	global_load_lds_dwordx4 v[236:237], off
	v_lshl_add_u64 v[236:237], s[50:51], 0, v[4:5]
	s_mov_b32 m0, s64
	s_nop 0
	global_load_lds_dwordx4 v[236:237], off
	v_lshl_add_u64 v[236:237], s[50:51], 0, v[0:1]
	s_mov_b32 m0, s66
	s_nop 0
	global_load_lds_dwordx4 v[236:237], off
	v_lshl_add_u64 v[236:237], v[244:245], 0, s[4:5]
	s_mov_b32 m0, s30
	s_nop 0
	global_load_lds_dwordx4 v[236:237], off
	v_lshl_add_u64 v[236:237], v[246:247], 0, s[4:5]
	s_mov_b32 m0, s31
	s_nop 0
	global_load_lds_dwordx4 v[236:237], off
	s_waitcnt vmcnt(8)
	s_waitcnt lgkmcnt(0)
	s_barrier
	s_waitcnt lgkmcnt(0)
	v_mfma_f32_16x16x32_bf16 v[8:11], v[128:131], v[186:189], v[8:11]
	v_mfma_f32_16x16x32_bf16 v[12:15], v[136:139], v[186:189], v[12:15]
	v_mfma_f32_16x16x32_bf16 v[148:151], v[128:131], v[194:197], v[148:151]
	v_mfma_f32_16x16x32_bf16 v[152:155], v[136:139], v[194:197], v[152:155]
	v_mfma_f32_16x16x32_bf16 v[156:159], v[128:131], v[202:205], v[156:159]
	v_mfma_f32_16x16x32_bf16 v[178:181], v[136:139], v[202:205], v[178:181]
	v_mfma_f32_16x16x32_bf16 v[24:27], v[128:131], v[228:231], v[24:27]
	v_mfma_f32_16x16x32_bf16 v[28:31], v[136:139], v[228:231], v[28:31]
	v_mfma_f32_16x16x32_bf16 v[8:11], v[132:135], v[190:193], v[8:11]
	v_mfma_f32_16x16x32_bf16 v[12:15], v[140:143], v[190:193], v[12:15]
	v_mfma_f32_16x16x32_bf16 v[148:151], v[132:135], v[198:201], v[148:151]
	v_mfma_f32_16x16x32_bf16 v[152:155], v[140:143], v[198:201], v[152:155]
	v_mfma_f32_16x16x32_bf16 v[156:159], v[132:135], v[220:223], v[156:159]
	v_mfma_f32_16x16x32_bf16 v[178:181], v[140:143], v[220:223], v[178:181]
	v_mfma_f32_16x16x32_bf16 v[24:27], v[132:135], v[232:235], v[24:27]
	v_mfma_f32_16x16x32_bf16 v[28:31], v[140:143], v[232:235], v[28:31]
	v_mfma_f32_16x16x32_bf16 v[32:35], v[144:147], v[186:189], v[32:35]
	v_mfma_f32_16x16x32_bf16 v[44:47], v[182:185], v[186:189], v[44:47]
	v_mfma_f32_16x16x32_bf16 v[48:51], v[144:147], v[194:197], v[48:51]
	v_mfma_f32_16x16x32_bf16 v[72:75], v[182:185], v[194:197], v[72:75]
	v_mfma_f32_16x16x32_bf16 v[120:123], v[144:147], v[202:205], v[120:123]
	v_mfma_f32_16x16x32_bf16 v[124:127], v[182:185], v[202:205], v[124:127]
	v_mfma_f32_16x16x32_bf16 v[36:39], v[144:147], v[228:231], v[36:39]
	v_mfma_f32_16x16x32_bf16 v[40:43], v[182:185], v[228:231], v[40:43]
	v_mfma_f32_16x16x32_bf16 v[32:35], v[174:177], v[190:193], v[32:35]
	v_mfma_f32_16x16x32_bf16 v[44:47], v[20:23], v[190:193], v[44:47]
	v_mfma_f32_16x16x32_bf16 v[48:51], v[174:177], v[198:201], v[48:51]
	v_mfma_f32_16x16x32_bf16 v[72:75], v[20:23], v[198:201], v[72:75]
	v_mfma_f32_16x16x32_bf16 v[120:123], v[174:177], v[220:223], v[120:123]
	v_mfma_f32_16x16x32_bf16 v[124:127], v[20:23], v[220:223], v[124:127]
	v_mfma_f32_16x16x32_bf16 v[36:39], v[174:177], v[232:235], v[36:39]
	v_mfma_f32_16x16x32_bf16 v[20:23], v[20:23], v[232:235], v[40:43]
	s_barrier
	s_lshl_b32 s50, s55, 8
	s_lshl_b32 s51, s56, 19
	s_add_i32 s50, s50, s51
	v_add_u32_e32 v162, s50, v18
	v_lshl_add_u64 v[128:129], v[162:163], 1, s[46:47]
	v_cvt_pk_bf16_f32 v40, v76, v77
	v_cvt_pk_bf16_f32 v41, v78, v79
	v_cvt_pk_bf16_f32 v42, v80, v81
	v_cvt_pk_bf16_f32 v43, v82, v83
	global_store_dwordx4 v[128:129], v[40:43], off
	v_cvt_pk_bf16_f32 v8, v8, v9
	v_cvt_pk_bf16_f32 v9, v10, v11
	v_cvt_pk_bf16_f32 v40, v108, v109
	v_cvt_pk_bf16_f32 v41, v110, v111
	v_cvt_pk_bf16_f32 v42, v112, v113
	v_cvt_pk_bf16_f32 v43, v114, v115
	global_store_dwordx4 v[128:129], v[40:43], off offset:256
	v_cvt_pk_bf16_f32 v10, v12, v13
	v_cvt_pk_bf16_f32 v11, v14, v15
	v_add_u32_e32 v40, 0x8000, v162
	v_mov_b32_e32 v41, v163
	v_lshl_add_u64 v[76:77], v[40:41], 1, s[46:47]
	v_cvt_pk_bf16_f32 v40, v84, v85
	v_cvt_pk_bf16_f32 v41, v86, v87
	v_cvt_pk_bf16_f32 v42, v88, v89
	v_cvt_pk_bf16_f32 v43, v90, v91
	global_store_dwordx4 v[76:77], v[40:43], off
	s_add_i32 s54, s54, s82
	s_andn2_b64 vcc, exec, s[40:41]
	v_cvt_pk_bf16_f32 v40, v116, v117
	v_cvt_pk_bf16_f32 v41, v118, v119
	v_cvt_pk_bf16_f32 v42, v52, v53
	v_cvt_pk_bf16_f32 v43, v54, v55
	global_store_dwordx4 v[76:77], v[40:43], off offset:256
	s_mov_b32 s55, s6
	s_mov_b32 s56, s7
	v_add_u32_e32 v40, 0x10000, v162
	v_mov_b32_e32 v41, v163
	v_lshl_add_u64 v[52:53], v[40:41], 1, s[46:47]
	v_cvt_pk_bf16_f32 v40, v92, v93
	v_cvt_pk_bf16_f32 v41, v94, v95
	v_cvt_pk_bf16_f32 v42, v96, v97
	v_cvt_pk_bf16_f32 v43, v98, v99
	global_store_dwordx4 v[52:53], v[40:43], off
	s_mov_b64 s[52:53], s[44:45]
	s_mov_b64 s[50:51], s[42:43]
	v_cvt_pk_bf16_f32 v40, v56, v57
	v_cvt_pk_bf16_f32 v41, v58, v59
	v_cvt_pk_bf16_f32 v42, v60, v61
	v_cvt_pk_bf16_f32 v43, v62, v63
	global_store_dwordx4 v[52:53], v[40:43], off offset:256
	s_nop 1
	v_add_u32_e32 v40, 0x18000, v162
	v_mov_b32_e32 v41, v163
	v_lshl_add_u64 v[52:53], v[40:41], 1, s[46:47]
	v_cvt_pk_bf16_f32 v40, v100, v101
	v_cvt_pk_bf16_f32 v41, v102, v103
	v_cvt_pk_bf16_f32 v42, v104, v105
	v_cvt_pk_bf16_f32 v43, v106, v107
	global_store_dwordx4 v[52:53], v[40:43], off
	s_nop 1
	v_cvt_pk_bf16_f32 v40, v64, v65
	v_cvt_pk_bf16_f32 v41, v66, v67
	v_cvt_pk_bf16_f32 v42, v68, v69
	v_cvt_pk_bf16_f32 v43, v70, v71
	global_store_dwordx4 v[52:53], v[40:43], off offset:256
	s_nop 1
	v_add_u32_e32 v40, 0x40000, v162
	v_mov_b32_e32 v41, v163
	v_lshl_add_u64 v[40:41], v[40:41], 1, s[46:47]
	global_store_dwordx4 v[40:41], v[8:11], off
	s_nop 1
	v_cvt_pk_bf16_f32 v8, v32, v33
	v_cvt_pk_bf16_f32 v9, v34, v35
	v_cvt_pk_bf16_f32 v10, v44, v45
	v_cvt_pk_bf16_f32 v11, v46, v47
	global_store_dwordx4 v[40:41], v[8:11], off offset:256
	s_nop 1
	v_add_u32_e32 v8, 0x48000, v162
	v_mov_b32_e32 v9, v163
	v_lshl_add_u64 v[12:13], v[8:9], 1, s[46:47]
	v_cvt_pk_bf16_f32 v8, v148, v149
	v_cvt_pk_bf16_f32 v9, v150, v151
	v_cvt_pk_bf16_f32 v10, v152, v153
	v_cvt_pk_bf16_f32 v11, v154, v155
	global_store_dwordx4 v[12:13], v[8:11], off
	s_nop 1
	v_cvt_pk_bf16_f32 v8, v48, v49
	v_cvt_pk_bf16_f32 v9, v50, v51
	v_cvt_pk_bf16_f32 v10, v72, v73
	v_cvt_pk_bf16_f32 v11, v74, v75
	global_store_dwordx4 v[12:13], v[8:11], off offset:256
	s_nop 1
	v_add_u32_e32 v8, 0x50000, v162
	v_mov_b32_e32 v9, v163
	v_lshl_add_u64 v[12:13], v[8:9], 1, s[46:47]
	v_cvt_pk_bf16_f32 v8, v156, v157
	v_cvt_pk_bf16_f32 v9, v158, v159
	v_cvt_pk_bf16_f32 v10, v178, v179
	v_cvt_pk_bf16_f32 v11, v180, v181
	global_store_dwordx4 v[12:13], v[8:11], off
	v_add_u32_e32 v162, 0x58000, v162
	s_nop 0
	v_cvt_pk_bf16_f32 v8, v120, v121
	v_cvt_pk_bf16_f32 v9, v122, v123
	v_cvt_pk_bf16_f32 v10, v124, v125
	v_cvt_pk_bf16_f32 v11, v126, v127
	global_store_dwordx4 v[12:13], v[8:11], off offset:256
	v_lshl_add_u64 v[12:13], v[162:163], 1, s[46:47]
	s_nop 0
	v_cvt_pk_bf16_f32 v8, v24, v25
	v_cvt_pk_bf16_f32 v9, v26, v27
	v_cvt_pk_bf16_f32 v10, v28, v29
	v_cvt_pk_bf16_f32 v11, v30, v31
	global_store_dwordx4 v[12:13], v[8:11], off
	s_nop 1
	v_cvt_pk_bf16_f32 v8, v36, v37
	v_cvt_pk_bf16_f32 v9, v38, v39
	v_cvt_pk_bf16_f32 v10, v20, v21
	v_cvt_pk_bf16_f32 v11, v22, v23
	global_store_dwordx4 v[12:13], v[8:11], off offset:256
	s_cbranch_vccz .LBB0_513

.LBB0_771:
	s_add_u32 s55, s60, 0xfffc0080
	s_addc_u32 s62, s61, -1
	s_add_i32 s72, 0, 0x10000
	s_cmp_eq_u32 s53, 12
	s_cselect_b32 s65, s6, s62
	s_cselect_b32 s64, s7, s55
	s_cselect_b32 s63, s28, s31
	s_cselect_b32 s62, s29, s30
	s_add_i32 s55, 0, 0x14000
	v_add_u32_e32 v156, s72, v145
	v_add_u32_e32 v162, s55, v145
	ds_read_b128 v[140:143], v156
	ds_read_b128 v[148:151], v156 offset:1024
	ds_read_b128 v[152:155], v156 offset:2048
	ds_read_b128 v[156:159], v156 offset:3072
	ds_read_b128 v[174:177], v162
	ds_read_b128 v[178:181], v162 offset:1024
	ds_read_b128 v[182:185], v162 offset:2048
	ds_read_b128 v[186:189], v162 offset:3072
	v_lshl_add_u64 v[240:241], s[60:61], 0, v[136:137]
	s_add_i32 m0, s25, 0xc000
	ds_read_b128 v[190:193], v147
	ds_read_b128 v[194:197], v147 offset:1024
	ds_read_b128 v[198:201], v147 offset:2048
	ds_read_b128 v[202:205], v147 offset:3072
	ds_read_b128 v[220:223], v147 offset:4096
	ds_read_b128 v[228:231], v147 offset:5120
	ds_read_b128 v[232:235], v147 offset:6144
	ds_read_b128 v[236:239], v147 offset:7168
	global_load_lds_dwordx4 v[240:241], off
	v_lshl_add_u64 v[240:241], s[60:61], 0, v[138:139]
	s_add_i32 m0, s25, 0xe000
	s_nop 0
	global_load_lds_dwordx4 v[240:241], off
	s_waitcnt vmcnt(8)
	s_waitcnt lgkmcnt(0)
	s_barrier
	s_waitcnt lgkmcnt(0)
	v_mfma_f32_16x16x32_bf16 v[124:127], v[140:143], v[190:193], v[124:127]
	v_mfma_f32_16x16x32_bf16 v[120:123], v[152:155], v[190:193], v[120:123]
	v_mfma_f32_16x16x32_bf16 v[108:111], v[140:143], v[198:201], v[108:111]
	v_mfma_f32_16x16x32_bf16 v[104:107], v[152:155], v[198:201], v[104:107]
	v_mfma_f32_16x16x32_bf16 v[92:95], v[140:143], v[220:223], v[92:95]
	v_mfma_f32_16x16x32_bf16 v[88:91], v[152:155], v[220:223], v[88:91]
	v_mfma_f32_16x16x32_bf16 v[76:79], v[140:143], v[232:235], v[76:79]
	v_mfma_f32_16x16x32_bf16 v[72:75], v[152:155], v[232:235], v[72:75]
	v_mfma_f32_16x16x32_bf16 v[124:127], v[148:151], v[194:197], v[124:127]
	v_mfma_f32_16x16x32_bf16 v[120:123], v[156:159], v[194:197], v[120:123]
	v_mfma_f32_16x16x32_bf16 v[108:111], v[148:151], v[202:205], v[108:111]
	v_mfma_f32_16x16x32_bf16 v[104:107], v[156:159], v[202:205], v[104:107]
	v_mfma_f32_16x16x32_bf16 v[92:95], v[148:151], v[228:231], v[92:95]
	v_mfma_f32_16x16x32_bf16 v[88:91], v[156:159], v[228:231], v[88:91]
	v_mfma_f32_16x16x32_bf16 v[76:79], v[148:151], v[236:239], v[76:79]
	v_mfma_f32_16x16x32_bf16 v[72:75], v[156:159], v[236:239], v[72:75]
	v_mfma_f32_16x16x32_bf16 v[116:119], v[174:177], v[190:193], v[116:119]
	v_mfma_f32_16x16x32_bf16 v[112:115], v[182:185], v[190:193], v[112:115]
	v_mfma_f32_16x16x32_bf16 v[100:103], v[174:177], v[198:201], v[100:103]
	v_mfma_f32_16x16x32_bf16 v[96:99], v[182:185], v[198:201], v[96:99]
	v_mfma_f32_16x16x32_bf16 v[84:87], v[174:177], v[220:223], v[84:87]
	v_mfma_f32_16x16x32_bf16 v[80:83], v[182:185], v[220:223], v[80:83]
	v_mfma_f32_16x16x32_bf16 v[68:71], v[174:177], v[232:235], v[68:71]
	v_mfma_f32_16x16x32_bf16 v[64:67], v[182:185], v[232:235], v[64:67]
	v_mfma_f32_16x16x32_bf16 v[116:119], v[178:181], v[194:197], v[116:119]
	v_mfma_f32_16x16x32_bf16 v[112:115], v[186:189], v[194:197], v[112:115]
	v_mfma_f32_16x16x32_bf16 v[100:103], v[178:181], v[202:205], v[100:103]
	v_mfma_f32_16x16x32_bf16 v[96:99], v[186:189], v[202:205], v[96:99]
	v_mfma_f32_16x16x32_bf16 v[84:87], v[178:181], v[228:231], v[84:87]
	v_mfma_f32_16x16x32_bf16 v[80:83], v[186:189], v[228:231], v[80:83]
	v_mfma_f32_16x16x32_bf16 v[68:71], v[178:181], v[236:239], v[68:71]
	v_mfma_f32_16x16x32_bf16 v[64:67], v[186:189], v[236:239], v[64:67]
	s_barrier
	s_add_i32 s72, s72, s24
	v_lshl_add_u64 v[240:241], s[62:63], 0, v[132:133]
	s_mov_b32 m0, s72
	ds_read_b128 v[190:193], v147 offset:16384
	ds_read_b128 v[194:197], v147 offset:17408
	ds_read_b128 v[198:201], v147 offset:18432
	ds_read_b128 v[202:205], v147 offset:19456
	ds_read_b128 v[220:223], v147 offset:20480
	ds_read_b128 v[228:231], v147 offset:21504
	ds_read_b128 v[232:235], v147 offset:22528
	ds_read_b128 v[236:239], v147 offset:23552
	global_load_lds_dwordx4 v[240:241], off
	s_add_i32 m0, s72, 0x2000
	s_add_u32 s72, s62, 0x40000
	v_lshl_add_u64 v[242:243], s[62:63], 0, v[128:129]
	s_addc_u32 s73, s63, 0
	s_add_i32 s55, s55, s24
	global_load_lds_dwordx4 v[242:243], off
	v_lshl_add_u64 v[244:245], s[72:73], 0, v[132:133]
	s_mov_b32 m0, s55
	v_lshl_add_u64 v[246:247], s[64:65], 0, v[130:131]
	global_load_lds_dwordx4 v[244:245], off
	v_lshl_add_u64 v[244:245], s[72:73], 0, v[128:129]
	s_add_i32 m0, s55, 0x2000
	s_nop 0
	global_load_lds_dwordx4 v[244:245], off
	v_lshl_add_u64 v[244:245], s[64:65], 0, v[134:135]
	s_mov_b32 m0, s25
	s_nop 0
	global_load_lds_dwordx4 v[244:245], off
	s_mov_b32 m0, s66
	s_nop 0
	global_load_lds_dwordx4 v[246:247], off
	s_waitcnt vmcnt(8)
	s_waitcnt lgkmcnt(0)
	s_barrier
	s_waitcnt lgkmcnt(0)
	v_mfma_f32_16x16x32_bf16 v[60:63], v[140:143], v[190:193], v[60:63]
	v_mfma_f32_16x16x32_bf16 v[56:59], v[152:155], v[190:193], v[56:59]
	v_mfma_f32_16x16x32_bf16 v[44:47], v[140:143], v[198:201], v[44:47]
	v_mfma_f32_16x16x32_bf16 v[40:43], v[152:155], v[198:201], v[40:43]
	v_mfma_f32_16x16x32_bf16 v[28:31], v[140:143], v[220:223], v[28:31]
	v_mfma_f32_16x16x32_bf16 v[24:27], v[152:155], v[220:223], v[24:27]
	v_mfma_f32_16x16x32_bf16 v[12:15], v[140:143], v[232:235], v[12:15]
	v_mfma_f32_16x16x32_bf16 v[8:11], v[152:155], v[232:235], v[8:11]
	v_mfma_f32_16x16x32_bf16 v[60:63], v[148:151], v[194:197], v[60:63]
	v_mfma_f32_16x16x32_bf16 v[56:59], v[156:159], v[194:197], v[56:59]
	v_mfma_f32_16x16x32_bf16 v[44:47], v[148:151], v[202:205], v[44:47]
	v_mfma_f32_16x16x32_bf16 v[40:43], v[156:159], v[202:205], v[40:43]
	v_mfma_f32_16x16x32_bf16 v[28:31], v[148:151], v[228:231], v[28:31]
	v_mfma_f32_16x16x32_bf16 v[24:27], v[156:159], v[228:231], v[24:27]
	v_mfma_f32_16x16x32_bf16 v[12:15], v[148:151], v[236:239], v[12:15]
	v_mfma_f32_16x16x32_bf16 v[8:11], v[156:159], v[236:239], v[8:11]
	v_mfma_f32_16x16x32_bf16 v[52:55], v[174:177], v[190:193], v[52:55]
	v_mfma_f32_16x16x32_bf16 v[48:51], v[182:185], v[190:193], v[48:51]
	v_mfma_f32_16x16x32_bf16 v[36:39], v[174:177], v[198:201], v[36:39]
	v_mfma_f32_16x16x32_bf16 v[32:35], v[182:185], v[198:201], v[32:35]
	v_mfma_f32_16x16x32_bf16 v[20:23], v[174:177], v[220:223], v[20:23]
	v_mfma_f32_16x16x32_bf16 v[16:19], v[182:185], v[220:223], v[16:19]
	v_mfma_f32_16x16x32_bf16 v[4:7], v[174:177], v[232:235], v[4:7]
	v_mfma_f32_16x16x32_bf16 v[0:3], v[182:185], v[232:235], v[0:3]
	v_mfma_f32_16x16x32_bf16 v[52:55], v[178:181], v[194:197], v[52:55]
	v_mfma_f32_16x16x32_bf16 v[48:51], v[186:189], v[194:197], v[48:51]
	v_mfma_f32_16x16x32_bf16 v[36:39], v[178:181], v[202:205], v[36:39]
	v_mfma_f32_16x16x32_bf16 v[32:35], v[186:189], v[202:205], v[32:35]
	v_mfma_f32_16x16x32_bf16 v[20:23], v[178:181], v[228:231], v[20:23]
	v_mfma_f32_16x16x32_bf16 v[16:19], v[186:189], v[228:231], v[16:19]
	v_mfma_f32_16x16x32_bf16 v[4:7], v[178:181], v[236:239], v[4:7]
	v_mfma_f32_16x16x32_bf16 v[0:3], v[186:189], v[236:239], v[0:3]
	s_barrier
	s_add_i32 s55, 0, 0x18000
	s_add_i32 s72, 0, 0x1c000
	v_add_u32_e32 v156, s55, v145
	v_add_u32_e32 v162, s72, v145
	ds_read_b128 v[140:143], v156
	ds_read_b128 v[148:151], v156 offset:1024
	ds_read_b128 v[152:155], v156 offset:2048
	ds_read_b128 v[156:159], v156 offset:3072
	ds_read_b128 v[174:177], v162
	ds_read_b128 v[178:181], v162 offset:1024
	ds_read_b128 v[182:185], v162 offset:2048
	ds_read_b128 v[186:189], v162 offset:3072
	s_add_u32 s64, s64, 0x40000
	s_addc_u32 s65, s65, 0
	s_mov_b32 m0, s67
	v_lshl_add_u64 v[248:249], s[64:65], 0, v[134:135]
	ds_read_b128 v[190:193], v147 offset:32768
	ds_read_b128 v[194:197], v147 offset:33792
	ds_read_b128 v[198:201], v147 offset:34816
	ds_read_b128 v[202:205], v147 offset:35840
	ds_read_b128 v[220:223], v147 offset:36864
	ds_read_b128 v[228:231], v147 offset:37888
	ds_read_b128 v[232:235], v147 offset:38912
	ds_read_b128 v[236:239], v147 offset:39936
	global_load_lds_dwordx4 v[248:249], off
	v_lshl_add_u64 v[248:249], s[64:65], 0, v[130:131]
	s_mov_b32 m0, s68
	s_nop 0
	global_load_lds_dwordx4 v[248:249], off
	s_waitcnt vmcnt(8)
	s_waitcnt lgkmcnt(0)
	s_barrier
	s_waitcnt lgkmcnt(0)
	v_mfma_f32_16x16x32_bf16 v[124:127], v[140:143], v[190:193], v[124:127]
	v_mfma_f32_16x16x32_bf16 v[120:123], v[152:155], v[190:193], v[120:123]
	v_mfma_f32_16x16x32_bf16 v[108:111], v[140:143], v[198:201], v[108:111]
	v_mfma_f32_16x16x32_bf16 v[104:107], v[152:155], v[198:201], v[104:107]
	v_mfma_f32_16x16x32_bf16 v[92:95], v[140:143], v[220:223], v[92:95]
	v_mfma_f32_16x16x32_bf16 v[88:91], v[152:155], v[220:223], v[88:91]
	v_mfma_f32_16x16x32_bf16 v[76:79], v[140:143], v[232:235], v[76:79]
	v_mfma_f32_16x16x32_bf16 v[72:75], v[152:155], v[232:235], v[72:75]
	v_mfma_f32_16x16x32_bf16 v[124:127], v[148:151], v[194:197], v[124:127]
	v_mfma_f32_16x16x32_bf16 v[120:123], v[156:159], v[194:197], v[120:123]
	v_mfma_f32_16x16x32_bf16 v[108:111], v[148:151], v[202:205], v[108:111]
	v_mfma_f32_16x16x32_bf16 v[104:107], v[156:159], v[202:205], v[104:107]
	v_mfma_f32_16x16x32_bf16 v[92:95], v[148:151], v[228:231], v[92:95]
	v_mfma_f32_16x16x32_bf16 v[88:91], v[156:159], v[228:231], v[88:91]
	v_mfma_f32_16x16x32_bf16 v[76:79], v[148:151], v[236:239], v[76:79]
	v_mfma_f32_16x16x32_bf16 v[72:75], v[156:159], v[236:239], v[72:75]
	v_mfma_f32_16x16x32_bf16 v[116:119], v[174:177], v[190:193], v[116:119]
	v_mfma_f32_16x16x32_bf16 v[112:115], v[182:185], v[190:193], v[112:115]
	v_mfma_f32_16x16x32_bf16 v[100:103], v[174:177], v[198:201], v[100:103]
	v_mfma_f32_16x16x32_bf16 v[96:99], v[182:185], v[198:201], v[96:99]
	v_mfma_f32_16x16x32_bf16 v[84:87], v[174:177], v[220:223], v[84:87]
	v_mfma_f32_16x16x32_bf16 v[80:83], v[182:185], v[220:223], v[80:83]
	v_mfma_f32_16x16x32_bf16 v[68:71], v[174:177], v[232:235], v[68:71]
	v_mfma_f32_16x16x32_bf16 v[64:67], v[182:185], v[232:235], v[64:67]
	v_mfma_f32_16x16x32_bf16 v[116:119], v[178:181], v[194:197], v[116:119]
	v_mfma_f32_16x16x32_bf16 v[112:115], v[186:189], v[194:197], v[112:115]
	v_mfma_f32_16x16x32_bf16 v[100:103], v[178:181], v[202:205], v[100:103]
	v_mfma_f32_16x16x32_bf16 v[96:99], v[186:189], v[202:205], v[96:99]
	v_mfma_f32_16x16x32_bf16 v[84:87], v[178:181], v[228:231], v[84:87]
	v_mfma_f32_16x16x32_bf16 v[80:83], v[186:189], v[228:231], v[80:83]
	v_mfma_f32_16x16x32_bf16 v[68:71], v[178:181], v[236:239], v[68:71]
	v_mfma_f32_16x16x32_bf16 v[64:67], v[186:189], v[236:239], v[64:67]
	s_barrier
	s_add_i32 s55, s55, s24
	v_lshl_add_u64 v[240:241], v[240:241], 0, s[4:5]
	s_mov_b32 m0, s55
	ds_read_b128 v[190:193], v147 offset:49152
	ds_read_b128 v[194:197], v147 offset:50176
	ds_read_b128 v[198:201], v147 offset:51200
	ds_read_b128 v[202:205], v147 offset:52224
	ds_read_b128 v[220:223], v147 offset:53248
	ds_read_b128 v[228:231], v147 offset:54272
	ds_read_b128 v[232:235], v147 offset:55296
	ds_read_b128 v[236:239], v147 offset:56320
	global_load_lds_dwordx4 v[240:241], off
	s_add_i32 m0, s55, 0x2000
	s_add_u32 s62, s62, 0x40080
	v_lshl_add_u64 v[240:241], v[242:243], 0, s[4:5]
	s_addc_u32 s63, s63, 0
	s_add_i32 s55, s72, s24
	global_load_lds_dwordx4 v[240:241], off
	v_lshl_add_u64 v[240:241], s[62:63], 0, v[132:133]
	s_mov_b32 m0, s55
	s_nop 0
	global_load_lds_dwordx4 v[240:241], off
	v_lshl_add_u64 v[240:241], s[62:63], 0, v[128:129]
	s_add_i32 m0, s55, 0x2000
	s_nop 0
	global_load_lds_dwordx4 v[240:241], off
	v_lshl_add_u64 v[240:241], v[244:245], 0, s[4:5]
	s_mov_b32 m0, s69
	s_nop 0
	global_load_lds_dwordx4 v[240:241], off
	v_lshl_add_u64 v[240:241], v[246:247], 0, s[4:5]
	s_mov_b32 m0, s70
	s_nop 0
	global_load_lds_dwordx4 v[240:241], off
	s_waitcnt vmcnt(8)
	s_waitcnt lgkmcnt(0)
	s_barrier
	s_waitcnt lgkmcnt(0)
	v_mfma_f32_16x16x32_bf16 v[60:63], v[140:143], v[190:193], v[60:63]
	v_mfma_f32_16x16x32_bf16 v[56:59], v[152:155], v[190:193], v[56:59]
	v_mfma_f32_16x16x32_bf16 v[44:47], v[140:143], v[198:201], v[44:47]
	v_mfma_f32_16x16x32_bf16 v[40:43], v[152:155], v[198:201], v[40:43]
	v_mfma_f32_16x16x32_bf16 v[28:31], v[140:143], v[220:223], v[28:31]
	v_mfma_f32_16x16x32_bf16 v[24:27], v[152:155], v[220:223], v[24:27]
	v_mfma_f32_16x16x32_bf16 v[12:15], v[140:143], v[232:235], v[12:15]
	v_mfma_f32_16x16x32_bf16 v[8:11], v[152:155], v[232:235], v[8:11]
	v_mfma_f32_16x16x32_bf16 v[60:63], v[148:151], v[194:197], v[60:63]
	v_mfma_f32_16x16x32_bf16 v[56:59], v[156:159], v[194:197], v[56:59]
	v_mfma_f32_16x16x32_bf16 v[44:47], v[148:151], v[202:205], v[44:47]
	v_mfma_f32_16x16x32_bf16 v[40:43], v[156:159], v[202:205], v[40:43]
	v_mfma_f32_16x16x32_bf16 v[28:31], v[148:151], v[228:231], v[28:31]
	v_mfma_f32_16x16x32_bf16 v[24:27], v[156:159], v[228:231], v[24:27]
	v_mfma_f32_16x16x32_bf16 v[12:15], v[148:151], v[236:239], v[12:15]
	v_mfma_f32_16x16x32_bf16 v[8:11], v[156:159], v[236:239], v[8:11]
	v_mfma_f32_16x16x32_bf16 v[52:55], v[174:177], v[190:193], v[52:55]
	v_mfma_f32_16x16x32_bf16 v[48:51], v[182:185], v[190:193], v[48:51]
	v_mfma_f32_16x16x32_bf16 v[36:39], v[174:177], v[198:201], v[36:39]
	v_mfma_f32_16x16x32_bf16 v[32:35], v[182:185], v[198:201], v[32:35]
	v_mfma_f32_16x16x32_bf16 v[20:23], v[174:177], v[220:223], v[20:23]
	v_mfma_f32_16x16x32_bf16 v[16:19], v[182:185], v[220:223], v[16:19]
	v_mfma_f32_16x16x32_bf16 v[4:7], v[174:177], v[232:235], v[4:7]
	v_mfma_f32_16x16x32_bf16 v[0:3], v[182:185], v[232:235], v[0:3]
	v_mfma_f32_16x16x32_bf16 v[52:55], v[178:181], v[194:197], v[52:55]
	v_mfma_f32_16x16x32_bf16 v[48:51], v[186:189], v[194:197], v[48:51]
	v_mfma_f32_16x16x32_bf16 v[36:39], v[178:181], v[202:205], v[36:39]
	v_mfma_f32_16x16x32_bf16 v[32:35], v[186:189], v[202:205], v[32:35]
	v_mfma_f32_16x16x32_bf16 v[20:23], v[178:181], v[228:231], v[20:23]
	v_mfma_f32_16x16x32_bf16 v[16:19], v[186:189], v[228:231], v[16:19]
	v_mfma_f32_16x16x32_bf16 v[4:7], v[178:181], v[236:239], v[4:7]
	v_mfma_f32_16x16x32_bf16 v[0:3], v[186:189], v[236:239], v[0:3]
	s_barrier
	s_add_i32 s53, s53, 2
	s_add_u32 s60, s60, 0x100
	s_addc_u32 s61, s61, 0
	s_add_u32 s30, s30, 0x100
	s_addc_u32 s31, s31, 0
	s_cmp_gt_u32 s53, 13
	s_cbranch_scc0 .LBB0_771
	s_and_b64 vcc, exec, s[48:49]
	s_mov_b64 s[30:31], s[34:35]
	s_cbranch_vccz .LBB0_774
	s_barrier

.LBB0_858:
	s_add_u32 s61, s66, 0xfffe0080
	s_addc_u32 s68, s67, -1
	s_add_i32 s83, 0, 0x10000
	s_cmp_eq_u32 s59, 4
	s_cselect_b32 s71, s6, s68
	s_cselect_b32 s70, s7, s61
	v_add_u32_e32 v136, s83, v157
	s_cselect_b32 s69, s28, s31
	s_cselect_b32 s68, s29, s30
	s_add_i32 s61, 0, 0x14000
	ds_read_b128 v[128:131], v136
	ds_read_b128 v[132:135], v136 offset:1024
	ds_read_b128 v[148:151], v136 offset:2048
	ds_read_b128 v[152:155], v136 offset:3072
	v_add_u32_e32 v136, s61, v157
	ds_read_b128 v[174:177], v136
	ds_read_b128 v[178:181], v136 offset:1024
	ds_read_b128 v[182:185], v136 offset:2048
	ds_read_b128 v[186:189], v136 offset:3072
	v_lshl_add_u64 v[136:137], s[66:67], 0, v[144:145]
	s_add_i32 m0, s25, 0xc000
	ds_read_b128 v[190:193], v159
	ds_read_b128 v[194:197], v159 offset:1024
	ds_read_b128 v[198:201], v159 offset:2048
	ds_read_b128 v[202:205], v159 offset:3072
	ds_read_b128 v[220:223], v159 offset:4096
	ds_read_b128 v[228:231], v159 offset:5120
	ds_read_b128 v[232:235], v159 offset:6144
	ds_read_b128 v[236:239], v159 offset:7168
	global_load_lds_dwordx4 v[136:137], off
	v_lshl_add_u64 v[136:137], s[66:67], 0, v[146:147]
	s_add_i32 m0, s25, 0xe000
	s_nop 0
	global_load_lds_dwordx4 v[136:137], off
	s_waitcnt vmcnt(8)
	s_waitcnt lgkmcnt(0)
	s_barrier
	s_waitcnt lgkmcnt(0)
	v_mfma_f32_16x16x32_bf16 v[124:127], v[128:131], v[190:193], v[124:127]
	v_mfma_f32_16x16x32_bf16 v[120:123], v[148:151], v[190:193], v[120:123]
	v_mfma_f32_16x16x32_bf16 v[108:111], v[128:131], v[198:201], v[108:111]
	v_mfma_f32_16x16x32_bf16 v[104:107], v[148:151], v[198:201], v[104:107]
	v_mfma_f32_16x16x32_bf16 v[92:95], v[128:131], v[220:223], v[92:95]
	v_mfma_f32_16x16x32_bf16 v[88:91], v[148:151], v[220:223], v[88:91]
	v_mfma_f32_16x16x32_bf16 v[76:79], v[128:131], v[232:235], v[76:79]
	v_mfma_f32_16x16x32_bf16 v[72:75], v[148:151], v[232:235], v[72:75]
	v_mfma_f32_16x16x32_bf16 v[124:127], v[132:135], v[194:197], v[124:127]
	v_mfma_f32_16x16x32_bf16 v[120:123], v[152:155], v[194:197], v[120:123]
	v_mfma_f32_16x16x32_bf16 v[108:111], v[132:135], v[202:205], v[108:111]
	v_mfma_f32_16x16x32_bf16 v[104:107], v[152:155], v[202:205], v[104:107]
	v_mfma_f32_16x16x32_bf16 v[92:95], v[132:135], v[228:231], v[92:95]
	v_mfma_f32_16x16x32_bf16 v[88:91], v[152:155], v[228:231], v[88:91]
	v_mfma_f32_16x16x32_bf16 v[76:79], v[132:135], v[236:239], v[76:79]
	v_mfma_f32_16x16x32_bf16 v[72:75], v[152:155], v[236:239], v[72:75]
	v_mfma_f32_16x16x32_bf16 v[116:119], v[174:177], v[190:193], v[116:119]
	v_mfma_f32_16x16x32_bf16 v[112:115], v[182:185], v[190:193], v[112:115]
	v_mfma_f32_16x16x32_bf16 v[100:103], v[174:177], v[198:201], v[100:103]
	v_mfma_f32_16x16x32_bf16 v[96:99], v[182:185], v[198:201], v[96:99]
	v_mfma_f32_16x16x32_bf16 v[84:87], v[174:177], v[220:223], v[84:87]
	v_mfma_f32_16x16x32_bf16 v[80:83], v[182:185], v[220:223], v[80:83]
	v_mfma_f32_16x16x32_bf16 v[68:71], v[174:177], v[232:235], v[68:71]
	v_mfma_f32_16x16x32_bf16 v[64:67], v[182:185], v[232:235], v[64:67]
	v_mfma_f32_16x16x32_bf16 v[116:119], v[178:181], v[194:197], v[116:119]
	v_mfma_f32_16x16x32_bf16 v[112:115], v[186:189], v[194:197], v[112:115]
	v_mfma_f32_16x16x32_bf16 v[100:103], v[178:181], v[202:205], v[100:103]
	v_mfma_f32_16x16x32_bf16 v[96:99], v[186:189], v[202:205], v[96:99]
	v_mfma_f32_16x16x32_bf16 v[84:87], v[178:181], v[228:231], v[84:87]
	v_mfma_f32_16x16x32_bf16 v[80:83], v[186:189], v[228:231], v[80:83]
	v_mfma_f32_16x16x32_bf16 v[68:71], v[178:181], v[236:239], v[68:71]
	v_mfma_f32_16x16x32_bf16 v[64:67], v[186:189], v[236:239], v[64:67]
	s_barrier
	s_add_i32 s83, s83, s22
	v_lshl_add_u64 v[136:137], s[68:69], 0, v[162:163]
	s_mov_b32 m0, s83
	ds_read_b128 v[190:193], v159 offset:16384
	ds_read_b128 v[194:197], v159 offset:17408
	ds_read_b128 v[198:201], v159 offset:18432
	ds_read_b128 v[202:205], v159 offset:19456
	ds_read_b128 v[220:223], v159 offset:20480
	ds_read_b128 v[228:231], v159 offset:21504
	ds_read_b128 v[232:235], v159 offset:22528
	ds_read_b128 v[236:239], v159 offset:23552
	global_load_lds_dwordx4 v[136:137], off
	s_add_i32 m0, s83, 0x2000
	s_add_u32 s84, s68, 0x20000
	v_lshl_add_u64 v[240:241], s[68:69], 0, v[138:139]
	s_addc_u32 s85, s69, 0
	s_add_i32 s61, s61, s22
	global_load_lds_dwordx4 v[240:241], off
	v_lshl_add_u64 v[242:243], s[84:85], 0, v[162:163]
	s_mov_b32 m0, s61
	v_lshl_add_u64 v[244:245], s[70:71], 0, v[140:141]
	global_load_lds_dwordx4 v[242:243], off
	v_lshl_add_u64 v[242:243], s[84:85], 0, v[138:139]
	s_add_i32 m0, s61, 0x2000
	s_nop 0
	global_load_lds_dwordx4 v[242:243], off
	v_lshl_add_u64 v[242:243], s[70:71], 0, v[142:143]
	s_mov_b32 m0, s25
	s_nop 0
	global_load_lds_dwordx4 v[242:243], off
	s_mov_b32 m0, s72
	s_nop 0
	global_load_lds_dwordx4 v[244:245], off
	s_waitcnt vmcnt(8)
	s_waitcnt lgkmcnt(0)
	s_barrier
	s_waitcnt lgkmcnt(0)
	v_mfma_f32_16x16x32_bf16 v[60:63], v[128:131], v[190:193], v[60:63]
	v_mfma_f32_16x16x32_bf16 v[56:59], v[148:151], v[190:193], v[56:59]
	v_mfma_f32_16x16x32_bf16 v[44:47], v[128:131], v[198:201], v[44:47]
	v_mfma_f32_16x16x32_bf16 v[40:43], v[148:151], v[198:201], v[40:43]
	v_mfma_f32_16x16x32_bf16 v[28:31], v[128:131], v[220:223], v[28:31]
	v_mfma_f32_16x16x32_bf16 v[24:27], v[148:151], v[220:223], v[24:27]
	v_mfma_f32_16x16x32_bf16 v[12:15], v[128:131], v[232:235], v[12:15]
	v_mfma_f32_16x16x32_bf16 v[8:11], v[148:151], v[232:235], v[8:11]
	v_mfma_f32_16x16x32_bf16 v[60:63], v[132:135], v[194:197], v[60:63]
	v_mfma_f32_16x16x32_bf16 v[56:59], v[152:155], v[194:197], v[56:59]
	v_mfma_f32_16x16x32_bf16 v[44:47], v[132:135], v[202:205], v[44:47]
	v_mfma_f32_16x16x32_bf16 v[40:43], v[152:155], v[202:205], v[40:43]
	v_mfma_f32_16x16x32_bf16 v[28:31], v[132:135], v[228:231], v[28:31]
	v_mfma_f32_16x16x32_bf16 v[24:27], v[152:155], v[228:231], v[24:27]
	v_mfma_f32_16x16x32_bf16 v[12:15], v[132:135], v[236:239], v[12:15]
	v_mfma_f32_16x16x32_bf16 v[8:11], v[152:155], v[236:239], v[8:11]
	v_mfma_f32_16x16x32_bf16 v[52:55], v[174:177], v[190:193], v[52:55]
	v_mfma_f32_16x16x32_bf16 v[48:51], v[182:185], v[190:193], v[48:51]
	v_mfma_f32_16x16x32_bf16 v[36:39], v[174:177], v[198:201], v[36:39]
	v_mfma_f32_16x16x32_bf16 v[32:35], v[182:185], v[198:201], v[32:35]
	v_mfma_f32_16x16x32_bf16 v[20:23], v[174:177], v[220:223], v[20:23]
	v_mfma_f32_16x16x32_bf16 v[16:19], v[182:185], v[220:223], v[16:19]
	v_mfma_f32_16x16x32_bf16 v[4:7], v[174:177], v[232:235], v[4:7]
	v_mfma_f32_16x16x32_bf16 v[0:3], v[182:185], v[232:235], v[0:3]
	v_mfma_f32_16x16x32_bf16 v[52:55], v[178:181], v[194:197], v[52:55]
	v_mfma_f32_16x16x32_bf16 v[48:51], v[186:189], v[194:197], v[48:51]
	v_mfma_f32_16x16x32_bf16 v[36:39], v[178:181], v[202:205], v[36:39]
	v_mfma_f32_16x16x32_bf16 v[32:35], v[186:189], v[202:205], v[32:35]
	v_mfma_f32_16x16x32_bf16 v[20:23], v[178:181], v[228:231], v[20:23]
	v_mfma_f32_16x16x32_bf16 v[16:19], v[186:189], v[228:231], v[16:19]
	v_mfma_f32_16x16x32_bf16 v[4:7], v[178:181], v[236:239], v[4:7]
	v_mfma_f32_16x16x32_bf16 v[0:3], v[186:189], v[236:239], v[0:3]
	s_barrier
	s_add_i32 s61, 0, 0x18000
	s_add_i32 s83, 0, 0x1c000
	v_add_u32_e32 v152, s61, v157
	v_add_u32_e32 v186, s83, v157
	ds_read_b128 v[128:131], v152
	ds_read_b128 v[132:135], v152 offset:1024
	ds_read_b128 v[148:151], v152 offset:2048
	ds_read_b128 v[152:155], v152 offset:3072
	ds_read_b128 v[174:177], v186
	ds_read_b128 v[178:181], v186 offset:1024
	ds_read_b128 v[182:185], v186 offset:2048
	ds_read_b128 v[186:189], v186 offset:3072
	s_add_u32 s70, s70, 0x20000
	s_addc_u32 s71, s71, 0
	s_mov_b32 m0, s73
	v_lshl_add_u64 v[246:247], s[70:71], 0, v[142:143]
	ds_read_b128 v[190:193], v159 offset:32768
	ds_read_b128 v[194:197], v159 offset:33792
	ds_read_b128 v[198:201], v159 offset:34816
	ds_read_b128 v[202:205], v159 offset:35840
	ds_read_b128 v[220:223], v159 offset:36864
	ds_read_b128 v[228:231], v159 offset:37888
	ds_read_b128 v[232:235], v159 offset:38912
	ds_read_b128 v[236:239], v159 offset:39936
	global_load_lds_dwordx4 v[246:247], off
	v_lshl_add_u64 v[246:247], s[70:71], 0, v[140:141]
	s_mov_b32 m0, s74
	s_nop 0
	global_load_lds_dwordx4 v[246:247], off
	s_waitcnt vmcnt(8)
	s_waitcnt lgkmcnt(0)
	s_barrier
	s_waitcnt lgkmcnt(0)
	v_mfma_f32_16x16x32_bf16 v[124:127], v[128:131], v[190:193], v[124:127]
	v_mfma_f32_16x16x32_bf16 v[120:123], v[148:151], v[190:193], v[120:123]
	v_mfma_f32_16x16x32_bf16 v[108:111], v[128:131], v[198:201], v[108:111]
	v_mfma_f32_16x16x32_bf16 v[104:107], v[148:151], v[198:201], v[104:107]
	v_mfma_f32_16x16x32_bf16 v[92:95], v[128:131], v[220:223], v[92:95]
	v_mfma_f32_16x16x32_bf16 v[88:91], v[148:151], v[220:223], v[88:91]
	v_mfma_f32_16x16x32_bf16 v[76:79], v[128:131], v[232:235], v[76:79]
	v_mfma_f32_16x16x32_bf16 v[72:75], v[148:151], v[232:235], v[72:75]
	v_mfma_f32_16x16x32_bf16 v[124:127], v[132:135], v[194:197], v[124:127]
	v_mfma_f32_16x16x32_bf16 v[120:123], v[152:155], v[194:197], v[120:123]
	v_mfma_f32_16x16x32_bf16 v[108:111], v[132:135], v[202:205], v[108:111]
	v_mfma_f32_16x16x32_bf16 v[104:107], v[152:155], v[202:205], v[104:107]
	v_mfma_f32_16x16x32_bf16 v[92:95], v[132:135], v[228:231], v[92:95]
	v_mfma_f32_16x16x32_bf16 v[88:91], v[152:155], v[228:231], v[88:91]
	v_mfma_f32_16x16x32_bf16 v[76:79], v[132:135], v[236:239], v[76:79]
	v_mfma_f32_16x16x32_bf16 v[72:75], v[152:155], v[236:239], v[72:75]
	v_mfma_f32_16x16x32_bf16 v[116:119], v[174:177], v[190:193], v[116:119]
	v_mfma_f32_16x16x32_bf16 v[112:115], v[182:185], v[190:193], v[112:115]
	v_mfma_f32_16x16x32_bf16 v[100:103], v[174:177], v[198:201], v[100:103]
	v_mfma_f32_16x16x32_bf16 v[96:99], v[182:185], v[198:201], v[96:99]
	v_mfma_f32_16x16x32_bf16 v[84:87], v[174:177], v[220:223], v[84:87]
	v_mfma_f32_16x16x32_bf16 v[80:83], v[182:185], v[220:223], v[80:83]
	v_mfma_f32_16x16x32_bf16 v[68:71], v[174:177], v[232:235], v[68:71]
	v_mfma_f32_16x16x32_bf16 v[64:67], v[182:185], v[232:235], v[64:67]
	v_mfma_f32_16x16x32_bf16 v[116:119], v[178:181], v[194:197], v[116:119]
	v_mfma_f32_16x16x32_bf16 v[112:115], v[186:189], v[194:197], v[112:115]
	v_mfma_f32_16x16x32_bf16 v[100:103], v[178:181], v[202:205], v[100:103]
	v_mfma_f32_16x16x32_bf16 v[96:99], v[186:189], v[202:205], v[96:99]
	v_mfma_f32_16x16x32_bf16 v[84:87], v[178:181], v[228:231], v[84:87]
	v_mfma_f32_16x16x32_bf16 v[80:83], v[186:189], v[228:231], v[80:83]
	v_mfma_f32_16x16x32_bf16 v[68:71], v[178:181], v[236:239], v[68:71]
	v_mfma_f32_16x16x32_bf16 v[64:67], v[186:189], v[236:239], v[64:67]
	s_barrier
	s_add_i32 s61, s61, s22
	v_lshl_add_u64 v[136:137], v[136:137], 0, s[4:5]
	s_mov_b32 m0, s61
	ds_read_b128 v[190:193], v159 offset:49152
	ds_read_b128 v[194:197], v159 offset:50176
	ds_read_b128 v[198:201], v159 offset:51200
	ds_read_b128 v[202:205], v159 offset:52224
	ds_read_b128 v[220:223], v159 offset:53248
	ds_read_b128 v[228:231], v159 offset:54272
	ds_read_b128 v[232:235], v159 offset:55296
	ds_read_b128 v[236:239], v159 offset:56320
	global_load_lds_dwordx4 v[136:137], off
	s_add_i32 m0, s61, 0x2000
	s_add_u32 s68, s68, 0x20080
	v_lshl_add_u64 v[136:137], v[240:241], 0, s[4:5]
	s_addc_u32 s69, s69, 0
	s_add_i32 s61, s83, s22
	global_load_lds_dwordx4 v[136:137], off
	v_lshl_add_u64 v[136:137], s[68:69], 0, v[162:163]
	s_mov_b32 m0, s61
	s_nop 0
	global_load_lds_dwordx4 v[136:137], off
	v_lshl_add_u64 v[136:137], s[68:69], 0, v[138:139]
	s_add_i32 m0, s61, 0x2000
	s_nop 0
	global_load_lds_dwordx4 v[136:137], off
	v_lshl_add_u64 v[136:137], v[242:243], 0, s[4:5]
	s_mov_b32 m0, s75
	s_nop 0
	global_load_lds_dwordx4 v[136:137], off
	v_lshl_add_u64 v[136:137], v[244:245], 0, s[4:5]
	s_mov_b32 m0, s76
	s_nop 0
	global_load_lds_dwordx4 v[136:137], off
	s_waitcnt vmcnt(8)
	s_waitcnt lgkmcnt(0)
	s_barrier
	s_waitcnt lgkmcnt(0)
	v_mfma_f32_16x16x32_bf16 v[60:63], v[128:131], v[190:193], v[60:63]
	v_mfma_f32_16x16x32_bf16 v[56:59], v[148:151], v[190:193], v[56:59]
	v_mfma_f32_16x16x32_bf16 v[44:47], v[128:131], v[198:201], v[44:47]
	v_mfma_f32_16x16x32_bf16 v[40:43], v[148:151], v[198:201], v[40:43]
	v_mfma_f32_16x16x32_bf16 v[28:31], v[128:131], v[220:223], v[28:31]
	v_mfma_f32_16x16x32_bf16 v[24:27], v[148:151], v[220:223], v[24:27]
	v_mfma_f32_16x16x32_bf16 v[12:15], v[128:131], v[232:235], v[12:15]
	v_mfma_f32_16x16x32_bf16 v[8:11], v[148:151], v[232:235], v[8:11]
	v_mfma_f32_16x16x32_bf16 v[60:63], v[132:135], v[194:197], v[60:63]
	v_mfma_f32_16x16x32_bf16 v[56:59], v[152:155], v[194:197], v[56:59]
	v_mfma_f32_16x16x32_bf16 v[44:47], v[132:135], v[202:205], v[44:47]
	v_mfma_f32_16x16x32_bf16 v[40:43], v[152:155], v[202:205], v[40:43]
	v_mfma_f32_16x16x32_bf16 v[28:31], v[132:135], v[228:231], v[28:31]
	v_mfma_f32_16x16x32_bf16 v[24:27], v[152:155], v[228:231], v[24:27]
	v_mfma_f32_16x16x32_bf16 v[12:15], v[132:135], v[236:239], v[12:15]
	v_mfma_f32_16x16x32_bf16 v[8:11], v[152:155], v[236:239], v[8:11]
	v_mfma_f32_16x16x32_bf16 v[52:55], v[174:177], v[190:193], v[52:55]
	v_mfma_f32_16x16x32_bf16 v[48:51], v[182:185], v[190:193], v[48:51]
	v_mfma_f32_16x16x32_bf16 v[36:39], v[174:177], v[198:201], v[36:39]
	v_mfma_f32_16x16x32_bf16 v[32:35], v[182:185], v[198:201], v[32:35]
	v_mfma_f32_16x16x32_bf16 v[20:23], v[174:177], v[220:223], v[20:23]
	v_mfma_f32_16x16x32_bf16 v[16:19], v[182:185], v[220:223], v[16:19]
	v_mfma_f32_16x16x32_bf16 v[4:7], v[174:177], v[232:235], v[4:7]
	v_mfma_f32_16x16x32_bf16 v[0:3], v[182:185], v[232:235], v[0:3]
	v_mfma_f32_16x16x32_bf16 v[52:55], v[178:181], v[194:197], v[52:55]
	v_mfma_f32_16x16x32_bf16 v[48:51], v[186:189], v[194:197], v[48:51]
	v_mfma_f32_16x16x32_bf16 v[36:39], v[178:181], v[202:205], v[36:39]
	v_mfma_f32_16x16x32_bf16 v[32:35], v[186:189], v[202:205], v[32:35]
	v_mfma_f32_16x16x32_bf16 v[20:23], v[178:181], v[228:231], v[20:23]
	v_mfma_f32_16x16x32_bf16 v[16:19], v[186:189], v[228:231], v[16:19]
	v_mfma_f32_16x16x32_bf16 v[4:7], v[178:181], v[236:239], v[4:7]
	v_mfma_f32_16x16x32_bf16 v[0:3], v[186:189], v[236:239], v[0:3]
	s_barrier
	s_add_i32 s59, s59, 2
	s_add_u32 s66, s66, 0x100
	s_addc_u32 s67, s67, 0
	s_add_u32 s30, s30, 0x100
	s_addc_u32 s31, s31, 0
	s_cmp_gt_u32 s59, 5
	s_cbranch_scc0 .LBB0_858
	s_and_b64 vcc, exec, s[56:57]
	s_cbranch_vccz .LBB0_861
	s_barrier

.LBB0_975:
	s_add_u32 s29, s60, 0xfffc0080
	s_addc_u32 s30, s61, -1
	s_add_i32 s31, 0, 0x10000
	s_cmp_eq_u32 s28, 12
	s_cselect_b32 s65, s6, s30
	s_cselect_b32 s64, s7, s29
	v_add_u32_e32 v142, s31, v145
	s_cselect_b32 s63, s24, s27
	s_cselect_b32 s62, s25, s26
	s_add_i32 s29, 0, 0x14000
	ds_read_b128 v[138:141], v142
	ds_read_b128 v[148:151], v142 offset:1024
	ds_read_b128 v[152:155], v142 offset:2048
	ds_read_b128 v[156:159], v142 offset:3072
	v_add_u32_e32 v142, s29, v145
	ds_read_b128 v[174:177], v142
	ds_read_b128 v[178:181], v142 offset:1024
	ds_read_b128 v[182:185], v142 offset:2048
	ds_read_b128 v[186:189], v142 offset:3072
	v_lshl_add_u64 v[142:143], s[60:61], 0, v[134:135]
	s_add_i32 m0, s69, 0xc000
	ds_read_b128 v[190:193], v147
	ds_read_b128 v[194:197], v147 offset:1024
	ds_read_b128 v[198:201], v147 offset:2048
	ds_read_b128 v[202:205], v147 offset:3072
	ds_read_b128 v[220:223], v147 offset:4096
	ds_read_b128 v[228:231], v147 offset:5120
	ds_read_b128 v[232:235], v147 offset:6144
	ds_read_b128 v[236:239], v147 offset:7168
	global_load_lds_dwordx4 v[142:143], off
	v_lshl_add_u64 v[142:143], s[60:61], 0, v[136:137]
	s_add_i32 m0, s69, 0xe000
	s_nop 0
	global_load_lds_dwordx4 v[142:143], off
	s_waitcnt vmcnt(8)
	s_waitcnt lgkmcnt(0)
	s_barrier
	s_waitcnt lgkmcnt(0)
	v_mfma_f32_16x16x32_bf16 v[124:127], v[138:141], v[190:193], v[124:127]
	v_mfma_f32_16x16x32_bf16 v[120:123], v[152:155], v[190:193], v[120:123]
	v_mfma_f32_16x16x32_bf16 v[108:111], v[138:141], v[198:201], v[108:111]
	v_mfma_f32_16x16x32_bf16 v[104:107], v[152:155], v[198:201], v[104:107]
	v_mfma_f32_16x16x32_bf16 v[92:95], v[138:141], v[220:223], v[92:95]
	v_mfma_f32_16x16x32_bf16 v[88:91], v[152:155], v[220:223], v[88:91]
	v_mfma_f32_16x16x32_bf16 v[76:79], v[138:141], v[232:235], v[76:79]
	v_mfma_f32_16x16x32_bf16 v[72:75], v[152:155], v[232:235], v[72:75]
	v_mfma_f32_16x16x32_bf16 v[124:127], v[148:151], v[194:197], v[124:127]
	v_mfma_f32_16x16x32_bf16 v[120:123], v[156:159], v[194:197], v[120:123]
	v_mfma_f32_16x16x32_bf16 v[108:111], v[148:151], v[202:205], v[108:111]
	v_mfma_f32_16x16x32_bf16 v[104:107], v[156:159], v[202:205], v[104:107]
	v_mfma_f32_16x16x32_bf16 v[92:95], v[148:151], v[228:231], v[92:95]
	v_mfma_f32_16x16x32_bf16 v[88:91], v[156:159], v[228:231], v[88:91]
	v_mfma_f32_16x16x32_bf16 v[76:79], v[148:151], v[236:239], v[76:79]
	v_mfma_f32_16x16x32_bf16 v[72:75], v[156:159], v[236:239], v[72:75]
	v_mfma_f32_16x16x32_bf16 v[116:119], v[174:177], v[190:193], v[116:119]
	v_mfma_f32_16x16x32_bf16 v[112:115], v[182:185], v[190:193], v[112:115]
	v_mfma_f32_16x16x32_bf16 v[100:103], v[174:177], v[198:201], v[100:103]
	v_mfma_f32_16x16x32_bf16 v[96:99], v[182:185], v[198:201], v[96:99]
	v_mfma_f32_16x16x32_bf16 v[84:87], v[174:177], v[220:223], v[84:87]
	v_mfma_f32_16x16x32_bf16 v[80:83], v[182:185], v[220:223], v[80:83]
	v_mfma_f32_16x16x32_bf16 v[68:71], v[174:177], v[232:235], v[68:71]
	v_mfma_f32_16x16x32_bf16 v[64:67], v[182:185], v[232:235], v[64:67]
	v_mfma_f32_16x16x32_bf16 v[116:119], v[178:181], v[194:197], v[116:119]
	v_mfma_f32_16x16x32_bf16 v[112:115], v[186:189], v[194:197], v[112:115]
	v_mfma_f32_16x16x32_bf16 v[100:103], v[178:181], v[202:205], v[100:103]
	v_mfma_f32_16x16x32_bf16 v[96:99], v[186:189], v[202:205], v[96:99]
	v_mfma_f32_16x16x32_bf16 v[84:87], v[178:181], v[228:231], v[84:87]
	v_mfma_f32_16x16x32_bf16 v[80:83], v[186:189], v[228:231], v[80:83]
	v_mfma_f32_16x16x32_bf16 v[68:71], v[178:181], v[236:239], v[68:71]
	v_mfma_f32_16x16x32_bf16 v[64:67], v[186:189], v[236:239], v[64:67]
	s_barrier
	s_add_i32 s30, s31, s68
	v_lshl_add_u64 v[142:143], s[62:63], 0, v[162:163]
	s_mov_b32 m0, s30
	ds_read_b128 v[190:193], v147 offset:16384
	ds_read_b128 v[194:197], v147 offset:17408
	ds_read_b128 v[198:201], v147 offset:18432
	ds_read_b128 v[202:205], v147 offset:19456
	ds_read_b128 v[220:223], v147 offset:20480
	ds_read_b128 v[228:231], v147 offset:21504
	ds_read_b128 v[232:235], v147 offset:22528
	ds_read_b128 v[236:239], v147 offset:23552
	global_load_lds_dwordx4 v[142:143], off
	s_add_i32 m0, s30, 0x2000
	s_add_u32 s30, s62, 0x40000
	v_lshl_add_u64 v[240:241], s[62:63], 0, v[128:129]
	s_addc_u32 s31, s63, 0
	s_add_i32 s29, s29, s68
	global_load_lds_dwordx4 v[240:241], off
	v_lshl_add_u64 v[242:243], s[30:31], 0, v[162:163]
	s_mov_b32 m0, s29
	v_lshl_add_u64 v[244:245], s[64:65], 0, v[130:131]
	global_load_lds_dwordx4 v[242:243], off
	v_lshl_add_u64 v[242:243], s[30:31], 0, v[128:129]
	s_add_i32 m0, s29, 0x2000
	s_nop 0
	global_load_lds_dwordx4 v[242:243], off
	v_lshl_add_u64 v[242:243], s[64:65], 0, v[132:133]
	s_mov_b32 m0, s69
	s_nop 0
	global_load_lds_dwordx4 v[242:243], off
	s_mov_b32 m0, s70
	s_nop 0
	global_load_lds_dwordx4 v[244:245], off
	s_waitcnt vmcnt(8)
	s_waitcnt lgkmcnt(0)
	s_barrier
	s_waitcnt lgkmcnt(0)
	v_mfma_f32_16x16x32_bf16 v[60:63], v[138:141], v[190:193], v[60:63]
	v_mfma_f32_16x16x32_bf16 v[56:59], v[152:155], v[190:193], v[56:59]
	v_mfma_f32_16x16x32_bf16 v[44:47], v[138:141], v[198:201], v[44:47]
	v_mfma_f32_16x16x32_bf16 v[40:43], v[152:155], v[198:201], v[40:43]
	v_mfma_f32_16x16x32_bf16 v[28:31], v[138:141], v[220:223], v[28:31]
	v_mfma_f32_16x16x32_bf16 v[24:27], v[152:155], v[220:223], v[24:27]
	v_mfma_f32_16x16x32_bf16 v[12:15], v[138:141], v[232:235], v[12:15]
	v_mfma_f32_16x16x32_bf16 v[8:11], v[152:155], v[232:235], v[8:11]
	v_mfma_f32_16x16x32_bf16 v[60:63], v[148:151], v[194:197], v[60:63]
	v_mfma_f32_16x16x32_bf16 v[56:59], v[156:159], v[194:197], v[56:59]
	v_mfma_f32_16x16x32_bf16 v[44:47], v[148:151], v[202:205], v[44:47]
	v_mfma_f32_16x16x32_bf16 v[40:43], v[156:159], v[202:205], v[40:43]
	v_mfma_f32_16x16x32_bf16 v[28:31], v[148:151], v[228:231], v[28:31]
	v_mfma_f32_16x16x32_bf16 v[24:27], v[156:159], v[228:231], v[24:27]
	v_mfma_f32_16x16x32_bf16 v[12:15], v[148:151], v[236:239], v[12:15]
	v_mfma_f32_16x16x32_bf16 v[8:11], v[156:159], v[236:239], v[8:11]
	v_mfma_f32_16x16x32_bf16 v[52:55], v[174:177], v[190:193], v[52:55]
	v_mfma_f32_16x16x32_bf16 v[48:51], v[182:185], v[190:193], v[48:51]
	v_mfma_f32_16x16x32_bf16 v[36:39], v[174:177], v[198:201], v[36:39]
	v_mfma_f32_16x16x32_bf16 v[32:35], v[182:185], v[198:201], v[32:35]
	v_mfma_f32_16x16x32_bf16 v[20:23], v[174:177], v[220:223], v[20:23]
	v_mfma_f32_16x16x32_bf16 v[16:19], v[182:185], v[220:223], v[16:19]
	v_mfma_f32_16x16x32_bf16 v[4:7], v[174:177], v[232:235], v[4:7]
	v_mfma_f32_16x16x32_bf16 v[0:3], v[182:185], v[232:235], v[0:3]
	v_mfma_f32_16x16x32_bf16 v[52:55], v[178:181], v[194:197], v[52:55]
	v_mfma_f32_16x16x32_bf16 v[48:51], v[186:189], v[194:197], v[48:51]
	v_mfma_f32_16x16x32_bf16 v[36:39], v[178:181], v[202:205], v[36:39]
	v_mfma_f32_16x16x32_bf16 v[32:35], v[186:189], v[202:205], v[32:35]
	v_mfma_f32_16x16x32_bf16 v[20:23], v[178:181], v[228:231], v[20:23]
	v_mfma_f32_16x16x32_bf16 v[16:19], v[186:189], v[228:231], v[16:19]
	v_mfma_f32_16x16x32_bf16 v[4:7], v[178:181], v[236:239], v[4:7]
	v_mfma_f32_16x16x32_bf16 v[0:3], v[186:189], v[236:239], v[0:3]
	s_barrier
	s_add_i32 s29, 0, 0x18000
	s_add_i32 s53, 0, 0x1c000
	v_add_u32_e32 v156, s29, v145
	v_add_u32_e32 v186, s53, v145
	ds_read_b128 v[138:141], v156
	ds_read_b128 v[148:151], v156 offset:1024
	ds_read_b128 v[152:155], v156 offset:2048
	ds_read_b128 v[156:159], v156 offset:3072
	ds_read_b128 v[174:177], v186
	ds_read_b128 v[178:181], v186 offset:1024
	ds_read_b128 v[182:185], v186 offset:2048
	ds_read_b128 v[186:189], v186 offset:3072
	s_add_u32 s30, s64, 0x40000
	s_addc_u32 s31, s65, 0
	s_mov_b32 m0, s71
	v_lshl_add_u64 v[246:247], s[30:31], 0, v[132:133]
	ds_read_b128 v[190:193], v147 offset:32768
	ds_read_b128 v[194:197], v147 offset:33792
	ds_read_b128 v[198:201], v147 offset:34816
	ds_read_b128 v[202:205], v147 offset:35840
	ds_read_b128 v[220:223], v147 offset:36864
	ds_read_b128 v[228:231], v147 offset:37888
	ds_read_b128 v[232:235], v147 offset:38912
	ds_read_b128 v[236:239], v147 offset:39936
	global_load_lds_dwordx4 v[246:247], off
	v_lshl_add_u64 v[246:247], s[30:31], 0, v[130:131]
	s_mov_b32 m0, s72
	s_nop 0
	global_load_lds_dwordx4 v[246:247], off
	s_waitcnt vmcnt(8)
	s_waitcnt lgkmcnt(0)
	s_barrier
	s_waitcnt lgkmcnt(0)
	v_mfma_f32_16x16x32_bf16 v[124:127], v[138:141], v[190:193], v[124:127]
	v_mfma_f32_16x16x32_bf16 v[120:123], v[152:155], v[190:193], v[120:123]
	v_mfma_f32_16x16x32_bf16 v[108:111], v[138:141], v[198:201], v[108:111]
	v_mfma_f32_16x16x32_bf16 v[104:107], v[152:155], v[198:201], v[104:107]
	v_mfma_f32_16x16x32_bf16 v[92:95], v[138:141], v[220:223], v[92:95]
	v_mfma_f32_16x16x32_bf16 v[88:91], v[152:155], v[220:223], v[88:91]
	v_mfma_f32_16x16x32_bf16 v[76:79], v[138:141], v[232:235], v[76:79]
	v_mfma_f32_16x16x32_bf16 v[72:75], v[152:155], v[232:235], v[72:75]
	v_mfma_f32_16x16x32_bf16 v[124:127], v[148:151], v[194:197], v[124:127]
	v_mfma_f32_16x16x32_bf16 v[120:123], v[156:159], v[194:197], v[120:123]
	v_mfma_f32_16x16x32_bf16 v[108:111], v[148:151], v[202:205], v[108:111]
	v_mfma_f32_16x16x32_bf16 v[104:107], v[156:159], v[202:205], v[104:107]
	v_mfma_f32_16x16x32_bf16 v[92:95], v[148:151], v[228:231], v[92:95]
	v_mfma_f32_16x16x32_bf16 v[88:91], v[156:159], v[228:231], v[88:91]
	v_mfma_f32_16x16x32_bf16 v[76:79], v[148:151], v[236:239], v[76:79]
	v_mfma_f32_16x16x32_bf16 v[72:75], v[156:159], v[236:239], v[72:75]
	v_mfma_f32_16x16x32_bf16 v[116:119], v[174:177], v[190:193], v[116:119]
	v_mfma_f32_16x16x32_bf16 v[112:115], v[182:185], v[190:193], v[112:115]
	v_mfma_f32_16x16x32_bf16 v[100:103], v[174:177], v[198:201], v[100:103]
	v_mfma_f32_16x16x32_bf16 v[96:99], v[182:185], v[198:201], v[96:99]
	v_mfma_f32_16x16x32_bf16 v[84:87], v[174:177], v[220:223], v[84:87]
	v_mfma_f32_16x16x32_bf16 v[80:83], v[182:185], v[220:223], v[80:83]
	v_mfma_f32_16x16x32_bf16 v[68:71], v[174:177], v[232:235], v[68:71]
	v_mfma_f32_16x16x32_bf16 v[64:67], v[182:185], v[232:235], v[64:67]
	v_mfma_f32_16x16x32_bf16 v[116:119], v[178:181], v[194:197], v[116:119]
	v_mfma_f32_16x16x32_bf16 v[112:115], v[186:189], v[194:197], v[112:115]
	v_mfma_f32_16x16x32_bf16 v[100:103], v[178:181], v[202:205], v[100:103]
	v_mfma_f32_16x16x32_bf16 v[96:99], v[186:189], v[202:205], v[96:99]
	v_mfma_f32_16x16x32_bf16 v[84:87], v[178:181], v[228:231], v[84:87]
	v_mfma_f32_16x16x32_bf16 v[80:83], v[186:189], v[228:231], v[80:83]
	v_mfma_f32_16x16x32_bf16 v[68:71], v[178:181], v[236:239], v[68:71]
	v_mfma_f32_16x16x32_bf16 v[64:67], v[186:189], v[236:239], v[64:67]
	s_barrier
	s_add_i32 s29, s29, s68
	v_lshl_add_u64 v[142:143], v[142:143], 0, s[4:5]
	s_mov_b32 m0, s29
	ds_read_b128 v[190:193], v147 offset:49152
	ds_read_b128 v[194:197], v147 offset:50176
	ds_read_b128 v[198:201], v147 offset:51200
	ds_read_b128 v[202:205], v147 offset:52224
	ds_read_b128 v[220:223], v147 offset:53248
	ds_read_b128 v[228:231], v147 offset:54272
	ds_read_b128 v[232:235], v147 offset:55296
	ds_read_b128 v[236:239], v147 offset:56320
	global_load_lds_dwordx4 v[142:143], off
	s_add_i32 m0, s29, 0x2000
	s_add_u32 s30, s62, 0x40080
	v_lshl_add_u64 v[142:143], v[240:241], 0, s[4:5]
	s_addc_u32 s31, s63, 0
	s_add_i32 s29, s53, s68
	global_load_lds_dwordx4 v[142:143], off
	v_lshl_add_u64 v[142:143], s[30:31], 0, v[162:163]
	s_mov_b32 m0, s29
	s_nop 0
	global_load_lds_dwordx4 v[142:143], off
	v_lshl_add_u64 v[142:143], s[30:31], 0, v[128:129]
	s_add_i32 m0, s29, 0x2000
	s_nop 0
	global_load_lds_dwordx4 v[142:143], off
	v_lshl_add_u64 v[142:143], v[242:243], 0, s[4:5]
	s_mov_b32 m0, s74
	s_nop 0
	global_load_lds_dwordx4 v[142:143], off
	v_lshl_add_u64 v[142:143], v[244:245], 0, s[4:5]
	s_mov_b32 m0, s75
	s_nop 0
	global_load_lds_dwordx4 v[142:143], off
	s_waitcnt vmcnt(8)
	s_waitcnt lgkmcnt(0)
	s_barrier
	s_waitcnt lgkmcnt(0)
	v_mfma_f32_16x16x32_bf16 v[60:63], v[138:141], v[190:193], v[60:63]
	v_mfma_f32_16x16x32_bf16 v[56:59], v[152:155], v[190:193], v[56:59]
	v_mfma_f32_16x16x32_bf16 v[44:47], v[138:141], v[198:201], v[44:47]
	v_mfma_f32_16x16x32_bf16 v[40:43], v[152:155], v[198:201], v[40:43]
	v_mfma_f32_16x16x32_bf16 v[28:31], v[138:141], v[220:223], v[28:31]
	v_mfma_f32_16x16x32_bf16 v[24:27], v[152:155], v[220:223], v[24:27]
	v_mfma_f32_16x16x32_bf16 v[12:15], v[138:141], v[232:235], v[12:15]
	v_mfma_f32_16x16x32_bf16 v[8:11], v[152:155], v[232:235], v[8:11]
	v_mfma_f32_16x16x32_bf16 v[60:63], v[148:151], v[194:197], v[60:63]
	v_mfma_f32_16x16x32_bf16 v[56:59], v[156:159], v[194:197], v[56:59]
	v_mfma_f32_16x16x32_bf16 v[44:47], v[148:151], v[202:205], v[44:47]
	v_mfma_f32_16x16x32_bf16 v[40:43], v[156:159], v[202:205], v[40:43]
	v_mfma_f32_16x16x32_bf16 v[28:31], v[148:151], v[228:231], v[28:31]
	v_mfma_f32_16x16x32_bf16 v[24:27], v[156:159], v[228:231], v[24:27]
	v_mfma_f32_16x16x32_bf16 v[12:15], v[148:151], v[236:239], v[12:15]
	v_mfma_f32_16x16x32_bf16 v[8:11], v[156:159], v[236:239], v[8:11]
	v_mfma_f32_16x16x32_bf16 v[52:55], v[174:177], v[190:193], v[52:55]
	v_mfma_f32_16x16x32_bf16 v[48:51], v[182:185], v[190:193], v[48:51]
	v_mfma_f32_16x16x32_bf16 v[36:39], v[174:177], v[198:201], v[36:39]
	v_mfma_f32_16x16x32_bf16 v[32:35], v[182:185], v[198:201], v[32:35]
	v_mfma_f32_16x16x32_bf16 v[20:23], v[174:177], v[220:223], v[20:23]
	v_mfma_f32_16x16x32_bf16 v[16:19], v[182:185], v[220:223], v[16:19]
	v_mfma_f32_16x16x32_bf16 v[4:7], v[174:177], v[232:235], v[4:7]
	v_mfma_f32_16x16x32_bf16 v[0:3], v[182:185], v[232:235], v[0:3]
	v_mfma_f32_16x16x32_bf16 v[52:55], v[178:181], v[194:197], v[52:55]
	v_mfma_f32_16x16x32_bf16 v[48:51], v[186:189], v[194:197], v[48:51]
	v_mfma_f32_16x16x32_bf16 v[36:39], v[178:181], v[202:205], v[36:39]
	v_mfma_f32_16x16x32_bf16 v[32:35], v[186:189], v[202:205], v[32:35]
	v_mfma_f32_16x16x32_bf16 v[20:23], v[178:181], v[228:231], v[20:23]
	v_mfma_f32_16x16x32_bf16 v[16:19], v[186:189], v[228:231], v[16:19]
	v_mfma_f32_16x16x32_bf16 v[4:7], v[178:181], v[236:239], v[4:7]
	v_mfma_f32_16x16x32_bf16 v[0:3], v[186:189], v[236:239], v[0:3]
	s_barrier
	s_add_i32 s28, s28, 2
	s_add_u32 s60, s60, 0x100
	s_addc_u32 s61, s61, 0
	s_add_u32 s26, s26, 0x100
	s_addc_u32 s27, s27, 0
	s_cmp_gt_u32 s28, 13
	s_cbranch_scc0 .LBB0_975
	s_and_b64 vcc, exec, s[50:51]
	s_cbranch_vccz .LBB0_978
	s_barrier

.LBB0_1066:
	s_add_u32 s29, s58, 0xfffc0080
	s_addc_u32 s30, s59, -1
	s_add_i32 s31, 0, 0x10000
	s_cmp_eq_u32 s28, 12
	s_cselect_b32 s63, s6, s30
	s_cselect_b32 s62, s7, s29
	v_add_u32_e32 v142, s31, v144
	s_cselect_b32 s61, s24, s27
	s_cselect_b32 s60, s25, s26
	s_add_i32 s29, 0, 0x14000
	ds_read_b128 v[138:141], v142
	ds_read_b128 v[148:151], v142 offset:1024
	ds_read_b128 v[152:155], v142 offset:2048
	ds_read_b128 v[156:159], v142 offset:3072
	v_add_u32_e32 v142, s29, v144
	ds_read_b128 v[174:177], v142
	ds_read_b128 v[178:181], v142 offset:1024
	ds_read_b128 v[182:185], v142 offset:2048
	ds_read_b128 v[186:189], v142 offset:3072
	v_lshl_add_u64 v[240:241], s[58:59], 0, v[134:135]
	s_add_i32 m0, s67, 0xc000
	ds_read_b128 v[190:193], v146
	ds_read_b128 v[194:197], v146 offset:1024
	ds_read_b128 v[198:201], v146 offset:2048
	ds_read_b128 v[202:205], v146 offset:3072
	ds_read_b128 v[220:223], v146 offset:4096
	ds_read_b128 v[228:231], v146 offset:5120
	ds_read_b128 v[232:235], v146 offset:6144
	ds_read_b128 v[236:239], v146 offset:7168
	global_load_lds_dwordx4 v[240:241], off
	v_lshl_add_u64 v[240:241], s[58:59], 0, v[136:137]
	s_add_i32 m0, s67, 0xe000
	s_nop 0
	global_load_lds_dwordx4 v[240:241], off
	s_waitcnt vmcnt(8)
	s_waitcnt lgkmcnt(0)
	s_barrier
	s_waitcnt lgkmcnt(0)
	v_mfma_f32_16x16x32_bf16 v[124:127], v[138:141], v[190:193], v[124:127]
	v_mfma_f32_16x16x32_bf16 v[120:123], v[152:155], v[190:193], v[120:123]
	v_mfma_f32_16x16x32_bf16 v[108:111], v[138:141], v[198:201], v[108:111]
	v_mfma_f32_16x16x32_bf16 v[104:107], v[152:155], v[198:201], v[104:107]
	v_mfma_f32_16x16x32_bf16 v[92:95], v[138:141], v[220:223], v[92:95]
	v_mfma_f32_16x16x32_bf16 v[88:91], v[152:155], v[220:223], v[88:91]
	v_mfma_f32_16x16x32_bf16 v[76:79], v[138:141], v[232:235], v[76:79]
	v_mfma_f32_16x16x32_bf16 v[72:75], v[152:155], v[232:235], v[72:75]
	v_mfma_f32_16x16x32_bf16 v[124:127], v[148:151], v[194:197], v[124:127]
	v_mfma_f32_16x16x32_bf16 v[120:123], v[156:159], v[194:197], v[120:123]
	v_mfma_f32_16x16x32_bf16 v[108:111], v[148:151], v[202:205], v[108:111]
	v_mfma_f32_16x16x32_bf16 v[104:107], v[156:159], v[202:205], v[104:107]
	v_mfma_f32_16x16x32_bf16 v[92:95], v[148:151], v[228:231], v[92:95]
	v_mfma_f32_16x16x32_bf16 v[88:91], v[156:159], v[228:231], v[88:91]
	v_mfma_f32_16x16x32_bf16 v[76:79], v[148:151], v[236:239], v[76:79]
	v_mfma_f32_16x16x32_bf16 v[72:75], v[156:159], v[236:239], v[72:75]
	v_mfma_f32_16x16x32_bf16 v[116:119], v[174:177], v[190:193], v[116:119]
	v_mfma_f32_16x16x32_bf16 v[112:115], v[182:185], v[190:193], v[112:115]
	v_mfma_f32_16x16x32_bf16 v[100:103], v[174:177], v[198:201], v[100:103]
	v_mfma_f32_16x16x32_bf16 v[96:99], v[182:185], v[198:201], v[96:99]
	v_mfma_f32_16x16x32_bf16 v[84:87], v[174:177], v[220:223], v[84:87]
	v_mfma_f32_16x16x32_bf16 v[80:83], v[182:185], v[220:223], v[80:83]
	v_mfma_f32_16x16x32_bf16 v[68:71], v[174:177], v[232:235], v[68:71]
	v_mfma_f32_16x16x32_bf16 v[64:67], v[182:185], v[232:235], v[64:67]
	v_mfma_f32_16x16x32_bf16 v[116:119], v[178:181], v[194:197], v[116:119]
	v_mfma_f32_16x16x32_bf16 v[112:115], v[186:189], v[194:197], v[112:115]
	v_mfma_f32_16x16x32_bf16 v[100:103], v[178:181], v[202:205], v[100:103]
	v_mfma_f32_16x16x32_bf16 v[96:99], v[186:189], v[202:205], v[96:99]
	v_mfma_f32_16x16x32_bf16 v[84:87], v[178:181], v[228:231], v[84:87]
	v_mfma_f32_16x16x32_bf16 v[80:83], v[186:189], v[228:231], v[80:83]
	v_mfma_f32_16x16x32_bf16 v[68:71], v[178:181], v[236:239], v[68:71]
	v_mfma_f32_16x16x32_bf16 v[64:67], v[186:189], v[236:239], v[64:67]
	s_barrier
	s_add_i32 s30, s31, s66
	v_lshl_add_u64 v[240:241], s[60:61], 0, v[162:163]
	s_mov_b32 m0, s30
	ds_read_b128 v[190:193], v146 offset:16384
	ds_read_b128 v[194:197], v146 offset:17408
	ds_read_b128 v[198:201], v146 offset:18432
	ds_read_b128 v[202:205], v146 offset:19456
	ds_read_b128 v[220:223], v146 offset:20480
	ds_read_b128 v[228:231], v146 offset:21504
	ds_read_b128 v[232:235], v146 offset:22528
	ds_read_b128 v[236:239], v146 offset:23552
	global_load_lds_dwordx4 v[240:241], off
	s_add_i32 m0, s30, 0x2000
	s_add_u32 s30, s60, 0x40000
	v_lshl_add_u64 v[242:243], s[60:61], 0, v[128:129]
	s_addc_u32 s31, s61, 0
	s_add_i32 s29, s29, s66
	global_load_lds_dwordx4 v[242:243], off
	v_lshl_add_u64 v[244:245], s[30:31], 0, v[162:163]
	s_mov_b32 m0, s29
	v_lshl_add_u64 v[246:247], s[62:63], 0, v[130:131]
	global_load_lds_dwordx4 v[244:245], off
	v_lshl_add_u64 v[244:245], s[30:31], 0, v[128:129]
	s_add_i32 m0, s29, 0x2000
	s_nop 0
	global_load_lds_dwordx4 v[244:245], off
	v_lshl_add_u64 v[244:245], s[62:63], 0, v[132:133]
	s_mov_b32 m0, s67
	s_nop 0
	global_load_lds_dwordx4 v[244:245], off
	s_mov_b32 m0, s68
	s_nop 0
	global_load_lds_dwordx4 v[246:247], off
	s_waitcnt vmcnt(8)
	s_waitcnt lgkmcnt(0)
	s_barrier
	s_waitcnt lgkmcnt(0)
	v_mfma_f32_16x16x32_bf16 v[60:63], v[138:141], v[190:193], v[60:63]
	v_mfma_f32_16x16x32_bf16 v[56:59], v[152:155], v[190:193], v[56:59]
	v_mfma_f32_16x16x32_bf16 v[44:47], v[138:141], v[198:201], v[44:47]
	v_mfma_f32_16x16x32_bf16 v[40:43], v[152:155], v[198:201], v[40:43]
	v_mfma_f32_16x16x32_bf16 v[28:31], v[138:141], v[220:223], v[28:31]
	v_mfma_f32_16x16x32_bf16 v[24:27], v[152:155], v[220:223], v[24:27]
	v_mfma_f32_16x16x32_bf16 v[12:15], v[138:141], v[232:235], v[12:15]
	v_mfma_f32_16x16x32_bf16 v[8:11], v[152:155], v[232:235], v[8:11]
	v_mfma_f32_16x16x32_bf16 v[60:63], v[148:151], v[194:197], v[60:63]
	v_mfma_f32_16x16x32_bf16 v[56:59], v[156:159], v[194:197], v[56:59]
	v_mfma_f32_16x16x32_bf16 v[44:47], v[148:151], v[202:205], v[44:47]
	v_mfma_f32_16x16x32_bf16 v[40:43], v[156:159], v[202:205], v[40:43]
	v_mfma_f32_16x16x32_bf16 v[28:31], v[148:151], v[228:231], v[28:31]
	v_mfma_f32_16x16x32_bf16 v[24:27], v[156:159], v[228:231], v[24:27]
	v_mfma_f32_16x16x32_bf16 v[12:15], v[148:151], v[236:239], v[12:15]
	v_mfma_f32_16x16x32_bf16 v[8:11], v[156:159], v[236:239], v[8:11]
	v_mfma_f32_16x16x32_bf16 v[52:55], v[174:177], v[190:193], v[52:55]
	v_mfma_f32_16x16x32_bf16 v[48:51], v[182:185], v[190:193], v[48:51]
	v_mfma_f32_16x16x32_bf16 v[36:39], v[174:177], v[198:201], v[36:39]
	v_mfma_f32_16x16x32_bf16 v[32:35], v[182:185], v[198:201], v[32:35]
	v_mfma_f32_16x16x32_bf16 v[20:23], v[174:177], v[220:223], v[20:23]
	v_mfma_f32_16x16x32_bf16 v[16:19], v[182:185], v[220:223], v[16:19]
	v_mfma_f32_16x16x32_bf16 v[4:7], v[174:177], v[232:235], v[4:7]
	v_mfma_f32_16x16x32_bf16 v[0:3], v[182:185], v[232:235], v[0:3]
	v_mfma_f32_16x16x32_bf16 v[52:55], v[178:181], v[194:197], v[52:55]
	v_mfma_f32_16x16x32_bf16 v[48:51], v[186:189], v[194:197], v[48:51]
	v_mfma_f32_16x16x32_bf16 v[36:39], v[178:181], v[202:205], v[36:39]
	v_mfma_f32_16x16x32_bf16 v[32:35], v[186:189], v[202:205], v[32:35]
	v_mfma_f32_16x16x32_bf16 v[20:23], v[178:181], v[228:231], v[20:23]
	v_mfma_f32_16x16x32_bf16 v[16:19], v[186:189], v[228:231], v[16:19]
	v_mfma_f32_16x16x32_bf16 v[4:7], v[178:181], v[236:239], v[4:7]
	v_mfma_f32_16x16x32_bf16 v[0:3], v[186:189], v[236:239], v[0:3]
	s_barrier
	s_add_i32 s29, 0, 0x18000
	v_add_u32_e32 v142, s29, v144
	s_add_i32 s51, 0, 0x1c000
	ds_read_b128 v[138:141], v142
	ds_read_b128 v[148:151], v142 offset:1024
	ds_read_b128 v[152:155], v142 offset:2048
	ds_read_b128 v[156:159], v142 offset:3072
	v_add_u32_e32 v142, s51, v144
	ds_read_b128 v[174:177], v142
	ds_read_b128 v[178:181], v142 offset:1024
	ds_read_b128 v[182:185], v142 offset:2048
	ds_read_b128 v[186:189], v142 offset:3072
	s_add_u32 s30, s62, 0x40000
	s_addc_u32 s31, s63, 0
	s_mov_b32 m0, s69
	v_lshl_add_u64 v[248:249], s[30:31], 0, v[132:133]
	ds_read_b128 v[190:193], v146 offset:32768
	ds_read_b128 v[194:197], v146 offset:33792
	ds_read_b128 v[198:201], v146 offset:34816
	ds_read_b128 v[202:205], v146 offset:35840
	ds_read_b128 v[220:223], v146 offset:36864
	ds_read_b128 v[228:231], v146 offset:37888
	ds_read_b128 v[232:235], v146 offset:38912
	ds_read_b128 v[236:239], v146 offset:39936
	global_load_lds_dwordx4 v[248:249], off
	v_lshl_add_u64 v[248:249], s[30:31], 0, v[130:131]
	s_mov_b32 m0, s70
	s_nop 0
	global_load_lds_dwordx4 v[248:249], off
	s_waitcnt vmcnt(8)
	s_waitcnt lgkmcnt(0)
	s_barrier
	s_waitcnt lgkmcnt(0)
	v_mfma_f32_16x16x32_bf16 v[124:127], v[138:141], v[190:193], v[124:127]
	v_mfma_f32_16x16x32_bf16 v[120:123], v[152:155], v[190:193], v[120:123]
	v_mfma_f32_16x16x32_bf16 v[108:111], v[138:141], v[198:201], v[108:111]
	v_mfma_f32_16x16x32_bf16 v[104:107], v[152:155], v[198:201], v[104:107]
	v_mfma_f32_16x16x32_bf16 v[92:95], v[138:141], v[220:223], v[92:95]
	v_mfma_f32_16x16x32_bf16 v[88:91], v[152:155], v[220:223], v[88:91]
	v_mfma_f32_16x16x32_bf16 v[76:79], v[138:141], v[232:235], v[76:79]
	v_mfma_f32_16x16x32_bf16 v[72:75], v[152:155], v[232:235], v[72:75]
	v_mfma_f32_16x16x32_bf16 v[124:127], v[148:151], v[194:197], v[124:127]
	v_mfma_f32_16x16x32_bf16 v[120:123], v[156:159], v[194:197], v[120:123]
	v_mfma_f32_16x16x32_bf16 v[108:111], v[148:151], v[202:205], v[108:111]
	v_mfma_f32_16x16x32_bf16 v[104:107], v[156:159], v[202:205], v[104:107]
	v_mfma_f32_16x16x32_bf16 v[92:95], v[148:151], v[228:231], v[92:95]
	v_mfma_f32_16x16x32_bf16 v[88:91], v[156:159], v[228:231], v[88:91]
	v_mfma_f32_16x16x32_bf16 v[76:79], v[148:151], v[236:239], v[76:79]
	v_mfma_f32_16x16x32_bf16 v[72:75], v[156:159], v[236:239], v[72:75]
	v_mfma_f32_16x16x32_bf16 v[116:119], v[174:177], v[190:193], v[116:119]
	v_mfma_f32_16x16x32_bf16 v[112:115], v[182:185], v[190:193], v[112:115]
	v_mfma_f32_16x16x32_bf16 v[100:103], v[174:177], v[198:201], v[100:103]
	v_mfma_f32_16x16x32_bf16 v[96:99], v[182:185], v[198:201], v[96:99]
	v_mfma_f32_16x16x32_bf16 v[84:87], v[174:177], v[220:223], v[84:87]
	v_mfma_f32_16x16x32_bf16 v[80:83], v[182:185], v[220:223], v[80:83]
	v_mfma_f32_16x16x32_bf16 v[68:71], v[174:177], v[232:235], v[68:71]
	v_mfma_f32_16x16x32_bf16 v[64:67], v[182:185], v[232:235], v[64:67]
	v_mfma_f32_16x16x32_bf16 v[116:119], v[178:181], v[194:197], v[116:119]
	v_mfma_f32_16x16x32_bf16 v[112:115], v[186:189], v[194:197], v[112:115]
	v_mfma_f32_16x16x32_bf16 v[100:103], v[178:181], v[202:205], v[100:103]
	v_mfma_f32_16x16x32_bf16 v[96:99], v[186:189], v[202:205], v[96:99]
	v_mfma_f32_16x16x32_bf16 v[84:87], v[178:181], v[228:231], v[84:87]
	v_mfma_f32_16x16x32_bf16 v[80:83], v[186:189], v[228:231], v[80:83]
	v_mfma_f32_16x16x32_bf16 v[68:71], v[178:181], v[236:239], v[68:71]
	v_mfma_f32_16x16x32_bf16 v[64:67], v[186:189], v[236:239], v[64:67]
	s_barrier
	s_add_i32 s29, s29, s66
	v_lshl_add_u64 v[240:241], v[240:241], 0, s[4:5]
	s_mov_b32 m0, s29
	ds_read_b128 v[190:193], v146 offset:49152
	ds_read_b128 v[194:197], v146 offset:50176
	ds_read_b128 v[198:201], v146 offset:51200
	ds_read_b128 v[202:205], v146 offset:52224
	ds_read_b128 v[220:223], v146 offset:53248
	ds_read_b128 v[228:231], v146 offset:54272
	ds_read_b128 v[232:235], v146 offset:55296
	ds_read_b128 v[236:239], v146 offset:56320
	global_load_lds_dwordx4 v[240:241], off
	s_add_i32 m0, s29, 0x2000
	s_add_u32 s30, s60, 0x40080
	v_lshl_add_u64 v[240:241], v[242:243], 0, s[4:5]
	s_addc_u32 s31, s61, 0
	s_add_i32 s29, s51, s66
	global_load_lds_dwordx4 v[240:241], off
	v_lshl_add_u64 v[240:241], s[30:31], 0, v[162:163]
	s_mov_b32 m0, s29
	s_nop 0
	global_load_lds_dwordx4 v[240:241], off
	v_lshl_add_u64 v[240:241], s[30:31], 0, v[128:129]
	s_add_i32 m0, s29, 0x2000
	s_nop 0
	global_load_lds_dwordx4 v[240:241], off
	v_lshl_add_u64 v[240:241], v[244:245], 0, s[4:5]
	s_mov_b32 m0, s71
	s_nop 0
	global_load_lds_dwordx4 v[240:241], off
	v_lshl_add_u64 v[240:241], v[246:247], 0, s[4:5]
	s_mov_b32 m0, s72
	s_nop 0
	global_load_lds_dwordx4 v[240:241], off
	s_waitcnt vmcnt(8)
	s_waitcnt lgkmcnt(0)
	s_barrier
	s_waitcnt lgkmcnt(0)
	v_mfma_f32_16x16x32_bf16 v[60:63], v[138:141], v[190:193], v[60:63]
	v_mfma_f32_16x16x32_bf16 v[56:59], v[152:155], v[190:193], v[56:59]
	v_mfma_f32_16x16x32_bf16 v[44:47], v[138:141], v[198:201], v[44:47]
	v_mfma_f32_16x16x32_bf16 v[40:43], v[152:155], v[198:201], v[40:43]
	v_mfma_f32_16x16x32_bf16 v[28:31], v[138:141], v[220:223], v[28:31]
	v_mfma_f32_16x16x32_bf16 v[24:27], v[152:155], v[220:223], v[24:27]
	v_mfma_f32_16x16x32_bf16 v[12:15], v[138:141], v[232:235], v[12:15]
	v_mfma_f32_16x16x32_bf16 v[8:11], v[152:155], v[232:235], v[8:11]
	v_mfma_f32_16x16x32_bf16 v[60:63], v[148:151], v[194:197], v[60:63]
	v_mfma_f32_16x16x32_bf16 v[56:59], v[156:159], v[194:197], v[56:59]
	v_mfma_f32_16x16x32_bf16 v[44:47], v[148:151], v[202:205], v[44:47]
	v_mfma_f32_16x16x32_bf16 v[40:43], v[156:159], v[202:205], v[40:43]
	v_mfma_f32_16x16x32_bf16 v[28:31], v[148:151], v[228:231], v[28:31]
	v_mfma_f32_16x16x32_bf16 v[24:27], v[156:159], v[228:231], v[24:27]
	v_mfma_f32_16x16x32_bf16 v[12:15], v[148:151], v[236:239], v[12:15]
	v_mfma_f32_16x16x32_bf16 v[8:11], v[156:159], v[236:239], v[8:11]
	v_mfma_f32_16x16x32_bf16 v[52:55], v[174:177], v[190:193], v[52:55]
	v_mfma_f32_16x16x32_bf16 v[48:51], v[182:185], v[190:193], v[48:51]
	v_mfma_f32_16x16x32_bf16 v[36:39], v[174:177], v[198:201], v[36:39]
	v_mfma_f32_16x16x32_bf16 v[32:35], v[182:185], v[198:201], v[32:35]
	v_mfma_f32_16x16x32_bf16 v[20:23], v[174:177], v[220:223], v[20:23]
	v_mfma_f32_16x16x32_bf16 v[16:19], v[182:185], v[220:223], v[16:19]
	v_mfma_f32_16x16x32_bf16 v[4:7], v[174:177], v[232:235], v[4:7]
	v_mfma_f32_16x16x32_bf16 v[0:3], v[182:185], v[232:235], v[0:3]
	v_mfma_f32_16x16x32_bf16 v[52:55], v[178:181], v[194:197], v[52:55]
	v_mfma_f32_16x16x32_bf16 v[48:51], v[186:189], v[194:197], v[48:51]
	v_mfma_f32_16x16x32_bf16 v[36:39], v[178:181], v[202:205], v[36:39]
	v_mfma_f32_16x16x32_bf16 v[32:35], v[186:189], v[202:205], v[32:35]
	v_mfma_f32_16x16x32_bf16 v[20:23], v[178:181], v[228:231], v[20:23]
	v_mfma_f32_16x16x32_bf16 v[16:19], v[186:189], v[228:231], v[16:19]
	v_mfma_f32_16x16x32_bf16 v[4:7], v[178:181], v[236:239], v[4:7]
	v_mfma_f32_16x16x32_bf16 v[0:3], v[186:189], v[236:239], v[0:3]
	s_barrier
	s_add_i32 s28, s28, 2
	s_add_u32 s58, s58, 0x100
	s_addc_u32 s59, s59, 0
	s_add_u32 s26, s26, 0x100
	s_addc_u32 s27, s27, 0
	s_cmp_gt_u32 s28, 13
	s_cbranch_scc0 .LBB0_1066
	s_and_b64 vcc, exec, s[48:49]
	s_cbranch_vccz .LBB0_1069
	s_barrier

.LBB0_1280:
	s_add_u32 s60, s58, 0x100
	s_addc_u32 s61, s59, 0
	s_add_i32 s25, 0, 0x10000
	s_cmp_eq_u32 s24, 40
	s_cselect_b32 s65, s45, s61
	s_cselect_b32 s64, s44, s60
	v_add_u32_e32 v142, s25, v145
	s_cselect_b32 s63, s57, s7
	s_cselect_b32 s62, s56, s6
	s_add_i32 s28, 0, 0x14000
	ds_read_b128 v[138:141], v142
	ds_read_b128 v[148:151], v142 offset:1024
	ds_read_b128 v[152:155], v142 offset:2048
	ds_read_b128 v[156:159], v142 offset:3072
	v_add_u32_e32 v142, s28, v145
	ds_read_b128 v[174:177], v142
	ds_read_b128 v[178:181], v142 offset:1024
	ds_read_b128 v[182:185], v142 offset:2048
	ds_read_b128 v[186:189], v142 offset:3072
	v_lshl_add_u64 v[142:143], s[58:59], 0, v[134:135]
	s_add_i32 m0, s68, 0xc000
	ds_read_b128 v[190:193], v147
	ds_read_b128 v[194:197], v147 offset:1024
	ds_read_b128 v[198:201], v147 offset:2048
	ds_read_b128 v[202:205], v147 offset:3072
	ds_read_b128 v[220:223], v147 offset:4096
	ds_read_b128 v[228:231], v147 offset:5120
	ds_read_b128 v[232:235], v147 offset:6144
	ds_read_b128 v[236:239], v147 offset:7168
	global_load_lds_dwordx4 v[142:143], off
	v_lshl_add_u64 v[142:143], s[58:59], 0, v[136:137]
	s_add_i32 m0, s68, 0xe000
	s_nop 0
	global_load_lds_dwordx4 v[142:143], off
	s_waitcnt vmcnt(8)
	s_waitcnt lgkmcnt(0)
	s_barrier
	s_waitcnt lgkmcnt(0)
	v_mfma_f32_16x16x32_bf16 v[124:127], v[138:141], v[190:193], v[124:127]
	v_mfma_f32_16x16x32_bf16 v[120:123], v[152:155], v[190:193], v[120:123]
	v_mfma_f32_16x16x32_bf16 v[108:111], v[138:141], v[198:201], v[108:111]
	v_mfma_f32_16x16x32_bf16 v[104:107], v[152:155], v[198:201], v[104:107]
	v_mfma_f32_16x16x32_bf16 v[92:95], v[138:141], v[220:223], v[92:95]
	v_mfma_f32_16x16x32_bf16 v[88:91], v[152:155], v[220:223], v[88:91]
	v_mfma_f32_16x16x32_bf16 v[76:79], v[138:141], v[232:235], v[76:79]
	v_mfma_f32_16x16x32_bf16 v[72:75], v[152:155], v[232:235], v[72:75]
	v_mfma_f32_16x16x32_bf16 v[124:127], v[148:151], v[194:197], v[124:127]
	v_mfma_f32_16x16x32_bf16 v[120:123], v[156:159], v[194:197], v[120:123]
	v_mfma_f32_16x16x32_bf16 v[108:111], v[148:151], v[202:205], v[108:111]
	v_mfma_f32_16x16x32_bf16 v[104:107], v[156:159], v[202:205], v[104:107]
	v_mfma_f32_16x16x32_bf16 v[92:95], v[148:151], v[228:231], v[92:95]
	v_mfma_f32_16x16x32_bf16 v[88:91], v[156:159], v[228:231], v[88:91]
	v_mfma_f32_16x16x32_bf16 v[76:79], v[148:151], v[236:239], v[76:79]
	v_mfma_f32_16x16x32_bf16 v[72:75], v[156:159], v[236:239], v[72:75]
	v_mfma_f32_16x16x32_bf16 v[116:119], v[174:177], v[190:193], v[116:119]
	v_mfma_f32_16x16x32_bf16 v[112:115], v[182:185], v[190:193], v[112:115]
	v_mfma_f32_16x16x32_bf16 v[100:103], v[174:177], v[198:201], v[100:103]
	v_mfma_f32_16x16x32_bf16 v[96:99], v[182:185], v[198:201], v[96:99]
	v_mfma_f32_16x16x32_bf16 v[84:87], v[174:177], v[220:223], v[84:87]
	v_mfma_f32_16x16x32_bf16 v[80:83], v[182:185], v[220:223], v[80:83]
	v_mfma_f32_16x16x32_bf16 v[68:71], v[174:177], v[232:235], v[68:71]
	v_mfma_f32_16x16x32_bf16 v[64:67], v[182:185], v[232:235], v[64:67]
	v_mfma_f32_16x16x32_bf16 v[116:119], v[178:181], v[194:197], v[116:119]
	v_mfma_f32_16x16x32_bf16 v[112:115], v[186:189], v[194:197], v[112:115]
	v_mfma_f32_16x16x32_bf16 v[100:103], v[178:181], v[202:205], v[100:103]
	v_mfma_f32_16x16x32_bf16 v[96:99], v[186:189], v[202:205], v[96:99]
	v_mfma_f32_16x16x32_bf16 v[84:87], v[178:181], v[228:231], v[84:87]
	v_mfma_f32_16x16x32_bf16 v[80:83], v[186:189], v[228:231], v[80:83]
	v_mfma_f32_16x16x32_bf16 v[68:71], v[178:181], v[236:239], v[68:71]
	v_mfma_f32_16x16x32_bf16 v[64:67], v[186:189], v[236:239], v[64:67]
	s_barrier
	s_add_i32 s25, s25, s67
	v_lshl_add_u64 v[142:143], s[62:63], 0, v[162:163]
	s_mov_b32 m0, s25
	ds_read_b128 v[190:193], v147 offset:16384
	ds_read_b128 v[194:197], v147 offset:17408
	ds_read_b128 v[198:201], v147 offset:18432
	ds_read_b128 v[202:205], v147 offset:19456
	ds_read_b128 v[220:223], v147 offset:20480
	ds_read_b128 v[228:231], v147 offset:21504
	ds_read_b128 v[232:235], v147 offset:22528
	ds_read_b128 v[236:239], v147 offset:23552
	global_load_lds_dwordx4 v[142:143], off
	s_add_i32 m0, s25, 0x2000
	s_add_u32 s26, s62, 0xb0000
	v_lshl_add_u64 v[240:241], s[62:63], 0, v[128:129]
	s_addc_u32 s27, s63, 0
	s_add_i32 s25, s28, s67
	global_load_lds_dwordx4 v[240:241], off
	v_lshl_add_u64 v[242:243], s[26:27], 0, v[162:163]
	s_mov_b32 m0, s25
	v_lshl_add_u64 v[244:245], s[64:65], 0, v[130:131]
	global_load_lds_dwordx4 v[242:243], off
	v_lshl_add_u64 v[242:243], s[26:27], 0, v[128:129]
	s_add_i32 m0, s25, 0x2000
	s_nop 0
	global_load_lds_dwordx4 v[242:243], off
	v_lshl_add_u64 v[242:243], s[64:65], 0, v[132:133]
	s_mov_b32 m0, s68
	s_nop 0
	global_load_lds_dwordx4 v[242:243], off
	s_mov_b32 m0, s69
	s_nop 0
	global_load_lds_dwordx4 v[244:245], off
	s_waitcnt vmcnt(8)
	s_waitcnt lgkmcnt(0)
	s_barrier
	s_waitcnt lgkmcnt(0)
	v_mfma_f32_16x16x32_bf16 v[60:63], v[138:141], v[190:193], v[60:63]
	v_mfma_f32_16x16x32_bf16 v[56:59], v[152:155], v[190:193], v[56:59]
	v_mfma_f32_16x16x32_bf16 v[44:47], v[138:141], v[198:201], v[44:47]
	v_mfma_f32_16x16x32_bf16 v[40:43], v[152:155], v[198:201], v[40:43]
	v_mfma_f32_16x16x32_bf16 v[28:31], v[138:141], v[220:223], v[28:31]
	v_mfma_f32_16x16x32_bf16 v[24:27], v[152:155], v[220:223], v[24:27]
	v_mfma_f32_16x16x32_bf16 v[12:15], v[138:141], v[232:235], v[12:15]
	v_mfma_f32_16x16x32_bf16 v[8:11], v[152:155], v[232:235], v[8:11]
	v_mfma_f32_16x16x32_bf16 v[60:63], v[148:151], v[194:197], v[60:63]
	v_mfma_f32_16x16x32_bf16 v[56:59], v[156:159], v[194:197], v[56:59]
	v_mfma_f32_16x16x32_bf16 v[44:47], v[148:151], v[202:205], v[44:47]
	v_mfma_f32_16x16x32_bf16 v[40:43], v[156:159], v[202:205], v[40:43]
	v_mfma_f32_16x16x32_bf16 v[28:31], v[148:151], v[228:231], v[28:31]
	v_mfma_f32_16x16x32_bf16 v[24:27], v[156:159], v[228:231], v[24:27]
	v_mfma_f32_16x16x32_bf16 v[12:15], v[148:151], v[236:239], v[12:15]
	v_mfma_f32_16x16x32_bf16 v[8:11], v[156:159], v[236:239], v[8:11]
	v_mfma_f32_16x16x32_bf16 v[52:55], v[174:177], v[190:193], v[52:55]
	v_mfma_f32_16x16x32_bf16 v[48:51], v[182:185], v[190:193], v[48:51]
	v_mfma_f32_16x16x32_bf16 v[36:39], v[174:177], v[198:201], v[36:39]
	v_mfma_f32_16x16x32_bf16 v[32:35], v[182:185], v[198:201], v[32:35]
	v_mfma_f32_16x16x32_bf16 v[20:23], v[174:177], v[220:223], v[20:23]
	v_mfma_f32_16x16x32_bf16 v[16:19], v[182:185], v[220:223], v[16:19]
	v_mfma_f32_16x16x32_bf16 v[4:7], v[174:177], v[232:235], v[4:7]
	v_mfma_f32_16x16x32_bf16 v[0:3], v[182:185], v[232:235], v[0:3]
	v_mfma_f32_16x16x32_bf16 v[52:55], v[178:181], v[194:197], v[52:55]
	v_mfma_f32_16x16x32_bf16 v[48:51], v[186:189], v[194:197], v[48:51]
	v_mfma_f32_16x16x32_bf16 v[36:39], v[178:181], v[202:205], v[36:39]
	v_mfma_f32_16x16x32_bf16 v[32:35], v[186:189], v[202:205], v[32:35]
	v_mfma_f32_16x16x32_bf16 v[20:23], v[178:181], v[228:231], v[20:23]
	v_mfma_f32_16x16x32_bf16 v[16:19], v[186:189], v[228:231], v[16:19]
	v_mfma_f32_16x16x32_bf16 v[4:7], v[178:181], v[236:239], v[4:7]
	v_mfma_f32_16x16x32_bf16 v[0:3], v[186:189], v[236:239], v[0:3]
	s_barrier
	s_add_i32 s25, 0, 0x18000
	s_add_i32 s28, 0, 0x1c000
	v_add_u32_e32 v156, s25, v145
	v_add_u32_e32 v186, s28, v145
	ds_read_b128 v[138:141], v156
	ds_read_b128 v[148:151], v156 offset:1024
	ds_read_b128 v[152:155], v156 offset:2048
	ds_read_b128 v[156:159], v156 offset:3072
	ds_read_b128 v[174:177], v186
	ds_read_b128 v[178:181], v186 offset:1024
	ds_read_b128 v[182:185], v186 offset:2048
	ds_read_b128 v[186:189], v186 offset:3072
	s_add_u32 s26, s64, 0xb0000
	s_addc_u32 s27, s65, 0
	s_mov_b32 m0, s70
	v_lshl_add_u64 v[246:247], s[26:27], 0, v[132:133]
	ds_read_b128 v[190:193], v147 offset:32768
	ds_read_b128 v[194:197], v147 offset:33792
	ds_read_b128 v[198:201], v147 offset:34816
	ds_read_b128 v[202:205], v147 offset:35840
	ds_read_b128 v[220:223], v147 offset:36864
	ds_read_b128 v[228:231], v147 offset:37888
	ds_read_b128 v[232:235], v147 offset:38912
	ds_read_b128 v[236:239], v147 offset:39936
	global_load_lds_dwordx4 v[246:247], off
	v_lshl_add_u64 v[246:247], s[26:27], 0, v[130:131]
	s_mov_b32 m0, s71
	s_nop 0
	global_load_lds_dwordx4 v[246:247], off
	s_waitcnt vmcnt(8)
	s_waitcnt lgkmcnt(0)
	s_barrier
	s_waitcnt lgkmcnt(0)
	v_mfma_f32_16x16x32_bf16 v[124:127], v[138:141], v[190:193], v[124:127]
	v_mfma_f32_16x16x32_bf16 v[120:123], v[152:155], v[190:193], v[120:123]
	v_mfma_f32_16x16x32_bf16 v[108:111], v[138:141], v[198:201], v[108:111]
	v_mfma_f32_16x16x32_bf16 v[104:107], v[152:155], v[198:201], v[104:107]
	v_mfma_f32_16x16x32_bf16 v[92:95], v[138:141], v[220:223], v[92:95]
	v_mfma_f32_16x16x32_bf16 v[88:91], v[152:155], v[220:223], v[88:91]
	v_mfma_f32_16x16x32_bf16 v[76:79], v[138:141], v[232:235], v[76:79]
	v_mfma_f32_16x16x32_bf16 v[72:75], v[152:155], v[232:235], v[72:75]
	v_mfma_f32_16x16x32_bf16 v[124:127], v[148:151], v[194:197], v[124:127]
	v_mfma_f32_16x16x32_bf16 v[120:123], v[156:159], v[194:197], v[120:123]
	v_mfma_f32_16x16x32_bf16 v[108:111], v[148:151], v[202:205], v[108:111]
	v_mfma_f32_16x16x32_bf16 v[104:107], v[156:159], v[202:205], v[104:107]
	v_mfma_f32_16x16x32_bf16 v[92:95], v[148:151], v[228:231], v[92:95]
	v_mfma_f32_16x16x32_bf16 v[88:91], v[156:159], v[228:231], v[88:91]
	v_mfma_f32_16x16x32_bf16 v[76:79], v[148:151], v[236:239], v[76:79]
	v_mfma_f32_16x16x32_bf16 v[72:75], v[156:159], v[236:239], v[72:75]
	v_mfma_f32_16x16x32_bf16 v[116:119], v[174:177], v[190:193], v[116:119]
	v_mfma_f32_16x16x32_bf16 v[112:115], v[182:185], v[190:193], v[112:115]
	v_mfma_f32_16x16x32_bf16 v[100:103], v[174:177], v[198:201], v[100:103]
	v_mfma_f32_16x16x32_bf16 v[96:99], v[182:185], v[198:201], v[96:99]
	v_mfma_f32_16x16x32_bf16 v[84:87], v[174:177], v[220:223], v[84:87]
	v_mfma_f32_16x16x32_bf16 v[80:83], v[182:185], v[220:223], v[80:83]
	v_mfma_f32_16x16x32_bf16 v[68:71], v[174:177], v[232:235], v[68:71]
	v_mfma_f32_16x16x32_bf16 v[64:67], v[182:185], v[232:235], v[64:67]
	v_mfma_f32_16x16x32_bf16 v[116:119], v[178:181], v[194:197], v[116:119]
	v_mfma_f32_16x16x32_bf16 v[112:115], v[186:189], v[194:197], v[112:115]
	v_mfma_f32_16x16x32_bf16 v[100:103], v[178:181], v[202:205], v[100:103]
	v_mfma_f32_16x16x32_bf16 v[96:99], v[186:189], v[202:205], v[96:99]
	v_mfma_f32_16x16x32_bf16 v[84:87], v[178:181], v[228:231], v[84:87]
	v_mfma_f32_16x16x32_bf16 v[80:83], v[186:189], v[228:231], v[80:83]
	v_mfma_f32_16x16x32_bf16 v[68:71], v[178:181], v[236:239], v[68:71]
	v_mfma_f32_16x16x32_bf16 v[64:67], v[186:189], v[236:239], v[64:67]
	s_barrier
	s_add_i32 s25, s25, s67
	v_lshl_add_u64 v[142:143], v[142:143], 0, s[4:5]
	s_mov_b32 m0, s25
	ds_read_b128 v[190:193], v147 offset:49152
	ds_read_b128 v[194:197], v147 offset:50176
	ds_read_b128 v[198:201], v147 offset:51200
	ds_read_b128 v[202:205], v147 offset:52224
	ds_read_b128 v[220:223], v147 offset:53248
	ds_read_b128 v[228:231], v147 offset:54272
	ds_read_b128 v[232:235], v147 offset:55296
	ds_read_b128 v[236:239], v147 offset:56320
	global_load_lds_dwordx4 v[142:143], off
	s_add_i32 m0, s25, 0x2000
	s_add_u32 s26, s62, 0xb0080
	v_lshl_add_u64 v[142:143], v[240:241], 0, s[4:5]
	s_addc_u32 s27, s63, 0
	s_add_i32 s25, s28, s67
	global_load_lds_dwordx4 v[142:143], off
	v_lshl_add_u64 v[142:143], s[26:27], 0, v[162:163]
	s_mov_b32 m0, s25
	s_nop 0
	global_load_lds_dwordx4 v[142:143], off
	v_lshl_add_u64 v[142:143], s[26:27], 0, v[128:129]
	s_add_i32 m0, s25, 0x2000
	s_nop 0
	global_load_lds_dwordx4 v[142:143], off
	v_lshl_add_u64 v[142:143], v[242:243], 0, s[4:5]
	s_mov_b32 m0, s73
	s_nop 0
	global_load_lds_dwordx4 v[142:143], off
	v_lshl_add_u64 v[142:143], v[244:245], 0, s[4:5]
	s_mov_b32 m0, s74
	s_nop 0
	global_load_lds_dwordx4 v[142:143], off
	s_waitcnt vmcnt(8)
	s_waitcnt lgkmcnt(0)
	s_barrier
	s_waitcnt lgkmcnt(0)
	v_mfma_f32_16x16x32_bf16 v[60:63], v[138:141], v[190:193], v[60:63]
	v_mfma_f32_16x16x32_bf16 v[56:59], v[152:155], v[190:193], v[56:59]
	v_mfma_f32_16x16x32_bf16 v[44:47], v[138:141], v[198:201], v[44:47]
	v_mfma_f32_16x16x32_bf16 v[40:43], v[152:155], v[198:201], v[40:43]
	v_mfma_f32_16x16x32_bf16 v[28:31], v[138:141], v[220:223], v[28:31]
	v_mfma_f32_16x16x32_bf16 v[24:27], v[152:155], v[220:223], v[24:27]
	v_mfma_f32_16x16x32_bf16 v[12:15], v[138:141], v[232:235], v[12:15]
	v_mfma_f32_16x16x32_bf16 v[8:11], v[152:155], v[232:235], v[8:11]
	v_mfma_f32_16x16x32_bf16 v[60:63], v[148:151], v[194:197], v[60:63]
	v_mfma_f32_16x16x32_bf16 v[56:59], v[156:159], v[194:197], v[56:59]
	v_mfma_f32_16x16x32_bf16 v[44:47], v[148:151], v[202:205], v[44:47]
	v_mfma_f32_16x16x32_bf16 v[40:43], v[156:159], v[202:205], v[40:43]
	v_mfma_f32_16x16x32_bf16 v[28:31], v[148:151], v[228:231], v[28:31]
	v_mfma_f32_16x16x32_bf16 v[24:27], v[156:159], v[228:231], v[24:27]
	v_mfma_f32_16x16x32_bf16 v[12:15], v[148:151], v[236:239], v[12:15]
	v_mfma_f32_16x16x32_bf16 v[8:11], v[156:159], v[236:239], v[8:11]
	v_mfma_f32_16x16x32_bf16 v[52:55], v[174:177], v[190:193], v[52:55]
	v_mfma_f32_16x16x32_bf16 v[48:51], v[182:185], v[190:193], v[48:51]
	v_mfma_f32_16x16x32_bf16 v[36:39], v[174:177], v[198:201], v[36:39]
	v_mfma_f32_16x16x32_bf16 v[32:35], v[182:185], v[198:201], v[32:35]
	v_mfma_f32_16x16x32_bf16 v[20:23], v[174:177], v[220:223], v[20:23]
	v_mfma_f32_16x16x32_bf16 v[16:19], v[182:185], v[220:223], v[16:19]
	v_mfma_f32_16x16x32_bf16 v[4:7], v[174:177], v[232:235], v[4:7]
	v_mfma_f32_16x16x32_bf16 v[0:3], v[182:185], v[232:235], v[0:3]
	v_mfma_f32_16x16x32_bf16 v[52:55], v[178:181], v[194:197], v[52:55]
	v_mfma_f32_16x16x32_bf16 v[48:51], v[186:189], v[194:197], v[48:51]
	v_mfma_f32_16x16x32_bf16 v[36:39], v[178:181], v[202:205], v[36:39]
	v_mfma_f32_16x16x32_bf16 v[32:35], v[186:189], v[202:205], v[32:35]
	v_mfma_f32_16x16x32_bf16 v[20:23], v[178:181], v[228:231], v[20:23]
	v_mfma_f32_16x16x32_bf16 v[16:19], v[186:189], v[228:231], v[16:19]
	v_mfma_f32_16x16x32_bf16 v[4:7], v[178:181], v[236:239], v[4:7]
	v_mfma_f32_16x16x32_bf16 v[0:3], v[186:189], v[236:239], v[0:3]
	s_barrier
	s_add_i32 s24, s24, 2
	s_add_u32 s6, s6, 0x100
	s_addc_u32 s7, s7, 0
	s_cmp_gt_u32 s24, 41
	s_mov_b64 s[58:59], s[60:61]
	s_cbranch_scc0 .LBB0_1280
	s_and_b64 vcc, exec, s[54:55]
	s_cbranch_vccz .LBB0_1283
	s_barrier
